# GEMM staging: waves 0-3 issue the LDS-DMA loads for both themselves and their SIMD partner wave, waves 4-7 issue none (on top of v37)
# baseline (speedup 1.0000x reference)
; #define LAS __attribute__((address_space(3)))
; __device__ __forceinline__ unsigned xb_add(unsigned* p, unsigned v) { return __hip_atomic_fetch_add(p, v, __ATOMIC_RELAXED, __HIP_MEMORY_SCOPE_AGENT); }
; __device__ __forceinline__ unsigned xb_xcc_id() { return (unsigned)__builtin_amdgcn_s_getreg((3 << 11) | 20) & 0xFu; }
; #define PF fresh_params()
; __device__ __forceinline__ XcdBarrier xcd_barrier_post(unsigned* bar, volatile LAS unsigned* st) {
;     XcdBarrier b; b.bar = bar; b.x = xb_xcc_id(); b.st = st;
;     if (threadIdx.x == 0) { st[2] = xb_add(&bar[XB_XCNT(b.x)], 1u); st[4] = b.x; }
;     return b;
; }
; __global__ void __launch_bounds__(BLOCK_THREADS, 2) mega(Params p_unused) {
;     __shared__ __attribute__((aligned(16))) char lds[LDS_BYTES];
;     cg::grid_group grid = cg::this_grid();
;     volatile LAS unsigned* st = (volatile LAS unsigned*)(lds + 2 * LDS_MAIN);
;     if (threadIdx.x < 16) st[threadIdx.x] = 0u;
;     __syncthreads();
;     XcdBarrier xb = xcd_barrier_post((unsigned*)PF.ws, st);
_Z4mega6Params:
	s_load_dwordx2 s[76:77], s[0:1], 0xe0
	s_load_dword s84, s[0:1], 0xe8
	s_mov_b64 s[80:81], s[0:1]
	s_add_u32 s12, s80, 0xe0
	v_and_b32_e32 v158, 0x3ff, v0
	s_addc_u32 s13, s81, 0
	v_cmp_gt_u32_e32 vcc, 16, v158
	v_writelane_b32 v222, s2, 0
	s_and_saveexec_b64 s[4:5], vcc
	v_mov_b32_e32 v1, 0x24000
	v_lshl_or_b32 v1, v158, 2, v1
	v_mov_b32_e32 v2, 0
	ds_write_b32 v1, v2
	s_or_b64 exec, exec, s[4:5]
	s_mov_b64 s[0:1], s[80:81]
	s_waitcnt lgkmcnt(0)
	s_barrier
	s_mov_b32 s98, 0x138000
	s_mov_b32 s99, 0
	s_mov_b32 s100, 0x40000
	s_mov_b32 s101, 0
	s_load_dwordx2 s[78:79], s[0:1], 0xd8
	s_getreg_b32 s0, hwreg(HW_REG_XCC_ID, 0, 4)
	s_and_b32 s83, s0, 15
	v_cmp_eq_u32_e64 s[0:1], 0, v158
	s_mov_b64 s[4:5], exec
	s_nop 0
	v_writelane_b32 v222, s0, 1
	s_nop 1
	v_writelane_b32 v222, s1, 2
	s_and_b64 s[0:1], s[4:5], s[0:1]
	s_mov_b64 exec, s[0:1]
	s_cbranch_execz .LBB0_6
	s_mov_b64 s[8:9], exec
	v_mbcnt_lo_u32_b32 v1, s8, 0
	v_mbcnt_hi_u32_b32 v1, s9, v1
	v_cmp_eq_u32_e32 vcc, 0, v1
	s_and_saveexec_b64 s[6:7], vcc
	s_cbranch_execz .LBB0_5
	s_lshl_b32 s0, s83, 8
	s_bcnt1_i32_b64 s1, s[8:9]
	v_mov_b32_e32 v2, s0
	v_mov_b32_e32 v3, s1
	s_waitcnt lgkmcnt(0)
	global_atomic_add v2, v2, v3, s[78:79] offset:1024 sc0

; #define TIDX512 launder_i((int)threadIdx.x)
; __device__ __forceinline__ void glds16(const bf16_t* g, char* l) { __builtin_amdgcn_global_load_lds((const unsigned*)g, (unsigned*)l, 16, 0, 0); }
; __device__ __forceinline__ void gemm_issue(const GemmSrc& g, int kt, int s, char* lds) {
;     const int tid = TIDX512, lane = tid & 63, wave = tid >> 6;
;     char* xdst = lds + s * 65536 + wave * 4096 + lane * 16;
;     char* wdst = xdst + 32768;
; #pragma unroll
;     for (int i = 0; i < 4; i++) {
;         const int d = (i & 1) ? g.dsw : 0;
;         glds16(g.xsrc + (size_t)i * 8 * g.ldx + kt * 64 + d, xdst + i * 1024);
;         glds16(g.wsrc + (size_t)i * 8 * g.ldw + kt * 64 + d, wdst + i * 1024);
;     }
; }
; __device__ __forceinline__ void gemm_prologue(const GemmSrc& g, char* lds) { gemm_issue(g, 0, 0, lds); }
; __device__ __forceinline__ void zero_acc(f32x4 (&acc)[8][4]) {
; #pragma unroll
;     for (int a = 0; a < 8; a++)
; #pragma unroll
;         for (int b = 0; b < 4; b++) acc[a][b] = (f32x4){0.f, 0.f, 0.f, 0.f};
.LBB0_298:
	s_andn2_b64 vcc, exec, s[8:9]
	s_mov_b64 s[8:9], -1
	s_cbranch_vccnz .LBB0_290
	v_mov_b32_e32 v0, v158
	s_lshl_b32 s82, s74, 8
	v_ashrrev_i32_e32 v1, 1, v0
	v_and_b32_e32 v12, 0xffffffe0, v1
	v_bfe_u32 v1, v0, 4, 2
	v_and_b32_e32 v3, 7, v0
	v_bitop3_b32 v4, v1, v0, 7 bitop3:0x78
	v_bitop3_b32 v5, v1, v3, 4 bitop3:0x36
	v_lshlrev_b32_e32 v128, 4, v4
	v_sub_u32_e32 v4, v5, v4
	v_mov_b32_e32 v5, v158
	v_bfe_u32 v13, v0, 3, 3
	v_or_b32_e32 v2, v12, v13
	v_lshlrev_b32_e32 v6, 6, v5
	v_lshlrev_b32_e32 v5, 4, v5
	s_lshl_b32 s44, s75, 8
	v_add_u32_e32 v0, s82, v2
	v_and_b32_e32 v5, 0x3f0, v5
	v_ashrrev_i32_e32 v1, 31, v0
	v_add_u32_e32 v2, s44, v2
	v_and_or_b32 v14, v6, s51, v5
	v_lshlrev_b64 v[0:1], 11, v[0:1]
	v_ashrrev_i32_e32 v3, 31, v2
	v_lshlrev_b32_e32 v4, 3, v4
	v_add_u32_e32 v5, 0x8000, v14
	v_readfirstlane_b32 s0, v14
	v_lshl_add_u64 v[0:1], s[14:15], 0, v[0:1]
	v_lshlrev_b64 v[2:3], 11, v[2:3]
	s_mov_b32 m0, s0
	v_readfirstlane_b32 s0, v5
	v_ashrrev_i32_e32 v5, 31, v4
	v_lshl_add_u64 v[0:1], v[0:1], 0, v[128:129]
	v_lshl_add_u64 v[2:3], s[16:17], 0, v[2:3]
	v_lshlrev_b64 v[4:5], 1, v[4:5]
	v_or_b32_e32 v10, 0x400, v14
	v_lshl_add_u64 v[2:3], v[2:3], 0, v[128:129]
	s_cmp_lg_u32 s33, 0
	s_cbranch_scc1 .Ldma_skip_0
	global_load_lds_dwordx4 v[0:1], off
	s_add_u32 m0, m0, 0x4000
	v_lshl_add_u64 v[220:221], v[0:1], 0, s[100:101]
	global_load_lds_dwordx4 v[220:221], off
.Ldma_skip_0:
	s_mov_b32 m0, s0
	v_lshl_add_u64 v[6:7], v[0:1], 0, v[4:5]
	v_readfirstlane_b32 s0, v10
	s_cmp_lg_u32 s33, 0
	s_cbranch_scc1 .Ldma_skip_1
	global_load_lds_dwordx4 v[2:3], off
	s_add_u32 m0, m0, 0x4000
	v_lshl_add_u64 v[220:221], v[2:3], 0, s[100:101]
	global_load_lds_dwordx4 v[220:221], off
.Ldma_skip_1:
	v_lshl_add_u64 v[8:9], v[6:7], 0, s[20:21]
	s_mov_b32 m0, s0
	v_add_u32_e32 v15, 0x8400, v14
	s_cmp_lg_u32 s33, 0
	s_cbranch_scc1 .Ldma_skip_2
	global_load_lds_dwordx4 v[8:9], off
	s_add_u32 m0, m0, 0x4000
	v_lshl_add_u64 v[220:221], v[8:9], 0, s[100:101]
	global_load_lds_dwordx4 v[220:221], off
.Ldma_skip_2:
	v_lshl_add_u64 v[8:9], v[2:3], 0, v[4:5]
	v_readfirstlane_b32 s0, v15
	v_lshl_add_u64 v[10:11], v[8:9], 0, s[20:21]
	s_mov_b32 m0, s0
	v_lshl_add_u64 v[0:1], v[0:1], 0, s[22:23]
	s_cmp_lg_u32 s33, 0
	s_cbranch_scc1 .Ldma_skip_3
	global_load_lds_dwordx4 v[10:11], off
	s_add_u32 m0, m0, 0x4000
	v_lshl_add_u64 v[220:221], v[10:11], 0, s[100:101]
	global_load_lds_dwordx4 v[220:221], off
.Ldma_skip_3:
	v_or_b32_e32 v10, 0x800, v14
	s_mov_b64 s[8:9], 0
	v_readfirstlane_b32 s0, v10
	s_mov_b32 m0, s0
	s_nop 0
	s_cmp_lg_u32 s33, 0
	s_cbranch_scc1 .Ldma_skip_4
	global_load_lds_dwordx4 v[0:1], off
	s_add_u32 m0, m0, 0x4000
	v_lshl_add_u64 v[220:221], v[0:1], 0, s[100:101]
	global_load_lds_dwordx4 v[220:221], off
.Ldma_skip_4:
	v_lshl_add_u64 v[0:1], v[2:3], 0, s[22:23]
	v_add_u32_e32 v2, 0x8800, v14
	s_nop 0
	v_readfirstlane_b32 s0, v2
	v_or_b32_e32 v2, 0xc00, v14
	s_mov_b32 m0, s0
	v_readfirstlane_b32 s0, v2
	v_add_u32_e32 v2, 0x8c00, v14
	s_cmp_lg_u32 s33, 0
	s_cbranch_scc1 .Ldma_skip_5
	global_load_lds_dwordx4 v[0:1], off
	s_add_u32 m0, m0, 0x4000
	v_lshl_add_u64 v[220:221], v[0:1], 0, s[100:101]
	global_load_lds_dwordx4 v[220:221], off
.Ldma_skip_5:
	v_lshl_add_u64 v[0:1], v[6:7], 0, s[24:25]
	s_mov_b32 m0, s0
	v_readfirstlane_b32 s0, v2
	s_cmp_lg_u32 s33, 0
	s_cbranch_scc1 .Ldma_skip_6
	global_load_lds_dwordx4 v[0:1], off
	s_add_u32 m0, m0, 0x4000
	v_lshl_add_u64 v[220:221], v[0:1], 0, s[100:101]
	global_load_lds_dwordx4 v[220:221], off
.Ldma_skip_6:
	v_lshl_add_u64 v[0:1], v[8:9], 0, s[24:25]
	s_mov_b32 m0, s0
	s_mov_b32 s0, 0x10000
	s_cmp_lg_u32 s33, 0
	s_cbranch_scc1 .Ldma_skip_7
	global_load_lds_dwordx4 v[0:1], off
	s_add_u32 m0, m0, 0x4000
	v_lshl_add_u64 v[220:221], v[0:1], 0, s[100:101]
	global_load_lds_dwordx4 v[220:221], off
.Ldma_skip_7:
	v_mov_b32_e32 v0, v158
	s_nop 0
	v_and_b32_e32 v1, 15, v0
	v_lshrrev_b32_e32 v2, 4, v0
	v_bfe_u32 v6, v0, 1, 3
	v_bfe_u32 v3, v0, 4, 2
	v_lshlrev_b32_e32 v1, 7, v1
	v_bitop3_b32 v2, v2, v6, 3 bitop3:0x6c
	v_lshl_or_b32 v142, v2, 4, v1
	v_bitop3_b32 v2, v3, v6, 4 bitop3:0x36
	v_lshl_or_b32 v133, v2, 4, v1
	v_lshlrev_b32_e32 v1, 7, v0
	v_lshlrev_b32_e32 v0, 6, v0
	v_and_b32_e32 v143, 0xffffc000, v0
	v_or_b32_e32 v0, s82, v13
	v_add_u32_e32 v0, v0, v12
	v_or_b32_e32 v2, s44, v13
	v_and_b32_e32 v144, 0x6000, v1
	v_ashrrev_i32_e32 v1, 31, v0
	v_add_u32_e32 v2, v2, v12
	v_lshlrev_b64 v[0:1], 11, v[0:1]
	v_ashrrev_i32_e32 v3, 31, v2
	v_or_b32_e32 v0, v0, v128
	v_lshlrev_b64 v[2:3], 11, v[2:3]
	v_lshl_add_u64 v[134:135], s[10:11], 0, v[0:1]
	v_or_b32_e32 v2, v2, v128
	v_lshl_add_u64 v[0:1], v[0:1], 0, v[4:5]
	v_lshl_add_u64 v[138:139], s[10:11], 0, v[0:1]
	v_lshl_add_u64 v[0:1], v[2:3], 0, v[4:5]
	v_lshl_add_u64 v[140:141], s[10:11], 0, v[0:1]
	v_mov_b32_e32 v0, 0
	v_lshl_add_u64 v[136:137], s[10:11], 0, v[2:3]
	v_mov_b32_e32 v1, v0
	v_mov_b32_e32 v2, v0
	v_mov_b32_e32 v3, v0
	v_mov_b32_e32 v4, v0
	v_mov_b32_e32 v5, v0
	v_mov_b32_e32 v6, v0
	v_mov_b32_e32 v7, v0
	v_mov_b32_e32 v8, v0
	v_mov_b32_e32 v9, v0
	v_mov_b32_e32 v10, v0
	v_mov_b32_e32 v11, v0
	v_mov_b32_e32 v12, v0
	v_mov_b32_e32 v13, v0
	v_mov_b32_e32 v14, v0
	v_mov_b32_e32 v15, v0
	v_mov_b32_e32 v16, v0
	v_mov_b32_e32 v17, v0
	v_mov_b32_e32 v18, v0
	v_mov_b32_e32 v19, v0
	v_mov_b32_e32 v20, v0
	v_mov_b32_e32 v21, v0
	v_mov_b32_e32 v22, v0
	v_mov_b32_e32 v23, v0
	v_mov_b32_e32 v24, v0
	v_mov_b32_e32 v25, v0
	v_mov_b32_e32 v26, v0
	v_mov_b32_e32 v27, v0
	v_mov_b32_e32 v28, v0
	v_mov_b32_e32 v29, v0
	v_mov_b32_e32 v30, v0
	v_mov_b32_e32 v31, v0
	v_mov_b32_e32 v32, v0
	v_mov_b32_e32 v33, v0
	v_mov_b32_e32 v34, v0
	v_mov_b32_e32 v35, v0
	v_mov_b32_e32 v36, v0
; #define TIDX512 launder_i((int)threadIdx.x)
; __device__ __forceinline__ f32x4 mfma16(bf16x8 a, bf16x8 b, f32x4 c) { return __builtin_amdgcn_mfma_f32_16x16x32_bf16(a, b, c, 0, 0, 0); }
; #define WAIT_V(n) asm volatile("s_waitcnt vmcnt(" #n ")" ::: "memory")
; __device__ __forceinline__ void glds16(const bf16_t* g, char* l) { __builtin_amdgcn_global_load_lds((const unsigned*)g, (unsigned*)l, 16, 0, 0); }
; __device__ __forceinline__ void gemm_issue(const GemmSrc& g, int kt, int s, char* lds) {
;     const int tid = TIDX512, lane = tid & 63, wave = tid >> 6;
;     char* xdst = lds + s * 65536 + wave * 4096 + lane * 16;
;     char* wdst = xdst + 32768;
; #pragma unroll
;     for (int i = 0; i < 4; i++) {
;         const int d = (i & 1) ? g.dsw : 0;
;         glds16(g.xsrc + (size_t)i * 8 * g.ldx + kt * 64 + d, xdst + i * 1024);
;         glds16(g.wsrc + (size_t)i * 8 * g.ldw + kt * 64 + d, wdst + i * 1024);
;     }
; __device__ __forceinline__ void gemm_mainloop(f32x4 (&acc)[8][4], const GemmSrc& g, int K, char* lds) {
;     ...
;     for (int kt = 0; kt < KT; kt++) {
;         WAIT_V(0);
;         __builtin_amdgcn_s_barrier();
;         const char* st = lds + (kt & 1) * 65536;
;         bf16x8 afA[4], afB[4], bX[4], bY[4];
; #pragma unroll
;         for (int ni = 0; ni < 4; ni++) afA[ni] = *(const bf16x8*)(st + woff + ni * 16 * 128 + rdo0);
; #pragma unroll
;         for (int mi = 0; mi < 4; mi++) bX[mi] = *(const bf16x8*)(st + xoff + mi * 16 * 128 + rdo0);
;         if (kt + 1 < KT) gemm_issue(g, kt + 1, (kt + 1) & 1, lds);
; #pragma unroll
;         for (int mi = 0; mi < 4; mi++) bY[mi] = *(const bf16x8*)(st + xoff + (4 + mi) * 16 * 128 + rdo0);
; #pragma unroll
;         for (int ni = 0; ni < 4; ni++) afB[ni] = *(const bf16x8*)(st + woff + ni * 16 * 128 + rdo1);
; #pragma unroll
;         for (int mi = 0; mi < 4; mi++)
; #pragma unroll
;             for (int ni = 0; ni < 4; ni++) acc[mi][ni] = mfma16(afA[ni], bX[mi], acc[mi][ni]);
	v_mov_b32_e32 v37, v0
	v_mov_b32_e32 v38, v0
	v_mov_b32_e32 v39, v0
	v_mov_b32_e32 v40, v0
	v_mov_b32_e32 v41, v0
	v_mov_b32_e32 v42, v0
	v_mov_b32_e32 v43, v0
	v_mov_b32_e32 v44, v0
	v_mov_b32_e32 v45, v0
	v_mov_b32_e32 v46, v0
	v_mov_b32_e32 v47, v0
	v_mov_b32_e32 v48, v0
	v_mov_b32_e32 v49, v0
	v_mov_b32_e32 v50, v0
	v_mov_b32_e32 v51, v0
	v_mov_b32_e32 v52, v0
	v_mov_b32_e32 v53, v0
	v_mov_b32_e32 v54, v0
	v_mov_b32_e32 v55, v0
	v_mov_b32_e32 v56, v0
	v_mov_b32_e32 v57, v0
	v_mov_b32_e32 v58, v0
	v_mov_b32_e32 v59, v0
	v_mov_b32_e32 v60, v0
	v_mov_b32_e32 v61, v0
	v_mov_b32_e32 v62, v0
	v_mov_b32_e32 v63, v0
	v_mov_b32_e32 v64, v0
	v_mov_b32_e32 v65, v0
	v_mov_b32_e32 v66, v0
	v_mov_b32_e32 v67, v0
	v_mov_b32_e32 v68, v0
	v_mov_b32_e32 v69, v0
	v_mov_b32_e32 v70, v0
	v_mov_b32_e32 v71, v0
	v_mov_b32_e32 v72, v0
	v_mov_b32_e32 v73, v0
	v_mov_b32_e32 v74, v0
	v_mov_b32_e32 v75, v0
	v_mov_b32_e32 v76, v0
	v_mov_b32_e32 v77, v0
	v_mov_b32_e32 v78, v0
	v_mov_b32_e32 v79, v0
	v_mov_b32_e32 v80, v0
	v_mov_b32_e32 v81, v0
	v_mov_b32_e32 v82, v0
	v_mov_b32_e32 v83, v0
	v_mov_b32_e32 v84, v0
	v_mov_b32_e32 v85, v0
	v_mov_b32_e32 v86, v0
	v_mov_b32_e32 v87, v0
	v_mov_b32_e32 v88, v0
	v_mov_b32_e32 v89, v0
	v_mov_b32_e32 v90, v0
	v_mov_b32_e32 v91, v0
	v_mov_b32_e32 v92, v0
	v_mov_b32_e32 v93, v0
	v_mov_b32_e32 v94, v0
	v_mov_b32_e32 v95, v0
	v_mov_b32_e32 v96, v0
	v_mov_b32_e32 v97, v0
	v_mov_b32_e32 v98, v0
	v_mov_b32_e32 v99, v0
	v_mov_b32_e32 v100, v0
	v_mov_b32_e32 v101, v0
	v_mov_b32_e32 v102, v0
	v_mov_b32_e32 v103, v0
	v_mov_b32_e32 v104, v0
	v_mov_b32_e32 v105, v0
	v_mov_b32_e32 v106, v0
	v_mov_b32_e32 v107, v0
	v_mov_b32_e32 v108, v0
	v_mov_b32_e32 v109, v0
	v_mov_b32_e32 v110, v0
	v_mov_b32_e32 v111, v0
	v_mov_b32_e32 v112, v0
	v_mov_b32_e32 v113, v0
	v_mov_b32_e32 v114, v0
	v_mov_b32_e32 v115, v0
	v_mov_b32_e32 v116, v0
	v_mov_b32_e32 v117, v0
	v_mov_b32_e32 v118, v0
	v_mov_b32_e32 v119, v0
	v_mov_b32_e32 v120, v0
	v_mov_b32_e32 v121, v0
	v_mov_b32_e32 v122, v0
	v_mov_b32_e32 v123, v0
	v_mov_b32_e32 v124, v0
	v_mov_b32_e32 v125, v0
	v_mov_b32_e32 v126, v0
	v_mov_b32_e32 v127, v0
.LBB0_300:
	s_add_i32 s45, s0, 0xffff0000
	s_and_b32 s45, s45, 0x10000
	v_or_b32_e32 v128, s45, v144
	v_add_u32_e32 v145, v128, v142
	s_waitcnt vmcnt(0)
	s_barrier
	ds_read_b128 v[146:149], v145 offset:32768
	ds_read_b128 v[160:163], v145 offset:34816
	ds_read_b128 v[164:167], v145 offset:36864
	ds_read_b128 v[168:171], v145 offset:38912
	v_add_u32_e32 v145, s45, v143
	v_add_u32_e32 v194, v145, v142
	v_mov_b32_e32 v150, v158
	ds_read_b128 v[172:175], v194
	ds_read_b128 v[176:179], v194 offset:2048
	ds_read_b128 v[180:183], v194 offset:4096
	ds_read_b128 v[184:187], v194 offset:6144
	s_and_b32 s45, s0, 0x10000
	v_lshlrev_b32_e32 v151, 6, v150
	v_and_b32_e32 v151, 0xfffff000, v151
	v_add_u32_e32 v151, s45, v151
	v_lshlrev_b32_e32 v150, 4, v150
	v_and_or_b32 v195, v150, s50, v151
	v_lshl_add_u64 v[150:151], v[134:135], 0, s[8:9]
	v_readfirstlane_b32 s45, v195
	v_add_u32_e32 v192, 0x8000, v195
	v_lshl_add_u64 v[188:189], v[150:151], 0, s[26:27]
	s_mov_b32 m0, s45
	v_readfirstlane_b32 s45, v192
	s_cmp_lg_u32 s33, 0
	s_cbranch_scc1 .Ldma_skip_8
	global_load_lds_dwordx4 v[188:189], off
	s_add_u32 m0, m0, 0x4000
	v_lshl_add_u64 v[220:221], v[188:189], 0, s[100:101]
	global_load_lds_dwordx4 v[220:221], off
.Ldma_skip_8:
	v_lshl_add_u64 v[188:189], v[136:137], 0, s[8:9]
	v_lshl_add_u64 v[190:191], v[188:189], 0, s[28:29]
	s_mov_b32 m0, s45
	v_or_b32_e32 v196, 0x400, v195
	s_cmp_lg_u32 s33, 0
	s_cbranch_scc1 .Ldma_skip_9
	global_load_lds_dwordx4 v[190:191], off
	s_add_u32 m0, m0, 0x4000
	v_lshl_add_u64 v[220:221], v[190:191], 0, s[100:101]
	global_load_lds_dwordx4 v[220:221], off
.Ldma_skip_9:
	v_lshl_add_u64 v[190:191], v[138:139], 0, s[8:9]
	v_readfirstlane_b32 s45, v196
	s_waitcnt lgkmcnt(0)
	v_mfma_f32_16x16x32_bf16 v[124:127], v[146:149], v[172:175], v[124:127]
	v_lshl_add_u64 v[192:193], v[190:191], 0, s[30:31]
	s_mov_b32 m0, s45
	v_lshl_add_u64 v[150:151], v[150:151], 0, s[36:37]
	v_mfma_f32_16x16x32_bf16 v[120:123], v[160:163], v[172:175], v[120:123]
	s_cmp_lg_u32 s33, 0
	s_cbranch_scc1 .Ldma_skip_10
	global_load_lds_dwordx4 v[192:193], off
	s_add_u32 m0, m0, 0x4000
	v_lshl_add_u64 v[220:221], v[192:193], 0, s[100:101]
	global_load_lds_dwordx4 v[220:221], off
.Ldma_skip_10:
	v_lshl_add_u64 v[192:193], v[140:141], 0, s[8:9]
	v_mfma_f32_16x16x32_bf16 v[116:119], v[164:167], v[172:175], v[116:119]
	v_add_u32_e32 v128, v128, v133
	v_mfma_f32_16x16x32_bf16 v[112:115], v[168:171], v[172:175], v[112:115]
	v_add_u32_e32 v174, 0x8400, v195
	v_lshl_add_u64 v[172:173], v[192:193], 0, s[34:35]
	v_readfirstlane_b32 s45, v174
	s_mov_b32 m0, s45
	v_mfma_f32_16x16x32_bf16 v[108:111], v[146:149], v[176:179], v[108:111]
	s_cmp_lg_u32 s33, 0
	s_cbranch_scc1 .Ldma_skip_11
	global_load_lds_dwordx4 v[172:173], off
	s_add_u32 m0, m0, 0x4000
	v_lshl_add_u64 v[220:221], v[172:173], 0, s[100:101]
	global_load_lds_dwordx4 v[220:221], off
.Ldma_skip_11:
	v_or_b32_e32 v172, 0x800, v195
	v_mfma_f32_16x16x32_bf16 v[104:107], v[160:163], v[176:179], v[104:107]
	v_readfirstlane_b32 s45, v172
	v_add_u32_e32 v172, 0x8800, v195
	s_mov_b32 m0, s45
	v_readfirstlane_b32 s45, v172
	v_or_b32_e32 v172, 0xc00, v195
	s_cmp_lg_u32 s33, 0
	s_cbranch_scc1 .Ldma_skip_12
	global_load_lds_dwordx4 v[150:151], off
	s_add_u32 m0, m0, 0x4000
	v_lshl_add_u64 v[220:221], v[150:151], 0, s[100:101]
	global_load_lds_dwordx4 v[220:221], off
; #define TIDX512 launder_i((int)threadIdx.x)
; __device__ __forceinline__ void gemm_issue(const GemmSrc& g, int kt, int s, char* lds) {
;     const int tid = TIDX512, lane = tid & 63, wave = tid >> 6;
;     char* xdst = lds + s * 65536 + wave * 4096 + lane * 16;
;     char* wdst = xdst + 32768;
; #pragma unroll
;     for (int i = 0; i < 4; i++) {
;         const int d = (i & 1) ? g.dsw : 0;
;         glds16(g.xsrc + (size_t)i * 8 * g.ldx + kt * 64 + d, xdst + i * 1024);
;         glds16(g.wsrc + (size_t)i * 8 * g.ldw + kt * 64 + d, wdst + i * 1024);
;     }
; __device__ __forceinline__ void gemm_mainloop(f32x4 (&acc)[8][4], const GemmSrc& g, int K, char* lds) {
;     ...
;         for (int ni = 0; ni < 4; ni++) afA[ni] = *(const bf16x8*)(st + woff + ni * 16 * 128 + rdo0);
; #pragma unroll
;         for (int mi = 0; mi < 4; mi++) bX[mi] = *(const bf16x8*)(st + xoff + mi * 16 * 128 + rdo0);
;         if (kt + 1 < KT) gemm_issue(g, kt + 1, (kt + 1) & 1, lds);
; #pragma unroll
;         for (int mi = 0; mi < 4; mi++) bY[mi] = *(const bf16x8*)(st + xoff + (4 + mi) * 16 * 128 + rdo0);
; #pragma unroll
;         for (int ni = 0; ni < 4; ni++) afB[ni] = *(const bf16x8*)(st + woff + ni * 16 * 128 + rdo1);
; #pragma unroll
;         for (int mi = 0; mi < 4; mi++)
; #pragma unroll
;             for (int ni = 0; ni < 4; ni++) acc[mi][ni] = mfma16(afA[ni], bX[mi], acc[mi][ni]);
;         __builtin_amdgcn_sched_barrier(0);
; #pragma unroll
;         for (int mi = 0; mi < 4; mi++) bX[mi] = *(const bf16x8*)(st + xoff + mi * 16 * 128 + rdo1);
; #pragma unroll
;         for (int mi = 0; mi < 4; mi++)
; #pragma unroll
;             for (int ni = 0; ni < 4; ni++) acc[4 + mi][ni] = mfma16(afA[ni], bY[mi], acc[4 + mi][ni]);
;         __builtin_amdgcn_sched_barrier(0);
; #pragma unroll
;         for (int mi = 0; mi < 4; mi++) bY[mi] = *(const bf16x8*)(st + xoff + (4 + mi) * 16 * 128 + rdo1);
; #pragma unroll
;         for (int mi = 0; mi < 4; mi++)
; #pragma unroll
;             for (int ni = 0; ni < 4; ni++) acc[mi][ni] = mfma16(afB[ni], bX[mi], acc[mi][ni]);
;         __builtin_amdgcn_sched_barrier(0);
; #pragma unroll
;         for (int mi = 0; mi < 4; mi++)
; #pragma unroll
;             for (int ni = 0; ni < 4; ni++) acc[4 + mi][ni] = mfma16(afB[ni], bY[mi], acc[4 + mi][ni]);
;         __builtin_amdgcn_sched_barrier(0);
.Ldma_skip_12:
	v_lshl_add_u64 v[150:151], v[188:189], 0, s[38:39]
	s_mov_b32 m0, s45
	v_readfirstlane_b32 s45, v172
	v_add_u32_e32 v172, 0x8c00, v195
	s_cmp_lg_u32 s33, 0
	s_cbranch_scc1 .Ldma_skip_13
	global_load_lds_dwordx4 v[150:151], off
	s_add_u32 m0, m0, 0x4000
	v_lshl_add_u64 v[220:221], v[150:151], 0, s[100:101]
	global_load_lds_dwordx4 v[220:221], off
.Ldma_skip_13:
	v_lshl_add_u64 v[150:151], v[190:191], 0, s[40:41]
	s_mov_b32 m0, s45
	v_readfirstlane_b32 s45, v172
	s_cmp_lg_u32 s33, 0
	s_cbranch_scc1 .Ldma_skip_14
	global_load_lds_dwordx4 v[150:151], off
	s_add_u32 m0, m0, 0x4000
	v_lshl_add_u64 v[220:221], v[150:151], 0, s[100:101]
	global_load_lds_dwordx4 v[220:221], off
.Ldma_skip_14:
	v_lshl_add_u64 v[150:151], v[192:193], 0, s[42:43]
	s_mov_b32 m0, s45
	v_mfma_f32_16x16x32_bf16 v[100:103], v[164:167], v[176:179], v[100:103]
	s_cmp_lg_u32 s33, 0
	s_cbranch_scc1 .Ldma_skip_15
	global_load_lds_dwordx4 v[150:151], off
	s_add_u32 m0, m0, 0x4000
	v_lshl_add_u64 v[220:221], v[150:151], 0, s[100:101]
	global_load_lds_dwordx4 v[220:221], off
.Ldma_skip_15:
	v_mfma_f32_16x16x32_bf16 v[96:99], v[168:171], v[176:179], v[96:99]
	ds_read_b128 v[172:175], v194 offset:8192
	ds_read_b128 v[176:179], v194 offset:10240
	v_mfma_f32_16x16x32_bf16 v[92:95], v[146:149], v[180:183], v[92:95]
	v_mfma_f32_16x16x32_bf16 v[88:91], v[160:163], v[180:183], v[88:91]
	v_mfma_f32_16x16x32_bf16 v[84:87], v[164:167], v[180:183], v[84:87]
	v_mfma_f32_16x16x32_bf16 v[80:83], v[168:171], v[180:183], v[80:83]
	ds_read_b128 v[180:183], v194 offset:12288
	ds_read_b128 v[188:191], v194 offset:14336
	ds_read_b128 v[192:195], v128 offset:32768
	ds_read_b128 v[196:199], v128 offset:34816
	ds_read_b128 v[200:203], v128 offset:36864
	ds_read_b128 v[204:207], v128 offset:38912
	v_mfma_f32_16x16x32_bf16 v[76:79], v[146:149], v[184:187], v[76:79]
	v_mfma_f32_16x16x32_bf16 v[72:75], v[160:163], v[184:187], v[72:75]
	v_mfma_f32_16x16x32_bf16 v[68:71], v[164:167], v[184:187], v[68:71]
	v_mfma_f32_16x16x32_bf16 v[64:67], v[168:171], v[184:187], v[64:67]
	v_add_u32_e32 v128, v145, v133
	s_waitcnt lgkmcnt(0)
	v_mfma_f32_16x16x32_bf16 v[60:63], v[146:149], v[172:175], v[60:63]
	v_mfma_f32_16x16x32_bf16 v[56:59], v[160:163], v[172:175], v[56:59]
	v_mfma_f32_16x16x32_bf16 v[52:55], v[164:167], v[172:175], v[52:55]
	v_mfma_f32_16x16x32_bf16 v[48:51], v[168:171], v[172:175], v[48:51]
	v_mfma_f32_16x16x32_bf16 v[44:47], v[146:149], v[176:179], v[44:47]
	v_mfma_f32_16x16x32_bf16 v[40:43], v[160:163], v[176:179], v[40:43]
	v_mfma_f32_16x16x32_bf16 v[36:39], v[164:167], v[176:179], v[36:39]
	v_mfma_f32_16x16x32_bf16 v[28:31], v[146:149], v[180:183], v[28:31]
	v_mfma_f32_16x16x32_bf16 v[24:27], v[160:163], v[180:183], v[24:27]
	v_mfma_f32_16x16x32_bf16 v[20:23], v[164:167], v[180:183], v[20:23]
	v_mfma_f32_16x16x32_bf16 v[12:15], v[146:149], v[188:191], v[12:15]
	v_mfma_f32_16x16x32_bf16 v[8:11], v[160:163], v[188:191], v[8:11]
	v_mfma_f32_16x16x32_bf16 v[4:7], v[164:167], v[188:191], v[4:7]
	ds_read_b128 v[146:149], v128
	ds_read_b128 v[160:163], v128 offset:2048
	ds_read_b128 v[164:167], v128 offset:4096
	ds_read_b128 v[172:175], v128 offset:6144
	v_mfma_f32_16x16x32_bf16 v[32:35], v[168:171], v[176:179], v[32:35]
	v_mfma_f32_16x16x32_bf16 v[16:19], v[168:171], v[180:183], v[16:19]
	v_mfma_f32_16x16x32_bf16 v[0:3], v[168:171], v[188:191], v[0:3]
	s_waitcnt lgkmcnt(0)
	v_mfma_f32_16x16x32_bf16 v[124:127], v[192:195], v[146:149], v[124:127]
	v_mfma_f32_16x16x32_bf16 v[120:123], v[196:199], v[146:149], v[120:123]
	v_mfma_f32_16x16x32_bf16 v[116:119], v[200:203], v[146:149], v[116:119]
	v_mfma_f32_16x16x32_bf16 v[112:115], v[204:207], v[146:149], v[112:115]
	v_mfma_f32_16x16x32_bf16 v[108:111], v[192:195], v[160:163], v[108:111]
	v_mfma_f32_16x16x32_bf16 v[104:107], v[196:199], v[160:163], v[104:107]
	v_mfma_f32_16x16x32_bf16 v[100:103], v[200:203], v[160:163], v[100:103]
	v_mfma_f32_16x16x32_bf16 v[96:99], v[204:207], v[160:163], v[96:99]
	v_mfma_f32_16x16x32_bf16 v[92:95], v[192:195], v[164:167], v[92:95]
	v_mfma_f32_16x16x32_bf16 v[88:91], v[196:199], v[164:167], v[88:91]
	v_mfma_f32_16x16x32_bf16 v[84:87], v[200:203], v[164:167], v[84:87]
	v_mfma_f32_16x16x32_bf16 v[80:83], v[204:207], v[164:167], v[80:83]
	ds_read_b128 v[146:149], v128 offset:8192
	ds_read_b128 v[160:163], v128 offset:10240
	ds_read_b128 v[164:167], v128 offset:12288
	ds_read_b128 v[168:171], v128 offset:14336
	v_mfma_f32_16x16x32_bf16 v[76:79], v[192:195], v[172:175], v[76:79]
	v_mfma_f32_16x16x32_bf16 v[72:75], v[196:199], v[172:175], v[72:75]
	v_mfma_f32_16x16x32_bf16 v[68:71], v[200:203], v[172:175], v[68:71]
	v_mfma_f32_16x16x32_bf16 v[64:67], v[204:207], v[172:175], v[64:67]
	s_waitcnt lgkmcnt(0)
	v_mfma_f32_16x16x32_bf16 v[60:63], v[192:195], v[146:149], v[60:63]
	v_mfma_f32_16x16x32_bf16 v[56:59], v[196:199], v[146:149], v[56:59]
	v_mfma_f32_16x16x32_bf16 v[52:55], v[200:203], v[146:149], v[52:55]
	v_mfma_f32_16x16x32_bf16 v[48:51], v[204:207], v[146:149], v[48:51]
	v_mfma_f32_16x16x32_bf16 v[44:47], v[192:195], v[160:163], v[44:47]
	v_mfma_f32_16x16x32_bf16 v[40:43], v[196:199], v[160:163], v[40:43]
	v_mfma_f32_16x16x32_bf16 v[36:39], v[200:203], v[160:163], v[36:39]
	v_mfma_f32_16x16x32_bf16 v[32:35], v[204:207], v[160:163], v[32:35]
	v_mfma_f32_16x16x32_bf16 v[28:31], v[192:195], v[164:167], v[28:31]
	v_mfma_f32_16x16x32_bf16 v[24:27], v[196:199], v[164:167], v[24:27]
	v_mfma_f32_16x16x32_bf16 v[20:23], v[200:203], v[164:167], v[20:23]
	v_mfma_f32_16x16x32_bf16 v[16:19], v[204:207], v[164:167], v[16:19]
	v_mfma_f32_16x16x32_bf16 v[12:15], v[192:195], v[168:171], v[12:15]
	v_mfma_f32_16x16x32_bf16 v[8:11], v[196:199], v[168:171], v[8:11]
	v_mfma_f32_16x16x32_bf16 v[4:7], v[200:203], v[168:171], v[4:7]
	v_mfma_f32_16x16x32_bf16 v[0:3], v[204:207], v[168:171], v[0:3]
	s_add_u32 s8, s8, 0x80
	s_addc_u32 s9, s9, 0
	s_add_i32 s0, s0, 0x10000
	s_cmpk_lg_i32 s8, 0x780
	s_cbranch_scc1 .LBB0_300
; __device__ __forceinline__ void gemm_mainloop(f32x4 (&acc)[8][4], const GemmSrc& g, int K, char* lds) {
;     ...
;     for (int kt = 0; kt < KT; kt++) {
;         WAIT_V(0);
;         __builtin_amdgcn_s_barrier();
;         const char* st = lds + (kt & 1) * 65536;
;         bf16x8 afA[4], afB[4], bX[4], bY[4];
; #pragma unroll
;         for (int ni = 0; ni < 4; ni++) afA[ni] = *(const bf16x8*)(st + woff + ni * 16 * 128 + rdo0);
; #pragma unroll
;         for (int mi = 0; mi < 4; mi++) bX[mi] = *(const bf16x8*)(st + xoff + mi * 16 * 128 + rdo0);
;         if (kt + 1 < KT) gemm_issue(g, kt + 1, (kt + 1) & 1, lds);
; #pragma unroll
;         for (int mi = 0; mi < 4; mi++) bY[mi] = *(const bf16x8*)(st + xoff + (4 + mi) * 16 * 128 + rdo0);
; #pragma unroll
;         for (int ni = 0; ni < 4; ni++) afB[ni] = *(const bf16x8*)(st + woff + ni * 16 * 128 + rdo1);
; #pragma unroll
;         for (int mi = 0; mi < 4; mi++)
; #pragma unroll
;             for (int ni = 0; ni < 4; ni++) acc[mi][ni] = mfma16(afA[ni], bX[mi], acc[mi][ni]);
;         __builtin_amdgcn_sched_barrier(0);
; #pragma unroll
;         for (int mi = 0; mi < 4; mi++) bX[mi] = *(const bf16x8*)(st + xoff + mi * 16 * 128 + rdo1);
; #pragma unroll
;         for (int mi = 0; mi < 4; mi++)
; #pragma unroll
;             for (int ni = 0; ni < 4; ni++) acc[4 + mi][ni] = mfma16(afA[ni], bY[mi], acc[4 + mi][ni]);
;         __builtin_amdgcn_sched_barrier(0);
; #pragma unroll
;         for (int mi = 0; mi < 4; mi++) bY[mi] = *(const bf16x8*)(st + xoff + (4 + mi) * 16 * 128 + rdo1);
; #pragma unroll
;         for (int mi = 0; mi < 4; mi++)
; #pragma unroll
;             for (int ni = 0; ni < 4; ni++) acc[mi][ni] = mfma16(afB[ni], bX[mi], acc[mi][ni]);
;         __builtin_amdgcn_sched_barrier(0);
; #pragma unroll
;         for (int mi = 0; mi < 4; mi++)
; #pragma unroll
;             for (int ni = 0; ni < 4; ni++) acc[4 + mi][ni] = mfma16(afB[ni], bY[mi], acc[4 + mi][ni]);
;         __builtin_amdgcn_sched_barrier(0);
;     }
; __device__ __forceinline__ void gemm_core(f32x4 (&acc)[8][4], const bf16_t* __restrict__ X, int ldx, const bf16_t* __restrict__ W, int ldw,
;                                           int K, int m0, int n0, char* lds) {
;     ...
;     __syncthreads();
; __device__ void phaseC(const Params& p, char* lds) {
;     ...
;         const int c0 = n0 + wc * 64;
;         const bool isq = (c0 >= ZQ_N && c0 < ZKC);
	v_or_b32_e32 v128, 0x8000, v144
	v_add_u32_e32 v151, 0x10000, v143
	v_add3_u32 v150, v128, v142, s52
	v_add_u32_e32 v192, v151, v142
	s_waitcnt vmcnt(0)
	s_barrier
	ds_read_b128 v[134:137], v150
	ds_read_b128 v[138:141], v150 offset:2048
	ds_read_b128 v[142:145], v192
	ds_read_b128 v[146:149], v192 offset:2048
	ds_read_b128 v[160:163], v150 offset:4096
	ds_read_b128 v[164:167], v150 offset:6144
	s_waitcnt lgkmcnt(0)
	v_mfma_f32_16x16x32_bf16 v[124:127], v[134:137], v[142:145], v[124:127]
	v_add3_u32 v128, v128, v133, s52
	v_mfma_f32_16x16x32_bf16 v[120:123], v[138:141], v[142:145], v[120:123]
	v_mfma_f32_16x16x32_bf16 v[116:119], v[160:163], v[142:145], v[116:119]
	v_mfma_f32_16x16x32_bf16 v[112:115], v[164:167], v[142:145], v[112:115]
	v_mfma_f32_16x16x32_bf16 v[108:111], v[134:137], v[146:149], v[108:111]
	v_mfma_f32_16x16x32_bf16 v[104:107], v[138:141], v[146:149], v[104:107]
	v_mfma_f32_16x16x32_bf16 v[100:103], v[160:163], v[146:149], v[100:103]
	v_mfma_f32_16x16x32_bf16 v[96:99], v[164:167], v[146:149], v[96:99]
	ds_read_b128 v[142:145], v192 offset:4096
	ds_read_b128 v[146:149], v192 offset:6144
	s_waitcnt lgkmcnt(0)
	v_mfma_f32_16x16x32_bf16 v[92:95], v[134:137], v[142:145], v[92:95]
	v_mfma_f32_16x16x32_bf16 v[88:91], v[138:141], v[142:145], v[88:91]
	v_mfma_f32_16x16x32_bf16 v[84:87], v[160:163], v[142:145], v[84:87]
	v_mfma_f32_16x16x32_bf16 v[80:83], v[164:167], v[142:145], v[80:83]
	ds_read_b128 v[142:145], v128 offset:6144
	ds_read_b128 v[168:171], v128 offset:4096
	ds_read_b128 v[172:175], v128 offset:2048
	ds_read_b128 v[176:179], v128
	ds_read_b128 v[180:183], v192 offset:14336
	ds_read_b128 v[184:187], v192 offset:12288
	ds_read_b128 v[188:191], v192 offset:10240
	ds_read_b128 v[192:195], v192 offset:8192
	v_mfma_f32_16x16x32_bf16 v[76:79], v[134:137], v[146:149], v[76:79]
	v_mfma_f32_16x16x32_bf16 v[72:75], v[138:141], v[146:149], v[72:75]
	v_mfma_f32_16x16x32_bf16 v[68:71], v[160:163], v[146:149], v[68:71]
	v_mfma_f32_16x16x32_bf16 v[64:67], v[164:167], v[146:149], v[64:67]
	v_add_u32_e32 v128, v151, v133
	s_waitcnt lgkmcnt(0)
	v_mfma_f32_16x16x32_bf16 v[60:63], v[134:137], v[192:195], v[60:63]
	v_mfma_f32_16x16x32_bf16 v[56:59], v[138:141], v[192:195], v[56:59]
	v_mfma_f32_16x16x32_bf16 v[52:55], v[160:163], v[192:195], v[52:55]
	v_mfma_f32_16x16x32_bf16 v[44:47], v[134:137], v[188:191], v[44:47]
	v_mfma_f32_16x16x32_bf16 v[40:43], v[138:141], v[188:191], v[40:43]
	v_mfma_f32_16x16x32_bf16 v[36:39], v[160:163], v[188:191], v[36:39]
	v_mfma_f32_16x16x32_bf16 v[28:31], v[134:137], v[184:187], v[28:31]
	v_mfma_f32_16x16x32_bf16 v[24:27], v[138:141], v[184:187], v[24:27]
	v_mfma_f32_16x16x32_bf16 v[20:23], v[160:163], v[184:187], v[20:23]
	v_mfma_f32_16x16x32_bf16 v[12:15], v[134:137], v[180:183], v[12:15]
	v_mfma_f32_16x16x32_bf16 v[8:11], v[138:141], v[180:183], v[8:11]
	v_mfma_f32_16x16x32_bf16 v[4:7], v[160:163], v[180:183], v[4:7]
	ds_read_b128 v[134:137], v128
	ds_read_b128 v[138:141], v128 offset:2048
	ds_read_b128 v[146:149], v128 offset:4096
	ds_read_b128 v[160:163], v128 offset:6144
	v_mfma_f32_16x16x32_bf16 v[48:51], v[164:167], v[192:195], v[48:51]
	v_mfma_f32_16x16x32_bf16 v[32:35], v[164:167], v[188:191], v[32:35]
	v_mfma_f32_16x16x32_bf16 v[16:19], v[164:167], v[184:187], v[16:19]
	v_mfma_f32_16x16x32_bf16 v[0:3], v[164:167], v[180:183], v[0:3]
	s_waitcnt lgkmcnt(0)
	v_mfma_f32_16x16x32_bf16 v[124:127], v[176:179], v[134:137], v[124:127]
	v_mfma_f32_16x16x32_bf16 v[120:123], v[172:175], v[134:137], v[120:123]
	v_mfma_f32_16x16x32_bf16 v[116:119], v[168:171], v[134:137], v[116:119]
	v_mfma_f32_16x16x32_bf16 v[112:115], v[142:145], v[134:137], v[112:115]
	v_mfma_f32_16x16x32_bf16 v[108:111], v[176:179], v[138:141], v[108:111]
	v_mfma_f32_16x16x32_bf16 v[104:107], v[172:175], v[138:141], v[104:107]
	v_mfma_f32_16x16x32_bf16 v[100:103], v[168:171], v[138:141], v[100:103]
	v_mfma_f32_16x16x32_bf16 v[96:99], v[142:145], v[138:141], v[96:99]
	v_mfma_f32_16x16x32_bf16 v[92:95], v[176:179], v[146:149], v[92:95]
	v_mfma_f32_16x16x32_bf16 v[88:91], v[172:175], v[146:149], v[88:91]
	v_mfma_f32_16x16x32_bf16 v[84:87], v[168:171], v[146:149], v[84:87]
	v_mfma_f32_16x16x32_bf16 v[80:83], v[142:145], v[146:149], v[80:83]
	ds_read_b128 v[134:137], v128 offset:8192
	ds_read_b128 v[138:141], v128 offset:10240
	ds_read_b128 v[146:149], v128 offset:12288
	ds_read_b128 v[164:167], v128 offset:14336
	v_mfma_f32_16x16x32_bf16 v[76:79], v[176:179], v[160:163], v[76:79]
	v_mfma_f32_16x16x32_bf16 v[72:75], v[172:175], v[160:163], v[72:75]
	v_mfma_f32_16x16x32_bf16 v[68:71], v[168:171], v[160:163], v[68:71]
	v_mfma_f32_16x16x32_bf16 v[64:67], v[142:145], v[160:163], v[64:67]
	s_waitcnt lgkmcnt(0)
	v_mfma_f32_16x16x32_bf16 v[60:63], v[176:179], v[134:137], v[60:63]
	v_mfma_f32_16x16x32_bf16 v[56:59], v[172:175], v[134:137], v[56:59]
	v_mfma_f32_16x16x32_bf16 v[52:55], v[168:171], v[134:137], v[52:55]
	v_mfma_f32_16x16x32_bf16 v[48:51], v[142:145], v[134:137], v[48:51]
	v_mfma_f32_16x16x32_bf16 v[44:47], v[176:179], v[138:141], v[44:47]
	v_mfma_f32_16x16x32_bf16 v[40:43], v[172:175], v[138:141], v[40:43]
	v_mfma_f32_16x16x32_bf16 v[36:39], v[168:171], v[138:141], v[36:39]
	v_mfma_f32_16x16x32_bf16 v[32:35], v[142:145], v[138:141], v[32:35]
	v_mfma_f32_16x16x32_bf16 v[28:31], v[176:179], v[146:149], v[28:31]
	v_mfma_f32_16x16x32_bf16 v[24:27], v[172:175], v[146:149], v[24:27]
	v_mfma_f32_16x16x32_bf16 v[20:23], v[168:171], v[146:149], v[20:23]
	v_mfma_f32_16x16x32_bf16 v[16:19], v[142:145], v[146:149], v[16:19]
	v_mfma_f32_16x16x32_bf16 v[12:15], v[176:179], v[164:167], v[12:15]
	v_mfma_f32_16x16x32_bf16 v[8:11], v[172:175], v[164:167], v[8:11]
	v_mfma_f32_16x16x32_bf16 v[4:7], v[168:171], v[164:167], v[4:7]
	v_mfma_f32_16x16x32_bf16 v[0:3], v[142:145], v[164:167], v[0:3]
	s_and_b32 s0, s75, 0xfffffc
	s_cmp_eq_u32 s0, 12
	s_cselect_b64 vcc, -1, 0
	s_add_i32 s0, s44, 0xfffff000
	s_cmpk_lt_u32 s0, 0x300
	s_cselect_b64 s[8:9], -1, 0
	s_and_b64 s[8:9], s[8:9], s[4:5]
	s_or_b64 s[46:47], vcc, s[8:9]
	v_add_u32_e32 v136, s82, v153
	s_waitcnt vmcnt(0)
	s_barrier
; __device__ void phaseC(const Params& p, char* lds) {
;     ...
;             if (rope) {
;                 f32x4 v = acc[mi][0];
;                 f32x4 pr;
; #pragma unroll
;                 for (int j = 0; j < 4; j++) pr[j] = __shfl_xor(v[j], 32, 64);
;                 const int ib = (q & 1) * 4;
;                 const f32x4 k0 = *(const f32x4*)(cs + (size_t)tok * 16 + ib * 2);
;                 const f32x4 k1 = *(const f32x4*)(cs + (size_t)tok * 16 + ib * 2 + 4);
;                 const float cc[4] = {k0[0], k0[2], k1[0], k1[2]}, sn[4] = {k0[1], k0[3], k1[1], k1[3]};
; #pragma unroll
;                 for (int j = 0; j < 4; j++) v[j] = (q < 2) ? (v[j] * cc[j] - pr[j] * sn[j]) : (v[j] * cc[j] + pr[j] * sn[j]);
;                 acc[mi][0] = v;
	s_and_saveexec_b64 s[48:49], s[46:47]
	s_cbranch_execz .LBB0_303
	v_ashrrev_i32_e32 v137, 31, v136
	v_lshlrev_b64 v[134:135], 6, v[136:137]
	v_lshl_add_u64 v[134:135], v[130:131], 0, v[134:135]
	global_load_dwordx4 v[138:141], v[134:135], off
	global_load_dwordx4 v[142:145], v[134:135], off offset:16
	v_and_b32_e32 v133, 64, v159
	v_xor_b32_e32 v128, 32, v159
	v_add_u32_e32 v133, 64, v133
	v_cmp_lt_i32_e64 s[8:9], v128, v133
	s_waitcnt vmcnt(1)
	v_mov_b32_e32 v149, v140
	v_cndmask_b32_e64 v128, v159, v128, s[8:9]
	v_lshlrev_b32_e32 v128, 2, v128
	ds_bpermute_b32 v134, v128, v124
	ds_bpermute_b32 v135, v128, v125
	ds_bpermute_b32 v146, v128, v126
	ds_bpermute_b32 v147, v128, v127
	v_mov_b32_e32 v140, v139
	s_waitcnt vmcnt(0)
	v_mov_b32_e32 v139, v144
	v_mov_b32_e32 v144, v143
	s_waitcnt lgkmcnt(2)
	v_pk_mul_f32 v[134:135], v[140:141], v[134:135]
	s_waitcnt lgkmcnt(0)
	v_pk_mul_f32 v[140:141], v[144:145], v[146:147]
	v_mov_b32_e32 v148, v138
	v_mov_b32_e32 v138, v142
	v_cndmask_b32_e64 v135, v135, -v135, s[6:7]
	v_cndmask_b32_e64 v134, v134, -v134, s[6:7]
	v_cndmask_b32_e64 v141, v141, -v141, s[6:7]
	v_cndmask_b32_e64 v140, v140, -v140, s[6:7]
	v_pk_fma_f32 v[124:125], v[124:125], v[148:149], v[134:135]
	v_pk_fma_f32 v[126:127], v[126:127], v[138:139], v[140:141]

; __device__ __forceinline__ int launder_i(int x) { asm volatile("" : "+v"(x)); return x; }
; #define TIDX512 launder_i((int)threadIdx.x)
; __device__ __forceinline__ void glds16(const bf16_t* g, char* l) { __builtin_amdgcn_global_load_lds((const unsigned*)g, (unsigned*)l, 16, 0, 0); }
; __device__ __forceinline__ void gemm_issue(const GemmSrc& g, int kt, int s, char* lds) {
;     const int tid = TIDX512, lane = tid & 63, wave = tid >> 6;
;     char* xdst = lds + s * 65536 + wave * 4096 + lane * 16;
;     char* wdst = xdst + 32768;
; #pragma unroll
;     for (int i = 0; i < 4; i++) {
;         const int d = (i & 1) ? g.dsw : 0;
;         glds16(g.xsrc + (size_t)i * 8 * g.ldx + kt * 64 + d, xdst + i * 1024);
;         glds16(g.wsrc + (size_t)i * 8 * g.ldw + kt * 64 + d, wdst + i * 1024);
;     }
; }
; __device__ __forceinline__ void gemm_prologue(const GemmSrc& g, char* lds) { gemm_issue(g, 0, 0, lds); }
; __device__ void phaseM1(const Params& p, char* lds) {
;     ...
;     while (tit.next(bm, bn)) {
;         const int m0 = bm * 256, n0 = bn * 256;
;         const int pbase = launder_i(((bm * 4 + bn) * 16) * 512 + tid_);
;         GemmSrc g = gemm_src(H, DM, (const bf16_t*)(p.ws + OFF_WM), DM, m0, n0);
;         gemm_prologue(g, lds);
.LBB0_711:
	s_lshl_b32 s74, s2, 8
	s_lshl_b32 s48, s1, 8
	s_lshl_b32 s1, s1, 13
	s_lshl_b32 s2, s2, 15
	s_add_i32 s1, s1, s2
	v_add_u32_e32 v146, s1, v144
	v_mov_b32_e32 v0, v158
	s_ashr_i32 s49, s48, 31
	v_ashrrev_i32_e32 v1, 1, v0
	v_bfe_u32 v2, v0, 3, 3
	v_and_or_b32 v2, v1, s63, v2
	v_bfe_u32 v1, v0, 4, 2
	v_and_b32_e32 v3, 7, v0
	v_bitop3_b32 v4, v1, v0, 7 bitop3:0x78
	v_add_u32_e32 v0, s74, v2
	v_bitop3_b32 v3, v1, v3, 4 bitop3:0x36
	v_ashrrev_i32_e32 v1, 31, v0
	v_lshlrev_b64 v[0:1], 11, v[0:1]
	v_lshl_add_u64 v[0:1], s[8:9], 0, v[0:1]
	v_lshlrev_b32_e32 v128, 4, v4
	v_lshl_add_u64 v[132:133], v[0:1], 0, v[128:129]
	v_add_u32_e32 v0, s48, v2
	v_ashrrev_i32_e32 v1, 31, v0
	v_lshlrev_b64 v[0:1], 11, v[0:1]
	v_lshl_add_u64 v[0:1], s[12:13], 0, v[0:1]
	v_lshl_add_u64 v[130:131], v[0:1], 0, v[128:129]
	v_sub_u32_e32 v0, v3, v4
	v_lshlrev_b32_e32 v134, 3, v0
	v_mov_b32_e32 v0, v158
	v_ashrrev_i32_e32 v135, 31, v134
	v_lshlrev_b32_e32 v1, 6, v0
	v_lshlrev_b32_e32 v0, 4, v0
	v_and_b32_e32 v0, 0x3f0, v0
	v_and_or_b32 v6, v1, s65, v0
	v_add_u32_e32 v0, 0x8000, v6
	v_readfirstlane_b32 s1, v6
	s_mov_b32 m0, s1
	v_readfirstlane_b32 s1, v0
	v_lshlrev_b64 v[0:1], 1, v[134:135]
	v_or_b32_e32 v7, 0x400, v6
	s_cmp_lg_u32 s33, 0
	s_cbranch_scc1 .Ldma_skip_16
	global_load_lds_dwordx4 v[132:133], off
	s_add_u32 m0, m0, 0x4000
	v_lshl_add_u64 v[220:221], v[132:133], 0, s[100:101]
	global_load_lds_dwordx4 v[220:221], off
.Ldma_skip_16:
	s_mov_b32 m0, s1
	v_lshl_add_u64 v[2:3], v[132:133], 0, v[0:1]
	v_readfirstlane_b32 s1, v7
	v_add_u32_e32 v7, 0x8400, v6
	s_cmp_lg_u32 s33, 0
	s_cbranch_scc1 .Ldma_skip_17
	global_load_lds_dwordx4 v[130:131], off
	s_add_u32 m0, m0, 0x4000
	v_lshl_add_u64 v[220:221], v[130:131], 0, s[100:101]
	global_load_lds_dwordx4 v[220:221], off
.Ldma_skip_17:
	v_lshl_add_u64 v[4:5], v[2:3], 0, s[16:17]
	s_mov_b32 m0, s1
	v_lshl_add_u64 v[0:1], v[130:131], 0, v[0:1]
	v_readfirstlane_b32 s1, v7
	v_or_b32_e32 v7, 0x800, v6
	s_cmp_lg_u32 s33, 0
	s_cbranch_scc1 .Ldma_skip_18
	global_load_lds_dwordx4 v[4:5], off
	s_add_u32 m0, m0, 0x4000
	v_lshl_add_u64 v[220:221], v[4:5], 0, s[100:101]
	global_load_lds_dwordx4 v[220:221], off
.Ldma_skip_18:
	v_lshl_add_u64 v[4:5], v[0:1], 0, s[16:17]
	s_mov_b32 m0, s1
	v_readfirstlane_b32 s1, v7
	v_add_u32_e32 v7, 0x8800, v6
	s_cmp_lg_u32 s33, 0
	s_cbranch_scc1 .Ldma_skip_19
	global_load_lds_dwordx4 v[4:5], off
	s_add_u32 m0, m0, 0x4000
	v_lshl_add_u64 v[220:221], v[4:5], 0, s[100:101]
	global_load_lds_dwordx4 v[220:221], off
.Ldma_skip_19:
	v_lshl_add_u64 v[4:5], v[132:133], 0, s[18:19]
	s_mov_b32 m0, s1
	v_readfirstlane_b32 s1, v7
	s_cmp_lg_u32 s33, 0
	s_cbranch_scc1 .Ldma_skip_20
	global_load_lds_dwordx4 v[4:5], off
	s_add_u32 m0, m0, 0x4000
	v_lshl_add_u64 v[220:221], v[4:5], 0, s[100:101]
	global_load_lds_dwordx4 v[220:221], off
.Ldma_skip_20:
	v_lshl_add_u64 v[4:5], v[130:131], 0, s[18:19]
	s_mov_b32 m0, s1
	v_lshl_add_u64 v[2:3], v[2:3], 0, s[20:21]
	s_cmp_lg_u32 s33, 0
	s_cbranch_scc1 .Ldma_skip_21
	global_load_lds_dwordx4 v[4:5], off
	s_add_u32 m0, m0, 0x4000
	v_lshl_add_u64 v[220:221], v[4:5], 0, s[100:101]
	global_load_lds_dwordx4 v[220:221], off
.Ldma_skip_21:
	v_or_b32_e32 v4, 0xc00, v6
	v_lshl_add_u64 v[0:1], v[0:1], 0, s[20:21]
	v_readfirstlane_b32 s1, v4
	s_mov_b32 m0, s1
	s_add_i32 s71, s71, s0
	s_cmp_lg_u32 s33, 0
	s_cbranch_scc1 .Ldma_skip_22
	global_load_lds_dwordx4 v[2:3], off
	s_add_u32 m0, m0, 0x4000
	v_lshl_add_u64 v[220:221], v[2:3], 0, s[100:101]
	global_load_lds_dwordx4 v[220:221], off
.Ldma_skip_22:
	v_add_u32_e32 v2, 0x8c00, v6
	v_add_u32_e32 v147, 0x200, v146
	v_readfirstlane_b32 s1, v2
	s_mov_b32 m0, s1
	s_lshl_b64 s[0:1], s[48:49], 1
	s_cmp_lg_u32 s33, 0
	s_cbranch_scc1 .Ldma_skip_23
	global_load_lds_dwordx4 v[0:1], off
	s_add_u32 m0, m0, 0x4000
	v_lshl_add_u64 v[220:221], v[0:1], 0, s[100:101]
	global_load_lds_dwordx4 v[220:221], off
.Ldma_skip_23:
	s_add_u32 s50, s60, s0
	s_addc_u32 s51, s61, s1
	v_add_u32_e32 v148, 0x400, v146
	v_add_u32_e32 v149, 0x600, v146
	v_add_u32_e32 v150, 0x800, v146
	v_add_u32_e32 v151, 0xa00, v146
	v_add_u32_e32 v152, 0xc00, v146
	v_add_u32_e32 v153, 0xe00, v146
	v_add_u32_e32 v154, 0x1000, v146
	v_add_u32_e32 v155, 0x1200, v146
	v_add_u32_e32 v156, 0x1400, v146
	v_add_u32_e32 v157, 0x1600, v146
	v_add_u32_e32 v160, 0x1800, v146
	v_add_u32_e32 v161, 0x1a00, v146
	v_add_u32_e32 v162, 0x1c00, v146
	v_add_u32_e32 v163, 0x1e00, v146
	s_mov_b64 s[56:57], 0x400
	s_mov_b64 s[54:55], -1
	s_branch .LBB0_713

; #define TIDX512 launder_i((int)threadIdx.x)
; __device__ __forceinline__ f32x4 mfma16(bf16x8 a, bf16x8 b, f32x4 c) { return __builtin_amdgcn_mfma_f32_16x16x32_bf16(a, b, c, 0, 0, 0); }
; #define WAIT_V(n) asm volatile("s_waitcnt vmcnt(" #n ")" ::: "memory")
; __device__ __forceinline__ void gemm_mainloop(f32x4 (&acc)[8][4], const GemmSrc& g, int K, char* lds) {
;     const int tid = TIDX512, lane = tid & 63, wave = tid >> 6;
;     const int wr = wave >> 2, wc = wave & 3, r = lane & 15, q = lane >> 4;
;     const int KT = K / 64;
;     const int rdo0 = r * 128 + ((q ^ (r >> 1)) * 16), rdo1 = r * 128 + (((4 + q) ^ (r >> 1)) * 16);
;     const int woff = 32768 + wc * 64 * 128, xoff = wr * 128 * 128;
;     for (int kt = 0; kt < KT; kt++) {
;         WAIT_V(0);
;         __builtin_amdgcn_s_barrier();
;         const char* st = lds + (kt & 1) * 65536;
;         bf16x8 afA[4], afB[4], bX[4], bY[4];
; #pragma unroll
;         for (int ni = 0; ni < 4; ni++) afA[ni] = *(const bf16x8*)(st + woff + ni * 16 * 128 + rdo0);
; #pragma unroll
;         for (int mi = 0; mi < 4; mi++) bX[mi] = *(const bf16x8*)(st + xoff + mi * 16 * 128 + rdo0);
;         if (kt + 1 < KT) gemm_issue(g, kt + 1, (kt + 1) & 1, lds);
; #pragma unroll
;         for (int mi = 0; mi < 4; mi++) bY[mi] = *(const bf16x8*)(st + xoff + (4 + mi) * 16 * 128 + rdo0);
; #pragma unroll
;         for (int ni = 0; ni < 4; ni++) afB[ni] = *(const bf16x8*)(st + woff + ni * 16 * 128 + rdo1);
; #pragma unroll
;         for (int mi = 0; mi < 4; mi++)
; #pragma unroll
;             for (int ni = 0; ni < 4; ni++) acc[mi][ni] = mfma16(afA[ni], bX[mi], acc[mi][ni]);
.LBB0_714:
	s_add_i32 s1, s0, 0xffff0000
	s_and_b32 s1, s1, 0x10000
	v_or_b32_e32 v165, s1, v164
	v_add_u32_e32 v218, s1, v143
	v_add_u32_e32 v178, v165, v142
	v_add_u32_e32 v202, v218, v142
	v_mov_b32_e32 v198, v158
	s_waitcnt vmcnt(0)
	s_barrier
	ds_read_b128 v[166:169], v178 offset:32768
	ds_read_b128 v[170:173], v178 offset:34816
	ds_read_b128 v[174:177], v178 offset:36864
	ds_read_b128 v[178:181], v178 offset:38912
	ds_read_b128 v[182:185], v202
	ds_read_b128 v[186:189], v202 offset:2048
	ds_read_b128 v[190:193], v202 offset:4096
	ds_read_b128 v[194:197], v202 offset:6144
	s_and_b32 s1, s0, 0x10000
	v_lshlrev_b32_e32 v199, 6, v198
	v_and_b32_e32 v199, 0xfffff000, v199
	v_add_u32_e32 v199, s1, v199
	v_lshlrev_b32_e32 v198, 4, v198
	v_and_or_b32 v203, v198, s64, v199
	v_add_u32_e32 v204, 0x8000, v203
	v_readfirstlane_b32 s1, v203
	v_lshl_add_u64 v[198:199], v[132:133], 0, s[56:57]
	s_mov_b32 m0, s1
	v_readfirstlane_b32 s1, v204
	s_cmp_lg_u32 s33, 0
	s_cbranch_scc1 .Ldma_skip_24
	global_load_lds_dwordx4 v[198:199], off
	s_add_u32 m0, m0, 0x4000
	v_lshl_add_u64 v[220:221], v[198:199], 0, s[100:101]
	global_load_lds_dwordx4 v[220:221], off
.Ldma_skip_24:
	v_lshl_add_u64 v[198:199], v[130:131], 0, s[56:57]
	v_or_b32_e32 v204, 0x400, v203
	v_lshl_add_u64 v[200:201], v[198:199], 0, s[22:23]
	s_mov_b32 m0, s1
	v_readfirstlane_b32 s1, v204
	s_waitcnt lgkmcnt(0)
	v_mfma_f32_16x16x32_bf16 v[124:127], v[166:169], v[182:185], v[124:127]
	s_cmp_lg_u32 s33, 0
	s_cbranch_scc1 .Ldma_skip_25
	global_load_lds_dwordx4 v[200:201], off
	s_add_u32 m0, m0, 0x4000
	v_lshl_add_u64 v[220:221], v[200:201], 0, s[100:101]
	global_load_lds_dwordx4 v[220:221], off
.Ldma_skip_25:
	v_lshl_add_u64 v[200:201], v[134:135], 0, s[56:57]
	v_mfma_f32_16x16x32_bf16 v[120:123], v[170:173], v[182:185], v[120:123]
	s_mov_b32 m0, s1
	v_add_u32_e32 v165, v165, v128
	s_cmp_lg_u32 s33, 0
	s_cbranch_scc1 .Ldma_skip_26
	global_load_lds_dwordx4 v[200:201], off
	s_add_u32 m0, m0, 0x4000
	v_lshl_add_u64 v[220:221], v[200:201], 0, s[100:101]
	global_load_lds_dwordx4 v[220:221], off
.Ldma_skip_26:
	v_mfma_f32_16x16x32_bf16 v[116:119], v[174:177], v[182:185], v[116:119]
	v_lshl_add_u64 v[200:201], v[136:137], 0, s[56:57]
	v_mfma_f32_16x16x32_bf16 v[112:115], v[178:181], v[182:185], v[112:115]
	v_add_u32_e32 v184, 0x8400, v203
	v_lshl_add_u64 v[182:183], v[200:201], 0, s[24:25]
	v_readfirstlane_b32 s1, v184
	v_or_b32_e32 v184, 0x800, v203
	s_mov_b32 m0, s1
	v_readfirstlane_b32 s1, v184
	v_add_u32_e32 v184, 0x8800, v203
	s_cmp_lg_u32 s33, 0
	s_cbranch_scc1 .Ldma_skip_27
	global_load_lds_dwordx4 v[182:183], off
	s_add_u32 m0, m0, 0x4000
	v_lshl_add_u64 v[220:221], v[182:183], 0, s[100:101]
	global_load_lds_dwordx4 v[220:221], off
.Ldma_skip_27:
	v_lshl_add_u64 v[182:183], v[138:139], 0, s[56:57]
	s_mov_b32 m0, s1
	v_readfirstlane_b32 s1, v184
	v_or_b32_e32 v184, 0xc00, v203
	s_cmp_lg_u32 s33, 0
	s_cbranch_scc1 .Ldma_skip_28
	global_load_lds_dwordx4 v[182:183], off
	s_add_u32 m0, m0, 0x4000
	v_lshl_add_u64 v[220:221], v[182:183], 0, s[100:101]
	global_load_lds_dwordx4 v[220:221], off
.Ldma_skip_28:
	v_lshl_add_u64 v[182:183], v[198:199], 0, s[26:27]
	s_mov_b32 m0, s1
	v_readfirstlane_b32 s1, v184
	v_add_u32_e32 v184, 0x8c00, v203
	s_cmp_lg_u32 s33, 0
	s_cbranch_scc1 .Ldma_skip_29
	global_load_lds_dwordx4 v[182:183], off
	s_add_u32 m0, m0, 0x4000
	v_lshl_add_u64 v[220:221], v[182:183], 0, s[100:101]
	global_load_lds_dwordx4 v[220:221], off
.Ldma_skip_29:
	v_lshl_add_u64 v[182:183], v[140:141], 0, s[56:57]
	s_mov_b32 m0, s1
	v_readfirstlane_b32 s1, v184
	s_cmp_lg_u32 s33, 0
	s_cbranch_scc1 .Ldma_skip_30
	global_load_lds_dwordx4 v[182:183], off
	s_add_u32 m0, m0, 0x4000
	v_lshl_add_u64 v[220:221], v[182:183], 0, s[100:101]
	global_load_lds_dwordx4 v[220:221], off
.Ldma_skip_30:
	v_lshl_add_u64 v[182:183], v[200:201], 0, s[28:29]
	s_mov_b32 m0, s1
	v_mfma_f32_16x16x32_bf16 v[108:111], v[166:169], v[186:189], v[108:111]
	s_cmp_lg_u32 s33, 0
	s_cbranch_scc1 .Ldma_skip_31
	global_load_lds_dwordx4 v[182:183], off
	s_add_u32 m0, m0, 0x4000
	v_lshl_add_u64 v[220:221], v[182:183], 0, s[100:101]
	global_load_lds_dwordx4 v[220:221], off
.Ldma_skip_31:
	v_mfma_f32_16x16x32_bf16 v[104:107], v[170:173], v[186:189], v[104:107]
	v_mfma_f32_16x16x32_bf16 v[100:103], v[174:177], v[186:189], v[100:103]
	v_mfma_f32_16x16x32_bf16 v[96:99], v[178:181], v[186:189], v[96:99]
	ds_read_b128 v[182:185], v202 offset:8192
	ds_read_b128 v[186:189], v202 offset:10240
	v_mfma_f32_16x16x32_bf16 v[92:95], v[166:169], v[190:193], v[92:95]
	v_mfma_f32_16x16x32_bf16 v[88:91], v[170:173], v[190:193], v[88:91]
	v_mfma_f32_16x16x32_bf16 v[84:87], v[174:177], v[190:193], v[84:87]
	v_mfma_f32_16x16x32_bf16 v[80:83], v[178:181], v[190:193], v[80:83]
	ds_read_b128 v[190:193], v202 offset:12288
	ds_read_b128 v[198:201], v202 offset:14336
	ds_read_b128 v[202:205], v165 offset:32768
	ds_read_b128 v[206:209], v165 offset:34816
	ds_read_b128 v[210:213], v165 offset:36864
	ds_read_b128 v[214:217], v165 offset:38912
	v_mfma_f32_16x16x32_bf16 v[76:79], v[166:169], v[194:197], v[76:79]
	v_mfma_f32_16x16x32_bf16 v[72:75], v[170:173], v[194:197], v[72:75]
	v_mfma_f32_16x16x32_bf16 v[68:71], v[174:177], v[194:197], v[68:71]
	v_mfma_f32_16x16x32_bf16 v[64:67], v[178:181], v[194:197], v[64:67]
	v_add_u32_e32 v165, v218, v128
	s_waitcnt lgkmcnt(0)
; __device__ __forceinline__ f32x4 mfma16(bf16x8 a, bf16x8 b, f32x4 c) { return __builtin_amdgcn_mfma_f32_16x16x32_bf16(a, b, c, 0, 0, 0); }
; __device__ __forceinline__ void gemm_mainloop(f32x4 (&acc)[8][4], const GemmSrc& g, int K, char* lds) {
;     ...
;         __builtin_amdgcn_sched_barrier(0);
; #pragma unroll
;         for (int mi = 0; mi < 4; mi++) bX[mi] = *(const bf16x8*)(st + xoff + mi * 16 * 128 + rdo1);
; #pragma unroll
;         for (int mi = 0; mi < 4; mi++)
; #pragma unroll
;             for (int ni = 0; ni < 4; ni++) acc[4 + mi][ni] = mfma16(afA[ni], bY[mi], acc[4 + mi][ni]);
;         __builtin_amdgcn_sched_barrier(0);
; #pragma unroll
;         for (int mi = 0; mi < 4; mi++) bY[mi] = *(const bf16x8*)(st + xoff + (4 + mi) * 16 * 128 + rdo1);
; #pragma unroll
;         for (int mi = 0; mi < 4; mi++)
; #pragma unroll
;             for (int ni = 0; ni < 4; ni++) acc[mi][ni] = mfma16(afB[ni], bX[mi], acc[mi][ni]);
;         __builtin_amdgcn_sched_barrier(0);
; #pragma unroll
;         for (int mi = 0; mi < 4; mi++)
; #pragma unroll
;             for (int ni = 0; ni < 4; ni++) acc[4 + mi][ni] = mfma16(afB[ni], bY[mi], acc[4 + mi][ni]);
;         __builtin_amdgcn_sched_barrier(0);
	v_mfma_f32_16x16x32_bf16 v[60:63], v[166:169], v[182:185], v[60:63]
	v_mfma_f32_16x16x32_bf16 v[56:59], v[170:173], v[182:185], v[56:59]
	v_mfma_f32_16x16x32_bf16 v[52:55], v[174:177], v[182:185], v[52:55]
	v_mfma_f32_16x16x32_bf16 v[48:51], v[178:181], v[182:185], v[48:51]
	v_mfma_f32_16x16x32_bf16 v[44:47], v[166:169], v[186:189], v[44:47]
	v_mfma_f32_16x16x32_bf16 v[40:43], v[170:173], v[186:189], v[40:43]
	v_mfma_f32_16x16x32_bf16 v[36:39], v[174:177], v[186:189], v[36:39]
	v_mfma_f32_16x16x32_bf16 v[28:31], v[166:169], v[190:193], v[28:31]
	v_mfma_f32_16x16x32_bf16 v[24:27], v[170:173], v[190:193], v[24:27]
	v_mfma_f32_16x16x32_bf16 v[20:23], v[174:177], v[190:193], v[20:23]
	v_mfma_f32_16x16x32_bf16 v[12:15], v[166:169], v[198:201], v[12:15]
	v_mfma_f32_16x16x32_bf16 v[8:11], v[170:173], v[198:201], v[8:11]
	v_mfma_f32_16x16x32_bf16 v[4:7], v[174:177], v[198:201], v[4:7]
	ds_read_b128 v[166:169], v165
	ds_read_b128 v[170:173], v165 offset:2048
	ds_read_b128 v[174:177], v165 offset:4096
	ds_read_b128 v[182:185], v165 offset:6144
	v_mfma_f32_16x16x32_bf16 v[32:35], v[178:181], v[186:189], v[32:35]
	v_mfma_f32_16x16x32_bf16 v[16:19], v[178:181], v[190:193], v[16:19]
	v_mfma_f32_16x16x32_bf16 v[0:3], v[178:181], v[198:201], v[0:3]
	s_waitcnt lgkmcnt(0)
	v_mfma_f32_16x16x32_bf16 v[124:127], v[202:205], v[166:169], v[124:127]
	v_mfma_f32_16x16x32_bf16 v[120:123], v[206:209], v[166:169], v[120:123]
	v_mfma_f32_16x16x32_bf16 v[116:119], v[210:213], v[166:169], v[116:119]
	v_mfma_f32_16x16x32_bf16 v[112:115], v[214:217], v[166:169], v[112:115]
	v_mfma_f32_16x16x32_bf16 v[108:111], v[202:205], v[170:173], v[108:111]
	v_mfma_f32_16x16x32_bf16 v[104:107], v[206:209], v[170:173], v[104:107]
	v_mfma_f32_16x16x32_bf16 v[100:103], v[210:213], v[170:173], v[100:103]
	v_mfma_f32_16x16x32_bf16 v[96:99], v[214:217], v[170:173], v[96:99]
	v_mfma_f32_16x16x32_bf16 v[92:95], v[202:205], v[174:177], v[92:95]
	v_mfma_f32_16x16x32_bf16 v[88:91], v[206:209], v[174:177], v[88:91]
	v_mfma_f32_16x16x32_bf16 v[84:87], v[210:213], v[174:177], v[84:87]
	v_mfma_f32_16x16x32_bf16 v[80:83], v[214:217], v[174:177], v[80:83]
	ds_read_b128 v[166:169], v165 offset:8192
	ds_read_b128 v[170:173], v165 offset:10240
	ds_read_b128 v[174:177], v165 offset:12288
	ds_read_b128 v[178:181], v165 offset:14336
	v_mfma_f32_16x16x32_bf16 v[76:79], v[202:205], v[182:185], v[76:79]
	v_mfma_f32_16x16x32_bf16 v[72:75], v[206:209], v[182:185], v[72:75]
	v_mfma_f32_16x16x32_bf16 v[68:71], v[210:213], v[182:185], v[68:71]
	v_mfma_f32_16x16x32_bf16 v[64:67], v[214:217], v[182:185], v[64:67]
	s_waitcnt lgkmcnt(0)
	v_mfma_f32_16x16x32_bf16 v[60:63], v[202:205], v[166:169], v[60:63]
	v_mfma_f32_16x16x32_bf16 v[56:59], v[206:209], v[166:169], v[56:59]
	v_mfma_f32_16x16x32_bf16 v[52:55], v[210:213], v[166:169], v[52:55]
	v_mfma_f32_16x16x32_bf16 v[48:51], v[214:217], v[166:169], v[48:51]
	v_mfma_f32_16x16x32_bf16 v[44:47], v[202:205], v[170:173], v[44:47]
	v_mfma_f32_16x16x32_bf16 v[40:43], v[206:209], v[170:173], v[40:43]
	v_mfma_f32_16x16x32_bf16 v[36:39], v[210:213], v[170:173], v[36:39]
	v_mfma_f32_16x16x32_bf16 v[32:35], v[214:217], v[170:173], v[32:35]
	v_mfma_f32_16x16x32_bf16 v[28:31], v[202:205], v[174:177], v[28:31]
	v_mfma_f32_16x16x32_bf16 v[24:27], v[206:209], v[174:177], v[24:27]
	v_mfma_f32_16x16x32_bf16 v[20:23], v[210:213], v[174:177], v[20:23]
	v_mfma_f32_16x16x32_bf16 v[16:19], v[214:217], v[174:177], v[16:19]
	v_mfma_f32_16x16x32_bf16 v[12:15], v[202:205], v[178:181], v[12:15]
	v_mfma_f32_16x16x32_bf16 v[8:11], v[206:209], v[178:181], v[8:11]
	v_mfma_f32_16x16x32_bf16 v[4:7], v[210:213], v[178:181], v[4:7]
	v_mfma_f32_16x16x32_bf16 v[0:3], v[214:217], v[178:181], v[0:3]
	s_add_u32 s56, s56, 0x80
	s_addc_u32 s57, s57, 0
	s_add_i32 s0, s0, 0x10000
	s_cmpk_lg_i32 s56, 0x780
	s_cbranch_scc1 .LBB0_714
	v_or_b32_e32 v176, 0x8000, v164
	s_mov_b32 s0, 0x10000
	v_add_u32_e32 v143, 0x10000, v143
	v_add3_u32 v172, v176, v142, s0
	v_add_u32_e32 v142, v143, v142
	s_waitcnt vmcnt(0)
	s_barrier
	ds_read_b128 v[130:133], v172
	ds_read_b128 v[134:137], v172 offset:2048
	ds_read_b128 v[138:141], v142
	ds_read_b128 v[164:167], v142 offset:2048
	ds_read_b128 v[168:171], v172 offset:4096
	ds_read_b128 v[172:175], v172 offset:6144
	s_waitcnt lgkmcnt(0)
	v_mfma_f32_16x16x32_bf16 v[124:127], v[130:133], v[138:141], v[124:127]
	v_add3_u32 v184, v176, v128, s0
	v_mfma_f32_16x16x32_bf16 v[120:123], v[134:137], v[138:141], v[120:123]
	v_mfma_f32_16x16x32_bf16 v[116:119], v[168:171], v[138:141], v[116:119]
	v_mfma_f32_16x16x32_bf16 v[112:115], v[172:175], v[138:141], v[112:115]
	v_mfma_f32_16x16x32_bf16 v[108:111], v[130:133], v[164:167], v[108:111]
	v_mfma_f32_16x16x32_bf16 v[104:107], v[134:137], v[164:167], v[104:107]
	v_mfma_f32_16x16x32_bf16 v[100:103], v[168:171], v[164:167], v[100:103]
	v_mfma_f32_16x16x32_bf16 v[96:99], v[172:175], v[164:167], v[96:99]
	ds_read_b128 v[138:141], v142 offset:4096
	ds_read_b128 v[164:167], v142 offset:6144
	s_waitcnt lgkmcnt(0)
	v_mfma_f32_16x16x32_bf16 v[92:95], v[130:133], v[138:141], v[92:95]
	v_mfma_f32_16x16x32_bf16 v[88:91], v[134:137], v[138:141], v[88:91]
	v_mfma_f32_16x16x32_bf16 v[84:87], v[168:171], v[138:141], v[84:87]
	v_mfma_f32_16x16x32_bf16 v[80:83], v[172:175], v[138:141], v[80:83]
	ds_read_b128 v[138:141], v184 offset:6144
	ds_read_b128 v[176:179], v184 offset:4096
	ds_read_b128 v[180:183], v184 offset:2048
	ds_read_b128 v[184:187], v184
	ds_read_b128 v[188:191], v142 offset:14336
	ds_read_b128 v[192:195], v142 offset:12288
	ds_read_b128 v[196:199], v142 offset:10240
	ds_read_b128 v[200:203], v142 offset:8192
	v_mfma_f32_16x16x32_bf16 v[76:79], v[130:133], v[164:167], v[76:79]
	v_mfma_f32_16x16x32_bf16 v[72:75], v[134:137], v[164:167], v[72:75]
	v_mfma_f32_16x16x32_bf16 v[68:71], v[168:171], v[164:167], v[68:71]
	v_mfma_f32_16x16x32_bf16 v[64:67], v[172:175], v[164:167], v[64:67]
	v_add_u32_e32 v128, v143, v128
	s_waitcnt lgkmcnt(0)
; __device__ __forceinline__ int launder_i(int x) { asm volatile("" : "+v"(x)); return x; }
; #define TIDX512 launder_i((int)threadIdx.x)
; __device__ __forceinline__ float sigmoidf_(float x) { return __builtin_amdgcn_rcpf(1.f + __expf(-x)); }
; __device__ __forceinline__ void glds16(const bf16_t* g, char* l) { __builtin_amdgcn_global_load_lds((const unsigned*)g, (unsigned*)l, 16, 0, 0); }
; __device__ __forceinline__ void gemm_issue(const GemmSrc& g, int kt, int s, char* lds) {
;     const int tid = TIDX512, lane = tid & 63, wave = tid >> 6;
;     char* xdst = lds + s * 65536 + wave * 4096 + lane * 16;
;     char* wdst = xdst + 32768;
; #pragma unroll
;     for (int i = 0; i < 4; i++) {
;         const int d = (i & 1) ? g.dsw : 0;
;         glds16(g.xsrc + (size_t)i * 8 * g.ldx + kt * 64 + d, xdst + i * 1024);
;         glds16(g.wsrc + (size_t)i * 8 * g.ldw + kt * 64 + d, wdst + i * 1024);
;     }
; }
; __device__ __forceinline__ void gemm_prologue(const GemmSrc& g, char* lds) { gemm_issue(g, 0, 0, lds); }
; __device__ void phaseM1(const Params& p, char* lds) {
;     ...
;             __syncthreads();
;             g = gemm_src(Z + (br ? ZQ_N : ZR_G), ZC, (const bf16_t*)(p.ws + (br ? OFF_WB : OFF_WA)), DM, m0, n0);
;             gemm_prologue(g, lds);
;             {
; #pragma unroll
;                 for (int mi = 0; mi < 8; mi++)
; #pragma unroll
;                     for (int nh = 0; nh < 2; nh++) {
;                         const f32x4 a0 = acc[mi][2 * nh], a1 = acc[mi][2 * nh + 1];
;                         SG[(size_t)launder_i(pbase + (mi * 2 + nh) * 512)] = (u32x4){pack2(sigmoidf_(a0[0]), sigmoidf_(a0[1])), pack2(sigmoidf_(a0[2]), sigmoidf_(a0[3])),
;                                                                           pack2(sigmoidf_(a1[0]), sigmoidf_(a1[1])), pack2(sigmoidf_(a1[2]), sigmoidf_(a1[3]))};
	v_mfma_f32_16x16x32_bf16 v[60:63], v[130:133], v[200:203], v[60:63]
	v_mfma_f32_16x16x32_bf16 v[56:59], v[134:137], v[200:203], v[56:59]
	v_mfma_f32_16x16x32_bf16 v[52:55], v[168:171], v[200:203], v[52:55]
	v_mfma_f32_16x16x32_bf16 v[44:47], v[130:133], v[196:199], v[44:47]
	v_mfma_f32_16x16x32_bf16 v[40:43], v[134:137], v[196:199], v[40:43]
	v_mfma_f32_16x16x32_bf16 v[36:39], v[168:171], v[196:199], v[36:39]
	v_mfma_f32_16x16x32_bf16 v[28:31], v[130:133], v[192:195], v[28:31]
	v_mfma_f32_16x16x32_bf16 v[24:27], v[134:137], v[192:195], v[24:27]
	v_mfma_f32_16x16x32_bf16 v[20:23], v[168:171], v[192:195], v[20:23]
	v_mfma_f32_16x16x32_bf16 v[12:15], v[130:133], v[188:191], v[12:15]
	v_mfma_f32_16x16x32_bf16 v[8:11], v[134:137], v[188:191], v[8:11]
	v_mfma_f32_16x16x32_bf16 v[4:7], v[168:171], v[188:191], v[4:7]
	ds_read_b128 v[130:133], v128
	ds_read_b128 v[134:137], v128 offset:2048
	ds_read_b128 v[164:167], v128 offset:4096
	ds_read_b128 v[168:171], v128 offset:6144
	v_mfma_f32_16x16x32_bf16 v[48:51], v[172:175], v[200:203], v[48:51]
	v_mfma_f32_16x16x32_bf16 v[32:35], v[172:175], v[196:199], v[32:35]
	v_mfma_f32_16x16x32_bf16 v[16:19], v[172:175], v[192:195], v[16:19]
	v_mfma_f32_16x16x32_bf16 v[0:3], v[172:175], v[188:191], v[0:3]
	s_waitcnt lgkmcnt(0)
	v_mfma_f32_16x16x32_bf16 v[124:127], v[184:187], v[130:133], v[124:127]
	v_mfma_f32_16x16x32_bf16 v[120:123], v[180:183], v[130:133], v[120:123]
	v_mfma_f32_16x16x32_bf16 v[116:119], v[176:179], v[130:133], v[116:119]
	v_mfma_f32_16x16x32_bf16 v[172:175], v[138:141], v[130:133], v[112:115]
	v_mfma_f32_16x16x32_bf16 v[108:111], v[184:187], v[134:137], v[108:111]
	v_mfma_f32_16x16x32_bf16 v[104:107], v[180:183], v[134:137], v[104:107]
	v_mfma_f32_16x16x32_bf16 v[100:103], v[176:179], v[134:137], v[100:103]
	v_mfma_f32_16x16x32_bf16 v[96:99], v[138:141], v[134:137], v[96:99]
	v_mfma_f32_16x16x32_bf16 v[92:95], v[184:187], v[164:167], v[92:95]
	v_mfma_f32_16x16x32_bf16 v[88:91], v[180:183], v[164:167], v[88:91]
	v_mfma_f32_16x16x32_bf16 v[84:87], v[176:179], v[164:167], v[84:87]
	v_mfma_f32_16x16x32_bf16 v[80:83], v[138:141], v[164:167], v[80:83]
	ds_read_b128 v[112:115], v128 offset:8192
	ds_read_b128 v[130:133], v128 offset:10240
	ds_read_b128 v[134:137], v128 offset:12288
	ds_read_b128 v[164:167], v128 offset:14336
	v_mfma_f32_16x16x32_bf16 v[76:79], v[184:187], v[168:171], v[76:79]
	v_mfma_f32_16x16x32_bf16 v[72:75], v[180:183], v[168:171], v[72:75]
	v_mfma_f32_16x16x32_bf16 v[68:71], v[176:179], v[168:171], v[68:71]
	v_mfma_f32_16x16x32_bf16 v[64:67], v[138:141], v[168:171], v[64:67]
	s_waitcnt lgkmcnt(0)
	v_mfma_f32_16x16x32_bf16 v[60:63], v[184:187], v[112:115], v[60:63]
	v_mfma_f32_16x16x32_bf16 v[56:59], v[180:183], v[112:115], v[56:59]
	v_mfma_f32_16x16x32_bf16 v[52:55], v[176:179], v[112:115], v[52:55]
	v_mfma_f32_16x16x32_bf16 v[48:51], v[138:141], v[112:115], v[48:51]
	v_mfma_f32_16x16x32_bf16 v[44:47], v[184:187], v[130:133], v[44:47]
	v_mfma_f32_16x16x32_bf16 v[40:43], v[180:183], v[130:133], v[40:43]
	v_mfma_f32_16x16x32_bf16 v[36:39], v[176:179], v[130:133], v[36:39]
	v_mfma_f32_16x16x32_bf16 v[32:35], v[138:141], v[130:133], v[32:35]
	v_mfma_f32_16x16x32_bf16 v[28:31], v[184:187], v[134:137], v[28:31]
	v_mfma_f32_16x16x32_bf16 v[24:27], v[180:183], v[134:137], v[24:27]
	v_mfma_f32_16x16x32_bf16 v[20:23], v[176:179], v[134:137], v[20:23]
	v_mfma_f32_16x16x32_bf16 v[16:19], v[138:141], v[134:137], v[16:19]
	v_mfma_f32_16x16x32_bf16 v[12:15], v[184:187], v[164:167], v[12:15]
	v_mfma_f32_16x16x32_bf16 v[8:11], v[180:183], v[164:167], v[8:11]
	v_mfma_f32_16x16x32_bf16 v[4:7], v[176:179], v[164:167], v[4:7]
	v_mfma_f32_16x16x32_bf16 v[0:3], v[138:141], v[164:167], v[0:3]
	s_and_b64 s[2:3], s[54:55], exec
	v_mov_b32_e32 v112, v158
	s_waitcnt vmcnt(0)
	s_barrier
	s_cselect_b32 s30, 0x1000, s67
	s_add_u32 s2, s58, s30
	v_ashrrev_i32_e32 v113, 1, v112
	v_and_b32_e32 v114, 0xffffffe0, v113
	v_bfe_u32 v115, v112, 3, 3
	s_addc_u32 s3, s59, 0
	v_or_b32_e32 v130, v114, v115
	v_bfe_u32 v113, v112, 4, 2
	v_and_b32_e32 v128, 7, v112
	v_bitop3_b32 v134, v113, v112, 7 bitop3:0x78
	v_bitop3_b32 v135, v113, v128, 4 bitop3:0x36
	v_add_u32_e32 v128, s74, v130
	v_mov_b64_e32 v[112:113], s[2:3]
	s_and_b64 s[54:55], s[54:55], exec
	v_mad_i64_i32 v[112:113], s[2:3], v128, s70, v[112:113]
	v_lshlrev_b32_e32 v128, 4, v134
	s_cselect_b32 s54, s69, 0x13c0000
	v_lshl_add_u64 v[132:133], v[112:113], 0, v[128:129]
	v_add_u32_e32 v112, s48, v130
	s_add_u32 s56, s6, s54
	v_ashrrev_i32_e32 v113, 31, v112
	s_addc_u32 s57, s7, 0
	v_lshlrev_b64 v[112:113], 11, v[112:113]
	v_lshl_add_u64 v[112:113], s[56:57], 0, v[112:113]
	v_lshl_add_u64 v[130:131], v[112:113], 0, v[128:129]
	v_sub_u32_e32 v112, v135, v134
	v_lshlrev_b32_e32 v134, 3, v112
	v_mov_b32_e32 v112, v158
	v_ashrrev_i32_e32 v135, 31, v134
	v_lshlrev_b32_e32 v113, 6, v112
	v_lshlrev_b32_e32 v112, 4, v112
	v_and_b32_e32 v112, 0x3f0, v112
	v_and_or_b32 v142, v113, s65, v112
	v_add_u32_e32 v112, 0x8000, v142
	v_readfirstlane_b32 s1, v142
	s_mov_b32 m0, s1
	v_readfirstlane_b32 s1, v112
	v_lshlrev_b64 v[112:113], 1, v[134:135]
	v_or_b32_e32 v135, 0x400, v142
	s_cmp_lg_u32 s33, 0
	s_cbranch_scc1 .Ldma_skip_32
	global_load_lds_dwordx4 v[132:133], off
	s_add_u32 m0, m0, 0x4000
	v_lshl_add_u64 v[220:221], v[132:133], 0, s[98:99]
	global_load_lds_dwordx4 v[220:221], off
.Ldma_skip_32:
	s_mov_b32 m0, s1
	v_lshl_add_u64 v[136:137], v[132:133], 0, v[112:113]
	v_readfirstlane_b32 s1, v135
	v_mul_f32_e32 v120, 0xbfb8aa3b, v120
	s_cmp_lg_u32 s33, 0
	s_cbranch_scc1 .Ldma_skip_33
	global_load_lds_dwordx4 v[130:131], off
	s_add_u32 m0, m0, 0x4000
	v_lshl_add_u64 v[220:221], v[130:131], 0, s[100:101]
	global_load_lds_dwordx4 v[220:221], off
; __device__ __forceinline__ int launder_i(int x) { asm volatile("" : "+v"(x)); return x; }
; #define TIDX512 launder_i((int)threadIdx.x)
; __device__ __forceinline__ float sigmoidf_(float x) { return __builtin_amdgcn_rcpf(1.f + __expf(-x)); }
; __device__ __forceinline__ void glds16(const bf16_t* g, char* l) { __builtin_amdgcn_global_load_lds((const unsigned*)g, (unsigned*)l, 16, 0, 0); }
; __device__ __forceinline__ void gemm_prologue(const GemmSrc& g, char* lds) { gemm_issue(g, 0, 0, lds); }
; __device__ __forceinline__ void gemm_issue(const GemmSrc& g, int kt, int s, char* lds) {
;     const int tid = TIDX512, lane = tid & 63, wave = tid >> 6;
;     char* xdst = lds + s * 65536 + wave * 4096 + lane * 16;
;     char* wdst = xdst + 32768;
; #pragma unroll
;     for (int i = 0; i < 4; i++) {
;         const int d = (i & 1) ? g.dsw : 0;
;         glds16(g.xsrc + (size_t)i * 8 * g.ldx + kt * 64 + d, xdst + i * 1024);
;         glds16(g.wsrc + (size_t)i * 8 * g.ldw + kt * 64 + d, wdst + i * 1024);
;     }
; __device__ void phaseM1(const Params& p, char* lds) {
;     ...
;             g = gemm_src(Z + (br ? ZQ_N : ZR_G), ZC, (const bf16_t*)(p.ws + (br ? OFF_WB : OFF_WA)), DM, m0, n0);
;             gemm_prologue(g, lds);
;             {
; #pragma unroll
;                 for (int mi = 0; mi < 8; mi++)
; #pragma unroll
;                     for (int nh = 0; nh < 2; nh++) {
;                         const f32x4 a0 = acc[mi][2 * nh], a1 = acc[mi][2 * nh + 1];
;                         SG[(size_t)launder_i(pbase + (mi * 2 + nh) * 512)] = (u32x4){pack2(sigmoidf_(a0[0]), sigmoidf_(a0[1])), pack2(sigmoidf_(a0[2]), sigmoidf_(a0[3])),
;                                                                           pack2(sigmoidf_(a1[0]), sigmoidf_(a1[1])), pack2(sigmoidf_(a1[2]), sigmoidf_(a1[3]))};
;                     }
.Ldma_skip_33:
	v_lshl_add_u64 v[138:139], v[136:137], 0, s[34:35]
	s_mov_b32 m0, s1
	v_add_u32_e32 v135, 0x8400, v142
	v_exp_f32_e32 v120, v120
	v_mul_f32_e32 v121, 0xbfb8aa3b, v121
	s_cmp_lg_u32 s33, 0
	s_cbranch_scc1 .Ldma_skip_34
	global_load_lds_dwordx4 v[138:139], off
	s_add_u32 m0, m0, 0x4000
	v_lshl_add_u64 v[220:221], v[138:139], 0, s[98:99]
	global_load_lds_dwordx4 v[220:221], off
.Ldma_skip_34:
	v_lshl_add_u64 v[138:139], v[130:131], 0, v[112:113]
	v_readfirstlane_b32 s1, v135
	v_or_b32_e32 v135, 0x800, v142
	v_exp_f32_e32 v121, v121
	v_lshl_add_u64 v[140:141], v[138:139], 0, s[16:17]
	s_mov_b32 m0, s1
	v_readfirstlane_b32 s1, v135
	v_add_u32_e32 v135, 0x8800, v142
	s_cmp_lg_u32 s33, 0
	s_cbranch_scc1 .Ldma_skip_35
	global_load_lds_dwordx4 v[140:141], off
	s_add_u32 m0, m0, 0x4000
	v_lshl_add_u64 v[220:221], v[140:141], 0, s[100:101]
	global_load_lds_dwordx4 v[220:221], off
.Ldma_skip_35:
	v_lshl_add_u64 v[140:141], v[132:133], 0, s[36:37]
	s_mov_b32 m0, s1
	v_readfirstlane_b32 s1, v135
	v_or_b32_e32 v135, 0xc00, v142
	s_cmp_lg_u32 s33, 0
	s_cbranch_scc1 .Ldma_skip_36
	global_load_lds_dwordx4 v[140:141], off
	s_add_u32 m0, m0, 0x4000
	v_lshl_add_u64 v[220:221], v[140:141], 0, s[98:99]
	global_load_lds_dwordx4 v[220:221], off
.Ldma_skip_36:
	v_lshl_add_u64 v[140:141], v[130:131], 0, s[18:19]
	s_mov_b32 m0, s1
	v_readfirstlane_b32 s1, v135
	v_add_u32_e32 v135, 0x8c00, v142
	v_mul_f32_e32 v124, 0xbfb8aa3b, v124
	v_mul_f32_e32 v125, 0xbfb8aa3b, v125
	v_add_f32_e32 v120, 1.0, v120
	s_cmp_lg_u32 s33, 0
	s_cbranch_scc1 .Ldma_skip_37
	global_load_lds_dwordx4 v[140:141], off
	s_add_u32 m0, m0, 0x4000
	v_lshl_add_u64 v[220:221], v[140:141], 0, s[100:101]
	global_load_lds_dwordx4 v[220:221], off
.Ldma_skip_37:
	s_mov_b32 m0, s1
	v_readfirstlane_b32 s1, v135
	v_exp_f32_e32 v124, v124
	v_exp_f32_e32 v125, v125
	v_rcp_f32_e32 v135, v120
	v_add_f32_e32 v120, 1.0, v121
	v_mul_f32_e32 v121, 0xbfb8aa3b, v122
	v_mul_f32_e32 v126, 0xbfb8aa3b, v126
	v_mul_f32_e32 v127, 0xbfb8aa3b, v127
	v_exp_f32_e32 v121, v121
	v_mul_f32_e32 v122, 0xbfb8aa3b, v123
	v_exp_f32_e32 v126, v126
	v_exp_f32_e32 v127, v127
	v_exp_f32_e32 v122, v122
	v_lshl_add_u64 v[136:137], v[136:137], 0, s[38:39]
	v_add_f32_e32 v124, 1.0, v124
	v_add_f32_e32 v125, 1.0, v125
	s_cmp_lg_u32 s33, 0
	s_cbranch_scc1 .Ldma_skip_38
	global_load_lds_dwordx4 v[136:137], off
	s_add_u32 m0, m0, 0x4000
	v_lshl_add_u64 v[220:221], v[136:137], 0, s[98:99]
	global_load_lds_dwordx4 v[220:221], off
.Ldma_skip_38:
	v_lshl_add_u64 v[136:137], v[138:139], 0, s[20:21]
	s_mov_b32 m0, s1
	v_rcp_f32_e32 v124, v124
	v_rcp_f32_e32 v125, v125
	v_rcp_f32_e32 v123, v120
	v_add_f32_e32 v120, 1.0, v121
	s_cmp_lg_u32 s33, 0
	s_cbranch_scc1 .Ldma_skip_39
	global_load_lds_dwordx4 v[136:137], off
	s_add_u32 m0, m0, 0x4000
	v_lshl_add_u64 v[220:221], v[136:137], 0, s[100:101]
	global_load_lds_dwordx4 v[220:221], off
.Ldma_skip_39:
	v_add_f32_e32 v126, 1.0, v126
	v_add_f32_e32 v127, 1.0, v127
	v_rcp_f32_e32 v136, v120
	v_add_f32_e32 v120, 1.0, v122
	v_rcp_f32_e32 v126, v126
	v_rcp_f32_e32 v127, v127
	v_rcp_f32_e32 v137, v120
	v_cvt_pk_bf16_f32 v120, v124, v125
	v_mov_b32_e32 v124, v146
	v_cvt_pk_bf16_f32 v121, v126, v127
	v_ashrrev_i32_e32 v125, 31, v124
	v_cvt_pk_bf16_f32 v122, v135, v123
	v_cvt_pk_bf16_f32 v123, v136, v137
	v_lshl_add_u64 v[124:125], v[124:125], 4, s[4:5]
	v_mul_f32_e32 v116, 0xbfb8aa3b, v116
	v_mul_f32_e32 v117, 0xbfb8aa3b, v117
	global_store_dwordx4 v[124:125], v[120:123], off
	v_mul_f32_e32 v118, 0xbfb8aa3b, v118
	v_mul_f32_e32 v119, 0xbfb8aa3b, v119
	v_mul_f32_e32 v120, 0xbfb8aa3b, v172
	v_mul_f32_e32 v121, 0xbfb8aa3b, v173
	v_exp_f32_e32 v116, v116
	v_exp_f32_e32 v117, v117
	v_exp_f32_e32 v118, v118
	v_exp_f32_e32 v119, v119
	v_exp_f32_e32 v120, v120
	v_exp_f32_e32 v121, v121
	v_mul_f32_e32 v122, 0xbfb8aa3b, v174
	v_mul_f32_e32 v123, 0xbfb8aa3b, v175
	v_exp_f32_e32 v122, v122
	v_exp_f32_e32 v123, v123
	v_add_f32_e32 v116, 1.0, v116
	v_add_f32_e32 v117, 1.0, v117
	v_add_f32_e32 v118, 1.0, v118
	v_add_f32_e32 v119, 1.0, v119
	v_add_f32_e32 v120, 1.0, v120
	v_add_f32_e32 v121, 1.0, v121
	v_rcp_f32_e32 v116, v116
	v_rcp_f32_e32 v117, v117
	v_rcp_f32_e32 v118, v118
	v_rcp_f32_e32 v119, v119
	v_rcp_f32_e32 v120, v120
	v_rcp_f32_e32 v121, v121
	v_add_f32_e32 v122, 1.0, v122
	v_add_f32_e32 v123, 1.0, v123
	v_mul_f32_e32 v104, 0xbfb8aa3b, v104
	v_rcp_f32_e32 v122, v122
	v_rcp_f32_e32 v123, v123
	v_exp_f32_e32 v104, v104
	v_mul_f32_e32 v105, 0xbfb8aa3b, v105
	v_exp_f32_e32 v105, v105
	v_cvt_pk_bf16_f32 v116, v116, v117
	v_cvt_pk_bf16_f32 v117, v118, v119
	v_cvt_pk_bf16_f32 v118, v120, v121
	v_mov_b32_e32 v120, v147
	v_cvt_pk_bf16_f32 v119, v122, v123
	v_ashrrev_i32_e32 v121, 31, v120
	v_lshl_add_u64 v[120:121], v[120:121], 4, s[4:5]
	v_mul_f32_e32 v108, 0xbfb8aa3b, v108
	v_mul_f32_e32 v109, 0xbfb8aa3b, v109
	v_add_f32_e32 v104, 1.0, v104
	v_exp_f32_e32 v108, v108
	v_exp_f32_e32 v109, v109
	global_store_dwordx4 v[120:121], v[116:119], off
	v_mul_f32_e32 v110, 0xbfb8aa3b, v110
	v_mul_f32_e32 v111, 0xbfb8aa3b, v111
	v_rcp_f32_e32 v116, v104
	v_add_f32_e32 v104, 1.0, v105
	v_mul_f32_e32 v105, 0xbfb8aa3b, v106
	v_exp_f32_e32 v105, v105
	v_mul_f32_e32 v106, 0xbfb8aa3b, v107
	v_exp_f32_e32 v110, v110
	v_exp_f32_e32 v111, v111
	v_exp_f32_e32 v106, v106
	v_add_f32_e32 v108, 1.0, v108
	v_add_f32_e32 v109, 1.0, v109
	v_rcp_f32_e32 v108, v108
	v_rcp_f32_e32 v109, v109
	v_rcp_f32_e32 v107, v104
	v_add_f32_e32 v104, 1.0, v105
	v_add_f32_e32 v110, 1.0, v110
	v_add_f32_e32 v111, 1.0, v111
	v_rcp_f32_e32 v117, v104
	v_add_f32_e32 v104, 1.0, v106
	v_mul_f32_e32 v96, 0xbfb8aa3b, v96
	v_rcp_f32_e32 v110, v110
	v_rcp_f32_e32 v111, v111
; __device__ __forceinline__ int launder_i(int x) { asm volatile("" : "+v"(x)); return x; }
; __device__ __forceinline__ float sigmoidf_(float x) { return __builtin_amdgcn_rcpf(1.f + __expf(-x)); }
; __device__ void phaseM1(const Params& p, char* lds) {
;     ...
; #pragma unroll
;                 for (int mi = 0; mi < 8; mi++)
; #pragma unroll
;                     for (int nh = 0; nh < 2; nh++) {
;                         const f32x4 a0 = acc[mi][2 * nh], a1 = acc[mi][2 * nh + 1];
;                         SG[(size_t)launder_i(pbase + (mi * 2 + nh) * 512)] = (u32x4){pack2(sigmoidf_(a0[0]), sigmoidf_(a0[1])), pack2(sigmoidf_(a0[2]), sigmoidf_(a0[3])),
;                                                                           pack2(sigmoidf_(a1[0]), sigmoidf_(a1[1])), pack2(sigmoidf_(a1[2]), sigmoidf_(a1[3]))};
;                     }
	v_rcp_f32_e32 v118, v104
	v_exp_f32_e32 v96, v96
	v_mul_f32_e32 v97, 0xbfb8aa3b, v97
	v_exp_f32_e32 v97, v97
	v_cvt_pk_bf16_f32 v104, v108, v109
	v_mov_b32_e32 v108, v148
	v_cvt_pk_bf16_f32 v105, v110, v111
	v_ashrrev_i32_e32 v109, 31, v108
	v_cvt_pk_bf16_f32 v106, v116, v107
	v_cvt_pk_bf16_f32 v107, v117, v118
	v_lshl_add_u64 v[108:109], v[108:109], 4, s[4:5]
	v_mul_f32_e32 v100, 0xbfb8aa3b, v100
	v_mul_f32_e32 v101, 0xbfb8aa3b, v101
	v_add_f32_e32 v96, 1.0, v96
	v_exp_f32_e32 v100, v100
	v_exp_f32_e32 v101, v101
	global_store_dwordx4 v[108:109], v[104:107], off
	v_mul_f32_e32 v102, 0xbfb8aa3b, v102
	v_mul_f32_e32 v103, 0xbfb8aa3b, v103
	v_rcp_f32_e32 v104, v96
	v_add_f32_e32 v96, 1.0, v97
	v_mul_f32_e32 v97, 0xbfb8aa3b, v98
	v_exp_f32_e32 v97, v97
	v_mul_f32_e32 v98, 0xbfb8aa3b, v99
	v_exp_f32_e32 v102, v102
	v_exp_f32_e32 v103, v103
	v_exp_f32_e32 v98, v98
	v_add_f32_e32 v100, 1.0, v100
	v_add_f32_e32 v101, 1.0, v101
	v_rcp_f32_e32 v100, v100
	v_rcp_f32_e32 v101, v101
	v_rcp_f32_e32 v99, v96
	v_add_f32_e32 v96, 1.0, v97
	v_add_f32_e32 v102, 1.0, v102
	v_add_f32_e32 v103, 1.0, v103
	v_rcp_f32_e32 v105, v96
	v_add_f32_e32 v96, 1.0, v98
	v_mul_f32_e32 v88, 0xbfb8aa3b, v88
	v_rcp_f32_e32 v102, v102
	v_rcp_f32_e32 v103, v103
	v_rcp_f32_e32 v106, v96
	v_exp_f32_e32 v88, v88
	v_mul_f32_e32 v89, 0xbfb8aa3b, v89
	v_exp_f32_e32 v89, v89
	v_cvt_pk_bf16_f32 v96, v100, v101
	v_mov_b32_e32 v100, v149
	v_cvt_pk_bf16_f32 v97, v102, v103
	v_ashrrev_i32_e32 v101, 31, v100
	v_cvt_pk_bf16_f32 v98, v104, v99
	v_cvt_pk_bf16_f32 v99, v105, v106
	v_lshl_add_u64 v[100:101], v[100:101], 4, s[4:5]
	v_mul_f32_e32 v92, 0xbfb8aa3b, v92
	v_mul_f32_e32 v93, 0xbfb8aa3b, v93
	v_add_f32_e32 v88, 1.0, v88
	v_exp_f32_e32 v92, v92
	v_exp_f32_e32 v93, v93
	global_store_dwordx4 v[100:101], v[96:99], off
	v_mul_f32_e32 v94, 0xbfb8aa3b, v94
	v_mul_f32_e32 v95, 0xbfb8aa3b, v95
	v_rcp_f32_e32 v96, v88
	v_add_f32_e32 v88, 1.0, v89
	v_mul_f32_e32 v89, 0xbfb8aa3b, v90
	v_exp_f32_e32 v89, v89
	v_mul_f32_e32 v90, 0xbfb8aa3b, v91
	v_exp_f32_e32 v94, v94
	v_exp_f32_e32 v95, v95
	v_exp_f32_e32 v90, v90
	v_add_f32_e32 v92, 1.0, v92
	v_add_f32_e32 v93, 1.0, v93
	v_rcp_f32_e32 v92, v92
	v_rcp_f32_e32 v93, v93
	v_rcp_f32_e32 v91, v88
	v_add_f32_e32 v88, 1.0, v89
	v_add_f32_e32 v94, 1.0, v94
	v_add_f32_e32 v95, 1.0, v95
	v_rcp_f32_e32 v97, v88
	v_add_f32_e32 v88, 1.0, v90
	v_mul_f32_e32 v80, 0xbfb8aa3b, v80
	v_rcp_f32_e32 v94, v94
	v_rcp_f32_e32 v95, v95
	v_rcp_f32_e32 v98, v88
	v_exp_f32_e32 v80, v80
	v_mul_f32_e32 v81, 0xbfb8aa3b, v81
	v_exp_f32_e32 v81, v81
	v_cvt_pk_bf16_f32 v88, v92, v93
	v_mov_b32_e32 v92, v150
	v_cvt_pk_bf16_f32 v89, v94, v95
	v_ashrrev_i32_e32 v93, 31, v92
	v_cvt_pk_bf16_f32 v90, v96, v91
	v_cvt_pk_bf16_f32 v91, v97, v98
	v_lshl_add_u64 v[92:93], v[92:93], 4, s[4:5]
	v_mul_f32_e32 v84, 0xbfb8aa3b, v84
	v_mul_f32_e32 v85, 0xbfb8aa3b, v85
	v_add_f32_e32 v80, 1.0, v80
	v_exp_f32_e32 v84, v84
	v_exp_f32_e32 v85, v85
	global_store_dwordx4 v[92:93], v[88:91], off
	v_mul_f32_e32 v86, 0xbfb8aa3b, v86
	v_mul_f32_e32 v87, 0xbfb8aa3b, v87
	v_rcp_f32_e32 v88, v80
	v_add_f32_e32 v80, 1.0, v81
	v_mul_f32_e32 v81, 0xbfb8aa3b, v82
	v_exp_f32_e32 v81, v81
	v_mul_f32_e32 v82, 0xbfb8aa3b, v83
	v_exp_f32_e32 v86, v86
	v_exp_f32_e32 v87, v87
	v_exp_f32_e32 v82, v82
	v_add_f32_e32 v84, 1.0, v84
	v_add_f32_e32 v85, 1.0, v85
	v_rcp_f32_e32 v84, v84
	v_rcp_f32_e32 v85, v85
	v_rcp_f32_e32 v83, v80
	v_add_f32_e32 v80, 1.0, v81
	v_add_f32_e32 v86, 1.0, v86
	v_add_f32_e32 v87, 1.0, v87
	v_rcp_f32_e32 v89, v80
	v_add_f32_e32 v80, 1.0, v82
	v_mul_f32_e32 v72, 0xbfb8aa3b, v72
	v_rcp_f32_e32 v86, v86
	v_rcp_f32_e32 v87, v87
	v_rcp_f32_e32 v90, v80
	v_exp_f32_e32 v72, v72
	v_mul_f32_e32 v73, 0xbfb8aa3b, v73
	v_exp_f32_e32 v73, v73
	v_cvt_pk_bf16_f32 v80, v84, v85
	v_mov_b32_e32 v84, v151
	v_cvt_pk_bf16_f32 v81, v86, v87
	v_ashrrev_i32_e32 v85, 31, v84
	v_cvt_pk_bf16_f32 v82, v88, v83
	v_cvt_pk_bf16_f32 v83, v89, v90
	v_lshl_add_u64 v[84:85], v[84:85], 4, s[4:5]
	v_mul_f32_e32 v76, 0xbfb8aa3b, v76
	v_mul_f32_e32 v77, 0xbfb8aa3b, v77
	v_add_f32_e32 v72, 1.0, v72
	v_exp_f32_e32 v76, v76
	v_exp_f32_e32 v77, v77
	global_store_dwordx4 v[84:85], v[80:83], off
	v_mul_f32_e32 v78, 0xbfb8aa3b, v78
	v_mul_f32_e32 v79, 0xbfb8aa3b, v79
	v_rcp_f32_e32 v80, v72
	v_add_f32_e32 v72, 1.0, v73
	v_mul_f32_e32 v73, 0xbfb8aa3b, v74
	v_exp_f32_e32 v73, v73
	v_mul_f32_e32 v74, 0xbfb8aa3b, v75
	v_exp_f32_e32 v78, v78
	v_exp_f32_e32 v79, v79
	v_exp_f32_e32 v74, v74
	v_add_f32_e32 v76, 1.0, v76
	v_add_f32_e32 v77, 1.0, v77
	v_rcp_f32_e32 v76, v76
	v_rcp_f32_e32 v77, v77
	v_rcp_f32_e32 v75, v72
	v_add_f32_e32 v72, 1.0, v73
	v_add_f32_e32 v78, 1.0, v78
	v_add_f32_e32 v79, 1.0, v79
	v_rcp_f32_e32 v81, v72
	v_add_f32_e32 v72, 1.0, v74
	v_mul_f32_e32 v64, 0xbfb8aa3b, v64
	v_rcp_f32_e32 v78, v78
	v_rcp_f32_e32 v79, v79
	v_rcp_f32_e32 v82, v72
	v_exp_f32_e32 v64, v64
	v_mul_f32_e32 v65, 0xbfb8aa3b, v65
	v_exp_f32_e32 v65, v65
	v_cvt_pk_bf16_f32 v72, v76, v77
	v_mov_b32_e32 v76, v152
	v_cvt_pk_bf16_f32 v73, v78, v79
	v_ashrrev_i32_e32 v77, 31, v76
	v_cvt_pk_bf16_f32 v74, v80, v75
	v_cvt_pk_bf16_f32 v75, v81, v82
	v_lshl_add_u64 v[76:77], v[76:77], 4, s[4:5]
	v_mul_f32_e32 v68, 0xbfb8aa3b, v68
	v_mul_f32_e32 v69, 0xbfb8aa3b, v69
	v_add_f32_e32 v64, 1.0, v64
	v_exp_f32_e32 v68, v68
	v_exp_f32_e32 v69, v69
	global_store_dwordx4 v[76:77], v[72:75], off
	v_mul_f32_e32 v70, 0xbfb8aa3b, v70
	v_mul_f32_e32 v71, 0xbfb8aa3b, v71
	v_rcp_f32_e32 v72, v64
	v_add_f32_e32 v64, 1.0, v65
	v_mul_f32_e32 v65, 0xbfb8aa3b, v66
	v_exp_f32_e32 v65, v65
	v_mul_f32_e32 v66, 0xbfb8aa3b, v67
	v_exp_f32_e32 v70, v70
	v_exp_f32_e32 v71, v71
	v_exp_f32_e32 v66, v66
; __device__ __forceinline__ int launder_i(int x) { asm volatile("" : "+v"(x)); return x; }
; __device__ __forceinline__ float sigmoidf_(float x) { return __builtin_amdgcn_rcpf(1.f + __expf(-x)); }
; __device__ void phaseM1(const Params& p, char* lds) {
;     ...
; #pragma unroll
;                 for (int mi = 0; mi < 8; mi++)
; #pragma unroll
;                     for (int nh = 0; nh < 2; nh++) {
;                         const f32x4 a0 = acc[mi][2 * nh], a1 = acc[mi][2 * nh + 1];
;                         SG[(size_t)launder_i(pbase + (mi * 2 + nh) * 512)] = (u32x4){pack2(sigmoidf_(a0[0]), sigmoidf_(a0[1])), pack2(sigmoidf_(a0[2]), sigmoidf_(a0[3])),
;                                                                           pack2(sigmoidf_(a1[0]), sigmoidf_(a1[1])), pack2(sigmoidf_(a1[2]), sigmoidf_(a1[3]))};
;                     }
	v_add_f32_e32 v68, 1.0, v68
	v_add_f32_e32 v69, 1.0, v69
	v_rcp_f32_e32 v68, v68
	v_rcp_f32_e32 v69, v69
	v_rcp_f32_e32 v67, v64
	v_add_f32_e32 v64, 1.0, v65
	v_add_f32_e32 v70, 1.0, v70
	v_add_f32_e32 v71, 1.0, v71
	v_rcp_f32_e32 v73, v64
	v_add_f32_e32 v64, 1.0, v66
	v_mul_f32_e32 v56, 0xbfb8aa3b, v56
	v_rcp_f32_e32 v70, v70
	v_rcp_f32_e32 v71, v71
	v_rcp_f32_e32 v74, v64
	v_exp_f32_e32 v56, v56
	v_mul_f32_e32 v57, 0xbfb8aa3b, v57
	v_exp_f32_e32 v57, v57
	v_cvt_pk_bf16_f32 v64, v68, v69
	v_mov_b32_e32 v68, v153
	v_cvt_pk_bf16_f32 v65, v70, v71
	v_ashrrev_i32_e32 v69, 31, v68
	v_cvt_pk_bf16_f32 v66, v72, v67
	v_cvt_pk_bf16_f32 v67, v73, v74
	v_lshl_add_u64 v[68:69], v[68:69], 4, s[4:5]
	v_mul_f32_e32 v60, 0xbfb8aa3b, v60
	v_mul_f32_e32 v61, 0xbfb8aa3b, v61
	v_add_f32_e32 v56, 1.0, v56
	v_exp_f32_e32 v60, v60
	v_exp_f32_e32 v61, v61
	global_store_dwordx4 v[68:69], v[64:67], off
	v_mul_f32_e32 v62, 0xbfb8aa3b, v62
	v_mul_f32_e32 v63, 0xbfb8aa3b, v63
	v_rcp_f32_e32 v64, v56
	v_add_f32_e32 v56, 1.0, v57
	v_mul_f32_e32 v57, 0xbfb8aa3b, v58
	v_exp_f32_e32 v57, v57
	v_mul_f32_e32 v58, 0xbfb8aa3b, v59
	v_exp_f32_e32 v62, v62
	v_exp_f32_e32 v63, v63
	v_exp_f32_e32 v58, v58
	v_add_f32_e32 v60, 1.0, v60
	v_add_f32_e32 v61, 1.0, v61
	v_rcp_f32_e32 v60, v60
	v_rcp_f32_e32 v61, v61
	v_rcp_f32_e32 v59, v56
	v_add_f32_e32 v56, 1.0, v57
	v_add_f32_e32 v62, 1.0, v62
	v_add_f32_e32 v63, 1.0, v63
	v_rcp_f32_e32 v65, v56
	v_add_f32_e32 v56, 1.0, v58
	v_mul_f32_e32 v48, 0xbfb8aa3b, v48
	v_rcp_f32_e32 v62, v62
	v_rcp_f32_e32 v63, v63
	v_rcp_f32_e32 v66, v56
	v_exp_f32_e32 v48, v48
	v_mul_f32_e32 v49, 0xbfb8aa3b, v49
	v_exp_f32_e32 v49, v49
	v_cvt_pk_bf16_f32 v56, v60, v61
	v_mov_b32_e32 v60, v154
	v_cvt_pk_bf16_f32 v57, v62, v63
	v_ashrrev_i32_e32 v61, 31, v60
	v_cvt_pk_bf16_f32 v58, v64, v59
	v_cvt_pk_bf16_f32 v59, v65, v66
	v_lshl_add_u64 v[60:61], v[60:61], 4, s[4:5]
	v_mul_f32_e32 v52, 0xbfb8aa3b, v52
	v_mul_f32_e32 v53, 0xbfb8aa3b, v53
	v_add_f32_e32 v48, 1.0, v48
	v_exp_f32_e32 v52, v52
	v_exp_f32_e32 v53, v53
	global_store_dwordx4 v[60:61], v[56:59], off
	v_mul_f32_e32 v54, 0xbfb8aa3b, v54
	v_mul_f32_e32 v55, 0xbfb8aa3b, v55
	v_rcp_f32_e32 v56, v48
	v_add_f32_e32 v48, 1.0, v49
	v_mul_f32_e32 v49, 0xbfb8aa3b, v50
	v_exp_f32_e32 v49, v49
	v_mul_f32_e32 v50, 0xbfb8aa3b, v51
	v_exp_f32_e32 v54, v54
	v_exp_f32_e32 v55, v55
	v_exp_f32_e32 v50, v50
	v_add_f32_e32 v52, 1.0, v52
	v_add_f32_e32 v53, 1.0, v53
	v_rcp_f32_e32 v52, v52
	v_rcp_f32_e32 v53, v53
	v_rcp_f32_e32 v51, v48
	v_add_f32_e32 v48, 1.0, v49
	v_add_f32_e32 v54, 1.0, v54
	v_add_f32_e32 v55, 1.0, v55
	v_rcp_f32_e32 v57, v48
	v_add_f32_e32 v48, 1.0, v50
	v_mul_f32_e32 v40, 0xbfb8aa3b, v40
	v_rcp_f32_e32 v54, v54
	v_rcp_f32_e32 v55, v55
	v_rcp_f32_e32 v58, v48
	v_exp_f32_e32 v40, v40
	v_mul_f32_e32 v41, 0xbfb8aa3b, v41
	v_exp_f32_e32 v41, v41
	v_cvt_pk_bf16_f32 v48, v52, v53
	v_mov_b32_e32 v52, v155
	v_cvt_pk_bf16_f32 v49, v54, v55
	v_ashrrev_i32_e32 v53, 31, v52
	v_cvt_pk_bf16_f32 v50, v56, v51
	v_cvt_pk_bf16_f32 v51, v57, v58
	v_lshl_add_u64 v[52:53], v[52:53], 4, s[4:5]
	v_mul_f32_e32 v44, 0xbfb8aa3b, v44
	v_mul_f32_e32 v45, 0xbfb8aa3b, v45
	v_add_f32_e32 v40, 1.0, v40
	v_exp_f32_e32 v44, v44
	v_exp_f32_e32 v45, v45
	global_store_dwordx4 v[52:53], v[48:51], off
	v_mul_f32_e32 v46, 0xbfb8aa3b, v46
	v_mul_f32_e32 v47, 0xbfb8aa3b, v47
	v_rcp_f32_e32 v48, v40
	v_add_f32_e32 v40, 1.0, v41
	v_mul_f32_e32 v41, 0xbfb8aa3b, v42
	v_exp_f32_e32 v41, v41
	v_mul_f32_e32 v42, 0xbfb8aa3b, v43
	v_exp_f32_e32 v46, v46
	v_exp_f32_e32 v47, v47
	v_exp_f32_e32 v42, v42
	v_add_f32_e32 v44, 1.0, v44
	v_add_f32_e32 v45, 1.0, v45
	v_rcp_f32_e32 v44, v44
	v_rcp_f32_e32 v45, v45
	v_rcp_f32_e32 v43, v40
	v_add_f32_e32 v40, 1.0, v41
	v_add_f32_e32 v46, 1.0, v46
	v_add_f32_e32 v47, 1.0, v47
	v_rcp_f32_e32 v49, v40
	v_add_f32_e32 v40, 1.0, v42
	v_mul_f32_e32 v32, 0xbfb8aa3b, v32
	v_rcp_f32_e32 v46, v46
	v_rcp_f32_e32 v47, v47
	v_rcp_f32_e32 v50, v40
	v_exp_f32_e32 v32, v32
	v_mul_f32_e32 v33, 0xbfb8aa3b, v33
	v_exp_f32_e32 v33, v33
	v_cvt_pk_bf16_f32 v40, v44, v45
	v_mov_b32_e32 v44, v156
	v_cvt_pk_bf16_f32 v41, v46, v47
	v_ashrrev_i32_e32 v45, 31, v44
	v_cvt_pk_bf16_f32 v42, v48, v43
	v_cvt_pk_bf16_f32 v43, v49, v50
	v_lshl_add_u64 v[44:45], v[44:45], 4, s[4:5]
	v_mul_f32_e32 v36, 0xbfb8aa3b, v36
	v_mul_f32_e32 v37, 0xbfb8aa3b, v37
	v_add_f32_e32 v32, 1.0, v32
	v_exp_f32_e32 v36, v36
	v_exp_f32_e32 v37, v37
	global_store_dwordx4 v[44:45], v[40:43], off
	v_mul_f32_e32 v38, 0xbfb8aa3b, v38
	v_mul_f32_e32 v39, 0xbfb8aa3b, v39
	v_rcp_f32_e32 v40, v32
	v_add_f32_e32 v32, 1.0, v33
	v_mul_f32_e32 v33, 0xbfb8aa3b, v34
	v_exp_f32_e32 v33, v33
	v_mul_f32_e32 v34, 0xbfb8aa3b, v35
	v_exp_f32_e32 v38, v38
	v_exp_f32_e32 v39, v39
	v_exp_f32_e32 v34, v34
	v_add_f32_e32 v36, 1.0, v36
	v_add_f32_e32 v37, 1.0, v37
	v_rcp_f32_e32 v36, v36
	v_rcp_f32_e32 v37, v37
	v_rcp_f32_e32 v35, v32
	v_add_f32_e32 v32, 1.0, v33
	v_add_f32_e32 v38, 1.0, v38
	v_add_f32_e32 v39, 1.0, v39
	v_rcp_f32_e32 v41, v32
	v_add_f32_e32 v32, 1.0, v34
	v_mul_f32_e32 v24, 0xbfb8aa3b, v24
	v_rcp_f32_e32 v38, v38
	v_rcp_f32_e32 v39, v39
	v_rcp_f32_e32 v42, v32
	v_exp_f32_e32 v24, v24
	v_mul_f32_e32 v25, 0xbfb8aa3b, v25
	v_exp_f32_e32 v25, v25
	v_cvt_pk_bf16_f32 v32, v36, v37
	v_mov_b32_e32 v36, v157
	v_cvt_pk_bf16_f32 v33, v38, v39
	v_ashrrev_i32_e32 v37, 31, v36
	v_cvt_pk_bf16_f32 v34, v40, v35
	v_cvt_pk_bf16_f32 v35, v41, v42
	v_lshl_add_u64 v[36:37], v[36:37], 4, s[4:5]
	v_mul_f32_e32 v28, 0xbfb8aa3b, v28
	v_mul_f32_e32 v29, 0xbfb8aa3b, v29
	v_add_f32_e32 v24, 1.0, v24
	v_exp_f32_e32 v28, v28
	v_exp_f32_e32 v29, v29
	global_store_dwordx4 v[36:37], v[32:35], off
; __device__ __forceinline__ int launder_i(int x) { asm volatile("" : "+v"(x)); return x; }
; #define TIDX512 launder_i((int)threadIdx.x)
; __device__ __forceinline__ float sigmoidf_(float x) { return __builtin_amdgcn_rcpf(1.f + __expf(-x)); }
; __device__ __forceinline__ void gemm_mainloop(f32x4 (&acc)[8][4], const GemmSrc& g, int K, char* lds) {
;     const int tid = TIDX512, lane = tid & 63, wave = tid >> 6;
;     const int wr = wave >> 2, wc = wave & 3, r = lane & 15, q = lane >> 4;
;     const int KT = K / 64;
;     const int rdo0 = r * 128 + ((q ^ (r >> 1)) * 16), rdo1 = r * 128 + (((4 + q) ^ (r >> 1)) * 16);
;     const int woff = 32768 + wc * 64 * 128, xoff = wr * 128 * 128;
; __device__ void phaseM1(const Params& p, char* lds) {
;     ...
; #pragma unroll
;                 for (int mi = 0; mi < 8; mi++)
; #pragma unroll
;                     for (int nh = 0; nh < 2; nh++) {
;                         const f32x4 a0 = acc[mi][2 * nh], a1 = acc[mi][2 * nh + 1];
;                         SG[(size_t)launder_i(pbase + (mi * 2 + nh) * 512)] = (u32x4){pack2(sigmoidf_(a0[0]), sigmoidf_(a0[1])), pack2(sigmoidf_(a0[2]), sigmoidf_(a0[3])),
;                                                                           pack2(sigmoidf_(a1[0]), sigmoidf_(a1[1])), pack2(sigmoidf_(a1[2]), sigmoidf_(a1[3]))};
;                     }
;             }
;             zero_acc(acc);
;             gemm_mainloop(acc, g, DM, lds);
	v_mul_f32_e32 v30, 0xbfb8aa3b, v30
	v_mul_f32_e32 v31, 0xbfb8aa3b, v31
	v_rcp_f32_e32 v32, v24
	v_add_f32_e32 v24, 1.0, v25
	v_mul_f32_e32 v25, 0xbfb8aa3b, v26
	v_exp_f32_e32 v25, v25
	v_mul_f32_e32 v26, 0xbfb8aa3b, v27
	v_exp_f32_e32 v30, v30
	v_exp_f32_e32 v31, v31
	v_exp_f32_e32 v26, v26
	v_add_f32_e32 v28, 1.0, v28
	v_add_f32_e32 v29, 1.0, v29
	v_rcp_f32_e32 v28, v28
	v_rcp_f32_e32 v29, v29
	v_rcp_f32_e32 v27, v24
	v_add_f32_e32 v24, 1.0, v25
	v_add_f32_e32 v30, 1.0, v30
	v_add_f32_e32 v31, 1.0, v31
	v_rcp_f32_e32 v33, v24
	v_add_f32_e32 v24, 1.0, v26
	v_mul_f32_e32 v16, 0xbfb8aa3b, v16
	v_rcp_f32_e32 v30, v30
	v_rcp_f32_e32 v31, v31
	v_rcp_f32_e32 v34, v24
	v_exp_f32_e32 v16, v16
	v_mul_f32_e32 v17, 0xbfb8aa3b, v17
	v_exp_f32_e32 v17, v17
	v_cvt_pk_bf16_f32 v24, v28, v29
	v_mov_b32_e32 v28, v160
	v_cvt_pk_bf16_f32 v25, v30, v31
	v_ashrrev_i32_e32 v29, 31, v28
	v_cvt_pk_bf16_f32 v26, v32, v27
	v_cvt_pk_bf16_f32 v27, v33, v34
	v_lshl_add_u64 v[28:29], v[28:29], 4, s[4:5]
	v_mul_f32_e32 v20, 0xbfb8aa3b, v20
	v_mul_f32_e32 v21, 0xbfb8aa3b, v21
	v_add_f32_e32 v16, 1.0, v16
	v_exp_f32_e32 v20, v20
	v_exp_f32_e32 v21, v21
	global_store_dwordx4 v[28:29], v[24:27], off
	v_mul_f32_e32 v22, 0xbfb8aa3b, v22
	v_mul_f32_e32 v23, 0xbfb8aa3b, v23
	v_rcp_f32_e32 v24, v16
	v_add_f32_e32 v16, 1.0, v17
	v_mul_f32_e32 v17, 0xbfb8aa3b, v18
	v_exp_f32_e32 v17, v17
	v_mul_f32_e32 v18, 0xbfb8aa3b, v19
	v_exp_f32_e32 v22, v22
	v_exp_f32_e32 v23, v23
	v_exp_f32_e32 v18, v18
	v_add_f32_e32 v20, 1.0, v20
	v_add_f32_e32 v21, 1.0, v21
	v_rcp_f32_e32 v20, v20
	v_rcp_f32_e32 v21, v21
	v_rcp_f32_e32 v19, v16
	v_add_f32_e32 v16, 1.0, v17
	v_add_f32_e32 v22, 1.0, v22
	v_add_f32_e32 v23, 1.0, v23
	v_rcp_f32_e32 v25, v16
	v_add_f32_e32 v16, 1.0, v18
	v_mul_f32_e32 v8, 0xbfb8aa3b, v8
	v_rcp_f32_e32 v22, v22
	v_rcp_f32_e32 v23, v23
	v_rcp_f32_e32 v26, v16
	v_exp_f32_e32 v8, v8
	v_mul_f32_e32 v9, 0xbfb8aa3b, v9
	v_exp_f32_e32 v9, v9
	v_cvt_pk_bf16_f32 v16, v20, v21
	v_mov_b32_e32 v20, v161
	v_cvt_pk_bf16_f32 v17, v22, v23
	v_ashrrev_i32_e32 v21, 31, v20
	v_cvt_pk_bf16_f32 v18, v24, v19
	v_cvt_pk_bf16_f32 v19, v25, v26
	v_lshl_add_u64 v[20:21], v[20:21], 4, s[4:5]
	v_mul_f32_e32 v12, 0xbfb8aa3b, v12
	v_mul_f32_e32 v13, 0xbfb8aa3b, v13
	v_add_f32_e32 v8, 1.0, v8
	v_exp_f32_e32 v12, v12
	v_exp_f32_e32 v13, v13
	global_store_dwordx4 v[20:21], v[16:19], off
	v_mul_f32_e32 v14, 0xbfb8aa3b, v14
	v_mul_f32_e32 v15, 0xbfb8aa3b, v15
	v_rcp_f32_e32 v16, v8
	v_add_f32_e32 v8, 1.0, v9
	v_mul_f32_e32 v9, 0xbfb8aa3b, v10
	v_exp_f32_e32 v9, v9
	v_mul_f32_e32 v10, 0xbfb8aa3b, v11
	v_exp_f32_e32 v14, v14
	v_exp_f32_e32 v15, v15
	v_exp_f32_e32 v10, v10
	v_add_f32_e32 v12, 1.0, v12
	v_add_f32_e32 v13, 1.0, v13
	v_rcp_f32_e32 v12, v12
	v_rcp_f32_e32 v13, v13
	v_rcp_f32_e32 v11, v8
	v_add_f32_e32 v8, 1.0, v9
	v_add_f32_e32 v14, 1.0, v14
	v_add_f32_e32 v15, 1.0, v15
	v_rcp_f32_e32 v17, v8
	v_add_f32_e32 v8, 1.0, v10
	v_mul_f32_e32 v0, 0xbfb8aa3b, v0
	v_rcp_f32_e32 v14, v14
	v_rcp_f32_e32 v15, v15
	v_rcp_f32_e32 v18, v8
	v_exp_f32_e32 v0, v0
	v_mul_f32_e32 v1, 0xbfb8aa3b, v1
	v_exp_f32_e32 v1, v1
	v_cvt_pk_bf16_f32 v8, v12, v13
	v_mov_b32_e32 v12, v162
	v_cvt_pk_bf16_f32 v9, v14, v15
	v_ashrrev_i32_e32 v13, 31, v12
	v_cvt_pk_bf16_f32 v10, v16, v11
	v_cvt_pk_bf16_f32 v11, v17, v18
	v_lshl_add_u64 v[12:13], v[12:13], 4, s[4:5]
	v_mul_f32_e32 v4, 0xbfb8aa3b, v4
	v_mul_f32_e32 v5, 0xbfb8aa3b, v5
	v_add_f32_e32 v0, 1.0, v0
	v_exp_f32_e32 v4, v4
	v_exp_f32_e32 v5, v5
	global_store_dwordx4 v[12:13], v[8:11], off
	v_mul_f32_e32 v6, 0xbfb8aa3b, v6
	v_mul_f32_e32 v7, 0xbfb8aa3b, v7
	v_rcp_f32_e32 v8, v0
	v_add_f32_e32 v0, 1.0, v1
	v_mul_f32_e32 v1, 0xbfb8aa3b, v2
	v_exp_f32_e32 v1, v1
	v_mul_f32_e32 v2, 0xbfb8aa3b, v3
	v_exp_f32_e32 v6, v6
	v_exp_f32_e32 v7, v7
	v_exp_f32_e32 v2, v2
	v_add_f32_e32 v4, 1.0, v4
	v_add_f32_e32 v5, 1.0, v5
	v_rcp_f32_e32 v4, v4
	v_rcp_f32_e32 v5, v5
	v_rcp_f32_e32 v3, v0
	v_add_f32_e32 v0, 1.0, v1
	v_add_f32_e32 v6, 1.0, v6
	v_add_f32_e32 v7, 1.0, v7
	v_rcp_f32_e32 v9, v0
	v_add_f32_e32 v0, 1.0, v2
	v_rcp_f32_e32 v6, v6
	v_rcp_f32_e32 v7, v7
	v_rcp_f32_e32 v10, v0
	v_cvt_pk_bf16_f32 v0, v4, v5
	v_mov_b32_e32 v4, v163
	v_cvt_pk_bf16_f32 v1, v6, v7
	v_ashrrev_i32_e32 v5, 31, v4
	v_cvt_pk_bf16_f32 v2, v8, v3
	v_cvt_pk_bf16_f32 v3, v9, v10
	v_lshl_add_u64 v[4:5], v[4:5], 4, s[4:5]
	global_store_dwordx4 v[4:5], v[0:3], off
	s_mov_b32 s55, s31
	s_nop 0
	v_mov_b32_e32 v0, v158
	s_nop 0
	v_and_b32_e32 v1, 15, v0
	v_lshrrev_b32_e32 v2, 4, v0
	v_bfe_u32 v4, v0, 1, 3
	v_bfe_u32 v3, v0, 4, 2
	v_lshlrev_b32_e32 v1, 7, v1
	v_bitop3_b32 v2, v2, v4, 3 bitop3:0x6c
	v_lshl_or_b32 v164, v2, 4, v1
	v_bitop3_b32 v2, v3, v4, 4 bitop3:0x36
	v_lshl_or_b32 v135, v2, 4, v1
	v_lshlrev_b32_e32 v1, 7, v0
	v_lshlrev_b32_e32 v0, 6, v0
	v_and_b32_e32 v165, 0xffffc000, v0
	v_add3_u32 v0, s74, v115, v114
	v_add3_u32 v2, s48, v115, v114
	v_and_b32_e32 v166, 0x6000, v1
	v_mad_i64_i32 v[0:1], s[2:3], v0, s70, 0
	v_ashrrev_i32_e32 v3, 31, v2
	v_or_b32_e32 v0, v0, v128
	v_lshlrev_b64 v[2:3], 11, v[2:3]
	v_lshl_add_u64 v[0:1], v[0:1], 0, s[30:31]
	v_lshl_add_u64 v[2:3], s[54:55], 0, v[2:3]
	v_lshl_add_u64 v[136:137], s[6:7], 0, v[0:1]
	v_or_b32_e32 v2, v2, v128
	v_lshl_add_u64 v[0:1], v[0:1], 0, v[112:113]
	v_lshl_add_u64 v[140:141], s[6:7], 0, v[0:1]
	v_lshl_add_u64 v[0:1], v[2:3], 0, v[112:113]
	v_lshl_add_u64 v[142:143], s[6:7], 0, v[0:1]
	v_mov_b32_e32 v0, 0
	v_lshl_add_u64 v[138:139], s[6:7], 0, v[2:3]
	s_mov_b64 s[54:55], 0
	v_mov_b32_e32 v1, v0
	v_mov_b32_e32 v2, v0
	v_mov_b32_e32 v3, v0
	v_mov_b32_e32 v4, v0
	v_mov_b32_e32 v5, v0
	v_mov_b32_e32 v6, v0
	v_mov_b32_e32 v7, v0
	v_mov_b32_e32 v8, v0
; #define TIDX512 launder_i((int)threadIdx.x)
; __device__ __forceinline__ f32x4 mfma16(bf16x8 a, bf16x8 b, f32x4 c) { return __builtin_amdgcn_mfma_f32_16x16x32_bf16(a, b, c, 0, 0, 0); }
; #define WAIT_V(n) asm volatile("s_waitcnt vmcnt(" #n ")" ::: "memory")
; __device__ __forceinline__ void gemm_mainloop(f32x4 (&acc)[8][4], const GemmSrc& g, int K, char* lds) {
;     const int tid = TIDX512, lane = tid & 63, wave = tid >> 6;
;     const int wr = wave >> 2, wc = wave & 3, r = lane & 15, q = lane >> 4;
;     const int KT = K / 64;
;     const int rdo0 = r * 128 + ((q ^ (r >> 1)) * 16), rdo1 = r * 128 + (((4 + q) ^ (r >> 1)) * 16);
;     const int woff = 32768 + wc * 64 * 128, xoff = wr * 128 * 128;
;     for (int kt = 0; kt < KT; kt++) {
;         WAIT_V(0);
;         __builtin_amdgcn_s_barrier();
;         const char* st = lds + (kt & 1) * 65536;
;         bf16x8 afA[4], afB[4], bX[4], bY[4];
; #pragma unroll
;         for (int ni = 0; ni < 4; ni++) afA[ni] = *(const bf16x8*)(st + woff + ni * 16 * 128 + rdo0);
; #pragma unroll
;         for (int mi = 0; mi < 4; mi++) bX[mi] = *(const bf16x8*)(st + xoff + mi * 16 * 128 + rdo0);
;         if (kt + 1 < KT) gemm_issue(g, kt + 1, (kt + 1) & 1, lds);
; #pragma unroll
;         for (int mi = 0; mi < 4; mi++) bY[mi] = *(const bf16x8*)(st + xoff + (4 + mi) * 16 * 128 + rdo0);
; #pragma unroll
;         for (int ni = 0; ni < 4; ni++) afB[ni] = *(const bf16x8*)(st + woff + ni * 16 * 128 + rdo1);
; #pragma unroll
;         for (int mi = 0; mi < 4; mi++)
; #pragma unroll
;             for (int ni = 0; ni < 4; ni++) acc[mi][ni] = mfma16(afA[ni], bX[mi], acc[mi][ni]);
; __device__ void phaseM1(const Params& p, char* lds) {
;     ...
;             zero_acc(acc);
;             gemm_mainloop(acc, g, DM, lds);
	v_mov_b32_e32 v9, v0
	v_mov_b32_e32 v10, v0
	v_mov_b32_e32 v11, v0
	v_mov_b32_e32 v12, v0
	v_mov_b32_e32 v13, v0
	v_mov_b32_e32 v14, v0
	v_mov_b32_e32 v15, v0
	v_mov_b32_e32 v16, v0
	v_mov_b32_e32 v17, v0
	v_mov_b32_e32 v18, v0
	v_mov_b32_e32 v19, v0
	v_mov_b32_e32 v20, v0
	v_mov_b32_e32 v21, v0
	v_mov_b32_e32 v22, v0
	v_mov_b32_e32 v23, v0
	v_mov_b32_e32 v24, v0
	v_mov_b32_e32 v25, v0
	v_mov_b32_e32 v26, v0
	v_mov_b32_e32 v27, v0
	v_mov_b32_e32 v28, v0
	v_mov_b32_e32 v29, v0
	v_mov_b32_e32 v30, v0
	v_mov_b32_e32 v31, v0
	v_mov_b32_e32 v32, v0
	v_mov_b32_e32 v33, v0
	v_mov_b32_e32 v34, v0
	v_mov_b32_e32 v35, v0
	v_mov_b32_e32 v36, v0
	v_mov_b32_e32 v37, v0
	v_mov_b32_e32 v38, v0
	v_mov_b32_e32 v39, v0
	v_mov_b32_e32 v40, v0
	v_mov_b32_e32 v41, v0
	v_mov_b32_e32 v42, v0
	v_mov_b32_e32 v43, v0
	v_mov_b32_e32 v44, v0
	v_mov_b32_e32 v45, v0
	v_mov_b32_e32 v46, v0
	v_mov_b32_e32 v47, v0
	v_mov_b32_e32 v48, v0
	v_mov_b32_e32 v49, v0
	v_mov_b32_e32 v50, v0
	v_mov_b32_e32 v51, v0
	v_mov_b32_e32 v52, v0
	v_mov_b32_e32 v53, v0
	v_mov_b32_e32 v54, v0
	v_mov_b32_e32 v55, v0
	v_mov_b32_e32 v56, v0
	v_mov_b32_e32 v57, v0
	v_mov_b32_e32 v58, v0
	v_mov_b32_e32 v59, v0
	v_mov_b32_e32 v60, v0
	v_mov_b32_e32 v61, v0
	v_mov_b32_e32 v62, v0
	v_mov_b32_e32 v63, v0
	v_mov_b32_e32 v64, v0
	v_mov_b32_e32 v65, v0
	v_mov_b32_e32 v66, v0
	v_mov_b32_e32 v67, v0
	v_mov_b32_e32 v68, v0
	v_mov_b32_e32 v69, v0
	v_mov_b32_e32 v70, v0
	v_mov_b32_e32 v71, v0
	v_mov_b32_e32 v72, v0
	v_mov_b32_e32 v73, v0
	v_mov_b32_e32 v74, v0
	v_mov_b32_e32 v75, v0
	v_mov_b32_e32 v76, v0
	v_mov_b32_e32 v77, v0
	v_mov_b32_e32 v78, v0
	v_mov_b32_e32 v79, v0
	v_mov_b32_e32 v80, v0
	v_mov_b32_e32 v81, v0
	v_mov_b32_e32 v82, v0
	v_mov_b32_e32 v83, v0
	v_mov_b32_e32 v84, v0
	v_mov_b32_e32 v85, v0
	v_mov_b32_e32 v86, v0
	v_mov_b32_e32 v87, v0
	v_mov_b32_e32 v88, v0
	v_mov_b32_e32 v89, v0
	v_mov_b32_e32 v90, v0
	v_mov_b32_e32 v91, v0
	v_mov_b32_e32 v92, v0
	v_mov_b32_e32 v93, v0
	v_mov_b32_e32 v94, v0
	v_mov_b32_e32 v95, v0
	v_mov_b32_e32 v96, v0
	v_mov_b32_e32 v97, v0
	v_mov_b32_e32 v98, v0
	v_mov_b32_e32 v99, v0
	v_mov_b32_e32 v100, v0
	v_mov_b32_e32 v101, v0
	v_mov_b32_e32 v102, v0
	v_mov_b32_e32 v103, v0
	v_mov_b32_e32 v104, v0
	v_mov_b32_e32 v105, v0
	v_mov_b32_e32 v106, v0
	v_mov_b32_e32 v107, v0
	v_mov_b32_e32 v108, v0
	v_mov_b32_e32 v109, v0
	v_mov_b32_e32 v110, v0
	v_mov_b32_e32 v111, v0
	v_mov_b32_e32 v112, v0
	v_mov_b32_e32 v113, v0
	v_mov_b32_e32 v114, v0
	v_mov_b32_e32 v115, v0
	v_mov_b32_e32 v116, v0
	v_mov_b32_e32 v117, v0
	v_mov_b32_e32 v118, v0
	v_mov_b32_e32 v119, v0
	v_mov_b32_e32 v120, v0
	v_mov_b32_e32 v121, v0
	v_mov_b32_e32 v122, v0
	v_mov_b32_e32 v123, v0
	v_mov_b32_e32 v124, v0
	v_mov_b32_e32 v125, v0
	v_mov_b32_e32 v126, v0
	v_mov_b32_e32 v127, v0
.LBB0_716:
	s_add_i32 s1, s0, 0xffff0000
	s_and_b32 s1, s1, 0x10000
	v_or_b32_e32 v128, s1, v166
	v_add_u32_e32 v167, v128, v164
	s_waitcnt vmcnt(0)
	s_barrier
	ds_read_b128 v[168:171], v167 offset:32768
	ds_read_b128 v[172:175], v167 offset:34816
	ds_read_b128 v[176:179], v167 offset:36864
	ds_read_b128 v[180:183], v167 offset:38912
	v_add_u32_e32 v167, s1, v165
	v_add_u32_e32 v208, v167, v164
	v_mov_b32_e32 v200, v158
	ds_read_b128 v[184:187], v208
	ds_read_b128 v[188:191], v208 offset:2048
	ds_read_b128 v[192:195], v208 offset:4096
	ds_read_b128 v[196:199], v208 offset:6144
	s_and_b32 s1, s0, 0x10000
	v_lshlrev_b32_e32 v201, 6, v200
	v_and_b32_e32 v201, 0xfffff000, v201
	v_add_u32_e32 v201, s1, v201
	v_lshlrev_b32_e32 v200, 4, v200
	v_and_or_b32 v209, v200, s64, v201
	v_lshl_add_u64 v[200:201], v[136:137], 0, s[54:55]
	v_readfirstlane_b32 s1, v209
	v_add_u32_e32 v206, 0x8000, v209
	v_lshl_add_u64 v[202:203], v[200:201], 0, s[40:41]
	s_mov_b32 m0, s1
	v_readfirstlane_b32 s1, v206
	s_cmp_lg_u32 s33, 0
	s_cbranch_scc1 .Ldma_skip_40
	global_load_lds_dwordx4 v[202:203], off
	s_add_u32 m0, m0, 0x4000
	v_lshl_add_u64 v[220:221], v[202:203], 0, s[98:99]
	global_load_lds_dwordx4 v[220:221], off
.Ldma_skip_40:
	v_lshl_add_u64 v[202:203], v[138:139], 0, s[54:55]
	v_lshl_add_u64 v[204:205], v[202:203], 0, s[22:23]
	s_mov_b32 m0, s1
	v_or_b32_e32 v210, 0x400, v209
	s_cmp_lg_u32 s33, 0
	s_cbranch_scc1 .Ldma_skip_41
	global_load_lds_dwordx4 v[204:205], off
	s_add_u32 m0, m0, 0x4000
	v_lshl_add_u64 v[220:221], v[204:205], 0, s[100:101]
	global_load_lds_dwordx4 v[220:221], off
.Ldma_skip_41:
	v_lshl_add_u64 v[204:205], v[140:141], 0, s[54:55]
	v_readfirstlane_b32 s1, v210
	s_waitcnt lgkmcnt(0)
	v_mfma_f32_16x16x32_bf16 v[124:127], v[168:171], v[184:187], v[124:127]
	v_lshl_add_u64 v[206:207], v[204:205], 0, s[42:43]
	s_mov_b32 m0, s1
	v_add_u32_e32 v128, v128, v135
	v_mfma_f32_16x16x32_bf16 v[120:123], v[172:175], v[184:187], v[120:123]
	s_cmp_lg_u32 s33, 0
	s_cbranch_scc1 .Ldma_skip_42
	global_load_lds_dwordx4 v[206:207], off
	s_add_u32 m0, m0, 0x4000
	v_lshl_add_u64 v[220:221], v[206:207], 0, s[98:99]
	global_load_lds_dwordx4 v[220:221], off
.Ldma_skip_42:
	v_lshl_add_u64 v[206:207], v[142:143], 0, s[54:55]
	v_mfma_f32_16x16x32_bf16 v[116:119], v[176:179], v[184:187], v[116:119]
	v_mfma_f32_16x16x32_bf16 v[112:115], v[180:183], v[184:187], v[112:115]
	v_add_u32_e32 v186, 0x8400, v209
	v_lshl_add_u64 v[184:185], v[206:207], 0, s[24:25]
	v_readfirstlane_b32 s1, v186
	v_or_b32_e32 v186, 0x800, v209
	s_mov_b32 m0, s1
	v_readfirstlane_b32 s1, v186
	v_add_u32_e32 v186, 0x8800, v209
	s_cmp_lg_u32 s33, 0
	s_cbranch_scc1 .Ldma_skip_43
	global_load_lds_dwordx4 v[184:185], off
	s_add_u32 m0, m0, 0x4000
	v_lshl_add_u64 v[220:221], v[184:185], 0, s[100:101]
	global_load_lds_dwordx4 v[220:221], off
; #define TIDX512 launder_i((int)threadIdx.x)
; __device__ __forceinline__ void gemm_issue(const GemmSrc& g, int kt, int s, char* lds) {
;     const int tid = TIDX512, lane = tid & 63, wave = tid >> 6;
;     char* xdst = lds + s * 65536 + wave * 4096 + lane * 16;
;     char* wdst = xdst + 32768;
; #pragma unroll
;     for (int i = 0; i < 4; i++) {
;         const int d = (i & 1) ? g.dsw : 0;
; __device__ __forceinline__ void gemm_mainloop(f32x4 (&acc)[8][4], const GemmSrc& g, int K, char* lds) {
;     ...
;     for (int kt = 0; kt < KT; kt++) {
;         WAIT_V(0);
;         __builtin_amdgcn_s_barrier();
;         const char* st = lds + (kt & 1) * 65536;
;         bf16x8 afA[4], afB[4], bX[4], bY[4];
; #pragma unroll
;         for (int ni = 0; ni < 4; ni++) afA[ni] = *(const bf16x8*)(st + woff + ni * 16 * 128 + rdo0);
; #pragma unroll
;         for (int mi = 0; mi < 4; mi++) bX[mi] = *(const bf16x8*)(st + xoff + mi * 16 * 128 + rdo0);
;         if (kt + 1 < KT) gemm_issue(g, kt + 1, (kt + 1) & 1, lds);
; #pragma unroll
;         for (int mi = 0; mi < 4; mi++) bY[mi] = *(const bf16x8*)(st + xoff + (4 + mi) * 16 * 128 + rdo0);
; #pragma unroll
;         for (int ni = 0; ni < 4; ni++) afB[ni] = *(const bf16x8*)(st + woff + ni * 16 * 128 + rdo1);
; #pragma unroll
;         for (int mi = 0; mi < 4; mi++)
; #pragma unroll
;             for (int ni = 0; ni < 4; ni++) acc[mi][ni] = mfma16(afA[ni], bX[mi], acc[mi][ni]);
;         __builtin_amdgcn_sched_barrier(0);
; #pragma unroll
;         for (int mi = 0; mi < 4; mi++) bX[mi] = *(const bf16x8*)(st + xoff + mi * 16 * 128 + rdo1);
; #pragma unroll
;         for (int mi = 0; mi < 4; mi++)
; #pragma unroll
;             for (int ni = 0; ni < 4; ni++) acc[4 + mi][ni] = mfma16(afA[ni], bY[mi], acc[4 + mi][ni]);
;         __builtin_amdgcn_sched_barrier(0);
; #pragma unroll
;         for (int mi = 0; mi < 4; mi++) bY[mi] = *(const bf16x8*)(st + xoff + (4 + mi) * 16 * 128 + rdo1);
; #pragma unroll
;         for (int mi = 0; mi < 4; mi++)
; #pragma unroll
;             for (int ni = 0; ni < 4; ni++) acc[mi][ni] = mfma16(afB[ni], bX[mi], acc[mi][ni]);
;         __builtin_amdgcn_sched_barrier(0);
; #pragma unroll
;         for (int mi = 0; mi < 4; mi++)
; #pragma unroll
;             for (int ni = 0; ni < 4; ni++) acc[4 + mi][ni] = mfma16(afB[ni], bY[mi], acc[4 + mi][ni]);
;         __builtin_amdgcn_sched_barrier(0);
;     }
.Ldma_skip_43:
	v_lshl_add_u64 v[184:185], v[200:201], 0, s[44:45]
	s_mov_b32 m0, s1
	v_readfirstlane_b32 s1, v186
	v_or_b32_e32 v186, 0xc00, v209
	s_cmp_lg_u32 s33, 0
	s_cbranch_scc1 .Ldma_skip_44
	global_load_lds_dwordx4 v[184:185], off
	s_add_u32 m0, m0, 0x4000
	v_lshl_add_u64 v[220:221], v[184:185], 0, s[98:99]
	global_load_lds_dwordx4 v[220:221], off
.Ldma_skip_44:
	v_lshl_add_u64 v[184:185], v[202:203], 0, s[26:27]
	s_mov_b32 m0, s1
	v_readfirstlane_b32 s1, v186
	v_add_u32_e32 v186, 0x8c00, v209
	s_cmp_lg_u32 s33, 0
	s_cbranch_scc1 .Ldma_skip_45
	global_load_lds_dwordx4 v[184:185], off
	s_add_u32 m0, m0, 0x4000
	v_lshl_add_u64 v[220:221], v[184:185], 0, s[100:101]
	global_load_lds_dwordx4 v[220:221], off
.Ldma_skip_45:
	v_lshl_add_u64 v[184:185], v[204:205], 0, s[46:47]
	s_mov_b32 m0, s1
	v_readfirstlane_b32 s1, v186
	s_cmp_lg_u32 s33, 0
	s_cbranch_scc1 .Ldma_skip_46
	global_load_lds_dwordx4 v[184:185], off
	s_add_u32 m0, m0, 0x4000
	v_lshl_add_u64 v[220:221], v[184:185], 0, s[98:99]
	global_load_lds_dwordx4 v[220:221], off
.Ldma_skip_46:
	v_lshl_add_u64 v[184:185], v[206:207], 0, s[28:29]
	s_mov_b32 m0, s1
	v_mfma_f32_16x16x32_bf16 v[108:111], v[168:171], v[188:191], v[108:111]
	s_cmp_lg_u32 s33, 0
	s_cbranch_scc1 .Ldma_skip_47
	global_load_lds_dwordx4 v[184:185], off
	s_add_u32 m0, m0, 0x4000
	v_lshl_add_u64 v[220:221], v[184:185], 0, s[100:101]
	global_load_lds_dwordx4 v[220:221], off
.Ldma_skip_47:
	v_mfma_f32_16x16x32_bf16 v[104:107], v[172:175], v[188:191], v[104:107]
	v_mfma_f32_16x16x32_bf16 v[100:103], v[176:179], v[188:191], v[100:103]
	v_mfma_f32_16x16x32_bf16 v[96:99], v[180:183], v[188:191], v[96:99]
	ds_read_b128 v[184:187], v208 offset:8192
	ds_read_b128 v[188:191], v208 offset:10240
	v_mfma_f32_16x16x32_bf16 v[92:95], v[168:171], v[192:195], v[92:95]
	v_mfma_f32_16x16x32_bf16 v[88:91], v[172:175], v[192:195], v[88:91]
	v_mfma_f32_16x16x32_bf16 v[84:87], v[176:179], v[192:195], v[84:87]
	v_mfma_f32_16x16x32_bf16 v[80:83], v[180:183], v[192:195], v[80:83]
	ds_read_b128 v[192:195], v208 offset:12288
	ds_read_b128 v[200:203], v208 offset:14336
	ds_read_b128 v[204:207], v128 offset:32768
	ds_read_b128 v[208:211], v128 offset:34816
	ds_read_b128 v[212:215], v128 offset:36864
	ds_read_b128 v[216:219], v128 offset:38912
	v_mfma_f32_16x16x32_bf16 v[76:79], v[168:171], v[196:199], v[76:79]
	v_mfma_f32_16x16x32_bf16 v[72:75], v[172:175], v[196:199], v[72:75]
	v_mfma_f32_16x16x32_bf16 v[68:71], v[176:179], v[196:199], v[68:71]
	v_mfma_f32_16x16x32_bf16 v[64:67], v[180:183], v[196:199], v[64:67]
	v_add_u32_e32 v128, v167, v135
	s_waitcnt lgkmcnt(0)
	v_mfma_f32_16x16x32_bf16 v[60:63], v[168:171], v[184:187], v[60:63]
	v_mfma_f32_16x16x32_bf16 v[56:59], v[172:175], v[184:187], v[56:59]
	v_mfma_f32_16x16x32_bf16 v[52:55], v[176:179], v[184:187], v[52:55]
	v_mfma_f32_16x16x32_bf16 v[48:51], v[180:183], v[184:187], v[48:51]
	v_mfma_f32_16x16x32_bf16 v[44:47], v[168:171], v[188:191], v[44:47]
	v_mfma_f32_16x16x32_bf16 v[40:43], v[172:175], v[188:191], v[40:43]
	v_mfma_f32_16x16x32_bf16 v[36:39], v[176:179], v[188:191], v[36:39]
	v_mfma_f32_16x16x32_bf16 v[28:31], v[168:171], v[192:195], v[28:31]
	v_mfma_f32_16x16x32_bf16 v[24:27], v[172:175], v[192:195], v[24:27]
	v_mfma_f32_16x16x32_bf16 v[20:23], v[176:179], v[192:195], v[20:23]
	v_mfma_f32_16x16x32_bf16 v[12:15], v[168:171], v[200:203], v[12:15]
	v_mfma_f32_16x16x32_bf16 v[8:11], v[172:175], v[200:203], v[8:11]
	v_mfma_f32_16x16x32_bf16 v[4:7], v[176:179], v[200:203], v[4:7]
	ds_read_b128 v[168:171], v128
	ds_read_b128 v[172:175], v128 offset:2048
	ds_read_b128 v[176:179], v128 offset:4096
	ds_read_b128 v[184:187], v128 offset:6144
	v_mfma_f32_16x16x32_bf16 v[32:35], v[180:183], v[188:191], v[32:35]
	v_mfma_f32_16x16x32_bf16 v[16:19], v[180:183], v[192:195], v[16:19]
	v_mfma_f32_16x16x32_bf16 v[0:3], v[180:183], v[200:203], v[0:3]
	s_waitcnt lgkmcnt(0)
	v_mfma_f32_16x16x32_bf16 v[124:127], v[204:207], v[168:171], v[124:127]
	v_mfma_f32_16x16x32_bf16 v[120:123], v[208:211], v[168:171], v[120:123]
	v_mfma_f32_16x16x32_bf16 v[116:119], v[212:215], v[168:171], v[116:119]
	v_mfma_f32_16x16x32_bf16 v[112:115], v[216:219], v[168:171], v[112:115]
	v_mfma_f32_16x16x32_bf16 v[108:111], v[204:207], v[172:175], v[108:111]
	v_mfma_f32_16x16x32_bf16 v[104:107], v[208:211], v[172:175], v[104:107]
	v_mfma_f32_16x16x32_bf16 v[100:103], v[212:215], v[172:175], v[100:103]
	v_mfma_f32_16x16x32_bf16 v[96:99], v[216:219], v[172:175], v[96:99]
	v_mfma_f32_16x16x32_bf16 v[92:95], v[204:207], v[176:179], v[92:95]
	v_mfma_f32_16x16x32_bf16 v[88:91], v[208:211], v[176:179], v[88:91]
	v_mfma_f32_16x16x32_bf16 v[84:87], v[212:215], v[176:179], v[84:87]
	v_mfma_f32_16x16x32_bf16 v[80:83], v[216:219], v[176:179], v[80:83]
	ds_read_b128 v[168:171], v128 offset:8192
	ds_read_b128 v[172:175], v128 offset:10240
	ds_read_b128 v[176:179], v128 offset:12288
	ds_read_b128 v[180:183], v128 offset:14336
	v_mfma_f32_16x16x32_bf16 v[76:79], v[204:207], v[184:187], v[76:79]
	v_mfma_f32_16x16x32_bf16 v[72:75], v[208:211], v[184:187], v[72:75]
	v_mfma_f32_16x16x32_bf16 v[68:71], v[212:215], v[184:187], v[68:71]
	v_mfma_f32_16x16x32_bf16 v[64:67], v[216:219], v[184:187], v[64:67]
	s_waitcnt lgkmcnt(0)
	v_mfma_f32_16x16x32_bf16 v[60:63], v[204:207], v[168:171], v[60:63]
	v_mfma_f32_16x16x32_bf16 v[56:59], v[208:211], v[168:171], v[56:59]
	v_mfma_f32_16x16x32_bf16 v[52:55], v[212:215], v[168:171], v[52:55]
	v_mfma_f32_16x16x32_bf16 v[48:51], v[216:219], v[168:171], v[48:51]
	v_mfma_f32_16x16x32_bf16 v[44:47], v[204:207], v[172:175], v[44:47]
	v_mfma_f32_16x16x32_bf16 v[40:43], v[208:211], v[172:175], v[40:43]
	v_mfma_f32_16x16x32_bf16 v[36:39], v[212:215], v[172:175], v[36:39]
	v_mfma_f32_16x16x32_bf16 v[32:35], v[216:219], v[172:175], v[32:35]
	v_mfma_f32_16x16x32_bf16 v[28:31], v[204:207], v[176:179], v[28:31]
	v_mfma_f32_16x16x32_bf16 v[24:27], v[208:211], v[176:179], v[24:27]
	v_mfma_f32_16x16x32_bf16 v[20:23], v[212:215], v[176:179], v[20:23]
	v_mfma_f32_16x16x32_bf16 v[16:19], v[216:219], v[176:179], v[16:19]
	v_mfma_f32_16x16x32_bf16 v[12:15], v[204:207], v[180:183], v[12:15]
	v_mfma_f32_16x16x32_bf16 v[8:11], v[208:211], v[180:183], v[8:11]
	v_mfma_f32_16x16x32_bf16 v[4:7], v[212:215], v[180:183], v[4:7]
	v_mfma_f32_16x16x32_bf16 v[0:3], v[216:219], v[180:183], v[0:3]
	s_add_u32 s54, s54, 0x80
	s_addc_u32 s55, s55, 0
	s_add_i32 s0, s0, 0x10000
	s_cmpk_lg_i32 s54, 0x780
	s_cbranch_scc1 .LBB0_716
; __device__ __forceinline__ f32x4 mfma16(bf16x8 a, bf16x8 b, f32x4 c) { return __builtin_amdgcn_mfma_f32_16x16x32_bf16(a, b, c, 0, 0, 0); }
; __device__ __forceinline__ void gemm_mainloop(f32x4 (&acc)[8][4], const GemmSrc& g, int K, char* lds) {
;     ...
;     for (int kt = 0; kt < KT; kt++) {
;         WAIT_V(0);
;         __builtin_amdgcn_s_barrier();
;         const char* st = lds + (kt & 1) * 65536;
;         bf16x8 afA[4], afB[4], bX[4], bY[4];
; #pragma unroll
;         for (int ni = 0; ni < 4; ni++) afA[ni] = *(const bf16x8*)(st + woff + ni * 16 * 128 + rdo0);
; #pragma unroll
;         for (int mi = 0; mi < 4; mi++) bX[mi] = *(const bf16x8*)(st + xoff + mi * 16 * 128 + rdo0);
;         if (kt + 1 < KT) gemm_issue(g, kt + 1, (kt + 1) & 1, lds);
; #pragma unroll
;         for (int mi = 0; mi < 4; mi++) bY[mi] = *(const bf16x8*)(st + xoff + (4 + mi) * 16 * 128 + rdo0);
; #pragma unroll
;         for (int ni = 0; ni < 4; ni++) afB[ni] = *(const bf16x8*)(st + woff + ni * 16 * 128 + rdo1);
; #pragma unroll
;         for (int mi = 0; mi < 4; mi++)
; #pragma unroll
;             for (int ni = 0; ni < 4; ni++) acc[mi][ni] = mfma16(afA[ni], bX[mi], acc[mi][ni]);
;         __builtin_amdgcn_sched_barrier(0);
; #pragma unroll
;         for (int mi = 0; mi < 4; mi++) bX[mi] = *(const bf16x8*)(st + xoff + mi * 16 * 128 + rdo1);
; #pragma unroll
;         for (int mi = 0; mi < 4; mi++)
; #pragma unroll
;             for (int ni = 0; ni < 4; ni++) acc[4 + mi][ni] = mfma16(afA[ni], bY[mi], acc[4 + mi][ni]);
;         __builtin_amdgcn_sched_barrier(0);
; #pragma unroll
;         for (int mi = 0; mi < 4; mi++) bY[mi] = *(const bf16x8*)(st + xoff + (4 + mi) * 16 * 128 + rdo1);
; #pragma unroll
;         for (int mi = 0; mi < 4; mi++)
; #pragma unroll
;             for (int ni = 0; ni < 4; ni++) acc[mi][ni] = mfma16(afB[ni], bX[mi], acc[mi][ni]);
;         __builtin_amdgcn_sched_barrier(0);
; #pragma unroll
;         for (int mi = 0; mi < 4; mi++)
; #pragma unroll
;             for (int ni = 0; ni < 4; ni++) acc[4 + mi][ni] = mfma16(afB[ni], bY[mi], acc[4 + mi][ni]);
;         __builtin_amdgcn_sched_barrier(0);
;     }
; __device__ void phaseM1(const Params& p, char* lds) {
;     ...
;             __syncthreads();
;             if (br == 0) {
;                 g = gemm_src(H, DM, (const bf16_t*)(p.ws + OFF_WM) + (size_t)1024 * 1024, DM, m0, n0);
;                 gemm_prologue(g, lds);
	v_or_b32_e32 v128, 0x8000, v166
	v_add_u32_e32 v208, 0x10000, v165
	v_add3_u32 v176, v128, v164, s68
	v_add_u32_e32 v204, v208, v164
	s_waitcnt vmcnt(0)
	s_barrier
	ds_read_b128 v[136:139], v176
	ds_read_b128 v[140:143], v176 offset:2048
	ds_read_b128 v[164:167], v204
	ds_read_b128 v[168:171], v204 offset:2048
	ds_read_b128 v[172:175], v176 offset:4096
	ds_read_b128 v[176:179], v176 offset:6144
	s_waitcnt lgkmcnt(0)
	v_mfma_f32_16x16x32_bf16 v[124:127], v[136:139], v[164:167], v[124:127]
	v_add3_u32 v128, v128, v135, s68
	v_mfma_f32_16x16x32_bf16 v[120:123], v[140:143], v[164:167], v[120:123]
	v_mfma_f32_16x16x32_bf16 v[116:119], v[172:175], v[164:167], v[116:119]
	v_mfma_f32_16x16x32_bf16 v[112:115], v[176:179], v[164:167], v[112:115]
	v_mfma_f32_16x16x32_bf16 v[108:111], v[136:139], v[168:171], v[108:111]
	v_mfma_f32_16x16x32_bf16 v[104:107], v[140:143], v[168:171], v[104:107]
	v_mfma_f32_16x16x32_bf16 v[100:103], v[172:175], v[168:171], v[100:103]
	v_mfma_f32_16x16x32_bf16 v[96:99], v[176:179], v[168:171], v[96:99]
	ds_read_b128 v[164:167], v204 offset:4096
	ds_read_b128 v[168:171], v204 offset:6144
	s_waitcnt lgkmcnt(0)
	v_mfma_f32_16x16x32_bf16 v[92:95], v[136:139], v[164:167], v[92:95]
	v_mfma_f32_16x16x32_bf16 v[88:91], v[140:143], v[164:167], v[88:91]
	v_mfma_f32_16x16x32_bf16 v[84:87], v[172:175], v[164:167], v[84:87]
	v_mfma_f32_16x16x32_bf16 v[80:83], v[176:179], v[164:167], v[80:83]
	ds_read_b128 v[164:167], v128 offset:6144
	ds_read_b128 v[180:183], v128 offset:4096
	ds_read_b128 v[184:187], v128 offset:2048
	ds_read_b128 v[188:191], v128
	ds_read_b128 v[192:195], v204 offset:14336
	ds_read_b128 v[196:199], v204 offset:12288
	ds_read_b128 v[200:203], v204 offset:10240
	ds_read_b128 v[204:207], v204 offset:8192
	v_mfma_f32_16x16x32_bf16 v[76:79], v[136:139], v[168:171], v[76:79]
	v_mfma_f32_16x16x32_bf16 v[72:75], v[140:143], v[168:171], v[72:75]
	v_mfma_f32_16x16x32_bf16 v[68:71], v[172:175], v[168:171], v[68:71]
	v_mfma_f32_16x16x32_bf16 v[168:171], v[176:179], v[168:171], v[64:67]
	v_add_u32_e32 v128, v208, v135
	s_waitcnt lgkmcnt(0)
	v_mfma_f32_16x16x32_bf16 v[60:63], v[136:139], v[204:207], v[60:63]
	v_mfma_f32_16x16x32_bf16 v[56:59], v[140:143], v[204:207], v[56:59]
	v_mfma_f32_16x16x32_bf16 v[52:55], v[172:175], v[204:207], v[52:55]
	v_mfma_f32_16x16x32_bf16 v[44:47], v[136:139], v[200:203], v[44:47]
	v_mfma_f32_16x16x32_bf16 v[40:43], v[140:143], v[200:203], v[40:43]
	v_mfma_f32_16x16x32_bf16 v[36:39], v[172:175], v[200:203], v[36:39]
	v_mfma_f32_16x16x32_bf16 v[28:31], v[136:139], v[196:199], v[28:31]
	v_mfma_f32_16x16x32_bf16 v[24:27], v[140:143], v[196:199], v[24:27]
	v_mfma_f32_16x16x32_bf16 v[20:23], v[172:175], v[196:199], v[20:23]
	v_mfma_f32_16x16x32_bf16 v[12:15], v[136:139], v[192:195], v[12:15]
	v_mfma_f32_16x16x32_bf16 v[8:11], v[140:143], v[192:195], v[8:11]
	v_mfma_f32_16x16x32_bf16 v[4:7], v[172:175], v[192:195], v[4:7]
	ds_read_b128 v[64:67], v128
	ds_read_b128 v[136:139], v128 offset:2048
	ds_read_b128 v[140:143], v128 offset:4096
	ds_read_b128 v[172:175], v128 offset:6144
	v_mfma_f32_16x16x32_bf16 v[48:51], v[176:179], v[204:207], v[48:51]
	v_mfma_f32_16x16x32_bf16 v[32:35], v[176:179], v[200:203], v[32:35]
	v_mfma_f32_16x16x32_bf16 v[16:19], v[176:179], v[196:199], v[16:19]
	v_mfma_f32_16x16x32_bf16 v[0:3], v[176:179], v[192:195], v[0:3]
	s_waitcnt lgkmcnt(0)
	v_mfma_f32_16x16x32_bf16 v[108:111], v[188:191], v[136:139], v[108:111]
	v_mfma_f32_16x16x32_bf16 v[104:107], v[184:187], v[136:139], v[104:107]
	v_mfma_f32_16x16x32_bf16 v[100:103], v[180:183], v[136:139], v[100:103]
	v_mfma_f32_16x16x32_bf16 v[96:99], v[164:167], v[136:139], v[96:99]
	v_mfma_f32_16x16x32_bf16 v[92:95], v[188:191], v[140:143], v[92:95]
	v_mfma_f32_16x16x32_bf16 v[88:91], v[184:187], v[140:143], v[88:91]
	v_mfma_f32_16x16x32_bf16 v[84:87], v[180:183], v[140:143], v[84:87]
	v_mfma_f32_16x16x32_bf16 v[80:83], v[164:167], v[140:143], v[80:83]
	ds_read_b128 v[136:139], v128 offset:8192
	ds_read_b128 v[140:143], v128 offset:10240
	ds_read_b128 v[176:179], v128 offset:12288
	ds_read_b128 v[192:195], v128 offset:14336
	v_mfma_f32_16x16x32_bf16 v[124:127], v[188:191], v[64:67], v[124:127]
	v_mfma_f32_16x16x32_bf16 v[120:123], v[184:187], v[64:67], v[120:123]
	v_mfma_f32_16x16x32_bf16 v[116:119], v[180:183], v[64:67], v[116:119]
	v_mfma_f32_16x16x32_bf16 v[112:115], v[164:167], v[64:67], v[112:115]
	v_mfma_f32_16x16x32_bf16 v[76:79], v[188:191], v[172:175], v[76:79]
	v_mfma_f32_16x16x32_bf16 v[72:75], v[184:187], v[172:175], v[72:75]
	v_mfma_f32_16x16x32_bf16 v[64:67], v[180:183], v[172:175], v[68:71]
	v_mfma_f32_16x16x32_bf16 v[68:71], v[164:167], v[172:175], v[168:171]
	s_waitcnt lgkmcnt(0)
	v_mfma_f32_16x16x32_bf16 v[60:63], v[188:191], v[136:139], v[60:63]
	v_mfma_f32_16x16x32_bf16 v[56:59], v[184:187], v[136:139], v[56:59]
	v_mfma_f32_16x16x32_bf16 v[52:55], v[180:183], v[136:139], v[52:55]
	v_mfma_f32_16x16x32_bf16 v[48:51], v[164:167], v[136:139], v[48:51]
	v_mfma_f32_16x16x32_bf16 v[44:47], v[188:191], v[140:143], v[44:47]
	v_mfma_f32_16x16x32_bf16 v[40:43], v[184:187], v[140:143], v[40:43]
	v_mfma_f32_16x16x32_bf16 v[36:39], v[180:183], v[140:143], v[36:39]
	v_mfma_f32_16x16x32_bf16 v[32:35], v[164:167], v[140:143], v[32:35]
	v_mfma_f32_16x16x32_bf16 v[28:31], v[188:191], v[176:179], v[28:31]
	v_mfma_f32_16x16x32_bf16 v[24:27], v[184:187], v[176:179], v[24:27]
	v_mfma_f32_16x16x32_bf16 v[20:23], v[180:183], v[176:179], v[20:23]
	v_mfma_f32_16x16x32_bf16 v[16:19], v[164:167], v[176:179], v[16:19]
	v_mfma_f32_16x16x32_bf16 v[12:15], v[188:191], v[192:195], v[12:15]
	v_mfma_f32_16x16x32_bf16 v[8:11], v[184:187], v[192:195], v[8:11]
	v_mfma_f32_16x16x32_bf16 v[4:7], v[180:183], v[192:195], v[4:7]
	v_mfma_f32_16x16x32_bf16 v[0:3], v[164:167], v[192:195], v[0:3]
	s_andn2_b64 vcc, exec, s[52:53]
	s_mov_b64 s[54:55], -1
	s_waitcnt vmcnt(0)
	s_barrier
	s_cbranch_vccz .LBB0_719
	s_mov_b64 s[56:57], 0x1380
	s_and_b64 vcc, exec, s[54:55]
	s_cbranch_vccz .LBB0_712
	s_branch .LBB0_722

; __device__ __forceinline__ float bf_lo(unsigned u) { return __uint_as_float(u << 16); }
; __device__ __forceinline__ float bf_hi(unsigned u) { return __uint_as_float(u & 0xffff0000u); }
; __device__ __forceinline__ int launder_i(int x) { asm volatile("" : "+v"(x)); return x; }
; #define TIDX512 launder_i((int)threadIdx.x)
; __device__ __forceinline__ void glds16(const bf16_t* g, char* l) { __builtin_amdgcn_global_load_lds((const unsigned*)g, (unsigned*)l, 16, 0, 0); }
; __device__ __forceinline__ void gemm_issue(const GemmSrc& g, int kt, int s, char* lds) {
;     const int tid = TIDX512, lane = tid & 63, wave = tid >> 6;
;     char* xdst = lds + s * 65536 + wave * 4096 + lane * 16;
;     char* wdst = xdst + 32768;
; #pragma unroll
;     for (int i = 0; i < 4; i++) {
;         const int d = (i & 1) ? g.dsw : 0;
;         glds16(g.xsrc + (size_t)i * 8 * g.ldx + kt * 64 + d, xdst + i * 1024);
;         glds16(g.wsrc + (size_t)i * 8 * g.ldw + kt * 64 + d, wdst + i * 1024);
;     }
; }
; __device__ __forceinline__ void gemm_prologue(const GemmSrc& g, char* lds) { gemm_issue(g, 0, 0, lds); }
; __device__ void phaseM1(const Params& p, char* lds) {
;     ...
;             if (br == 0) {
;                 g = gemm_src(H, DM, (const bf16_t*)(p.ws + OFF_WM) + (size_t)1024 * 1024, DM, m0, n0);
;                 gemm_prologue(g, lds);
;             }
;             if (br == 0) {
; #pragma unroll
;                 for (int mi = 0; mi < 8; mi++)
; #pragma unroll
;                     for (int nh = 0; nh < 2; nh++) {
;                         const u32x4 sg = SG[(size_t)launder_i(pbase + (mi * 2 + nh) * 512)];
;                         const f32x4 a0 = acc[mi][2 * nh], a1 = acc[mi][2 * nh + 1];
;                         PA[(size_t)launder_i(pbase + (mi * 2 + nh) * 512)] = (u32x4){pack2(bf_lo(sg.x) * a0[0], bf_hi(sg.x) * a0[1]), pack2(bf_lo(sg.y) * a0[2], bf_hi(sg.y) * a0[3]),
;                                                                           pack2(bf_lo(sg.z) * a1[0], bf_hi(sg.z) * a1[1]), pack2(bf_lo(sg.w) * a1[2], bf_hi(sg.w) * a1[3])};
;                     }
.LBB0_722:
	v_mov_b32_e32 v128, v158
	s_mov_b64 s[56:57], 0x400
	v_ashrrev_i32_e32 v130, 1, v128
	v_bfe_u32 v131, v128, 3, 3
	v_and_or_b32 v134, v130, s63, v131
	v_bfe_u32 v130, v128, 4, 2
	v_and_b32_e32 v131, 7, v128
	v_bitop3_b32 v135, v130, v128, 7 bitop3:0x78
	v_bitop3_b32 v136, v130, v131, 4 bitop3:0x36
	v_add_u32_e32 v130, s74, v134
	v_ashrrev_i32_e32 v131, 31, v130
	v_lshlrev_b64 v[130:131], 11, v[130:131]
	v_lshl_add_u64 v[130:131], s[8:9], 0, v[130:131]
	v_lshlrev_b32_e32 v128, 4, v135
	v_lshl_add_u64 v[132:133], v[130:131], 0, v[128:129]
	v_add_u32_e32 v130, s48, v134
	v_ashrrev_i32_e32 v131, 31, v130
	v_lshlrev_b64 v[130:131], 11, v[130:131]
	v_lshl_add_u64 v[130:131], s[14:15], 0, v[130:131]
	v_lshl_add_u64 v[130:131], v[130:131], 0, v[128:129]
	v_sub_u32_e32 v128, v136, v135
	v_lshlrev_b32_e32 v134, 3, v128
	v_mov_b32_e32 v128, v158
	s_nop 0
	v_lshlrev_b32_e32 v135, 6, v128
	v_lshlrev_b32_e32 v128, 4, v128
	v_and_b32_e32 v128, 0x3f0, v128
	v_and_or_b32 v128, v135, s65, v128
	v_add_u32_e32 v135, 0x8000, v128
	v_readfirstlane_b32 s0, v128
	s_mov_b32 m0, s0
	v_readfirstlane_b32 s0, v135
	v_ashrrev_i32_e32 v135, 31, v134
	v_lshlrev_b64 v[136:137], 1, v[134:135]
	v_or_b32_e32 v135, 0x400, v128
	s_cmp_lg_u32 s33, 0
	s_cbranch_scc1 .Ldma_skip_48
	global_load_lds_dwordx4 v[132:133], off
	s_add_u32 m0, m0, 0x4000
	v_lshl_add_u64 v[220:221], v[132:133], 0, s[100:101]
	global_load_lds_dwordx4 v[220:221], off
.Ldma_skip_48:
	s_mov_b32 m0, s0
	v_lshl_add_u64 v[138:139], v[132:133], 0, v[136:137]
	v_readfirstlane_b32 s0, v135
	v_add_u32_e32 v135, 0x8400, v128
	s_cmp_lg_u32 s33, 0
	s_cbranch_scc1 .Ldma_skip_49
	global_load_lds_dwordx4 v[130:131], off
	s_add_u32 m0, m0, 0x4000
	v_lshl_add_u64 v[220:221], v[130:131], 0, s[100:101]
	global_load_lds_dwordx4 v[220:221], off
.Ldma_skip_49:
	v_lshl_add_u64 v[140:141], v[138:139], 0, s[16:17]
	s_mov_b32 m0, s0
	v_lshl_add_u64 v[136:137], v[130:131], 0, v[136:137]
	v_readfirstlane_b32 s0, v135
	v_or_b32_e32 v135, 0x800, v128
	s_cmp_lg_u32 s33, 0
	s_cbranch_scc1 .Ldma_skip_50
	global_load_lds_dwordx4 v[140:141], off
	s_add_u32 m0, m0, 0x4000
	v_lshl_add_u64 v[220:221], v[140:141], 0, s[100:101]
	global_load_lds_dwordx4 v[220:221], off
.Ldma_skip_50:
	v_lshl_add_u64 v[140:141], v[136:137], 0, s[16:17]
	s_mov_b32 m0, s0
	v_readfirstlane_b32 s0, v135
	v_add_u32_e32 v135, 0x8800, v128
	s_cmp_lg_u32 s33, 0
	s_cbranch_scc1 .Ldma_skip_51
	global_load_lds_dwordx4 v[140:141], off
	s_add_u32 m0, m0, 0x4000
	v_lshl_add_u64 v[220:221], v[140:141], 0, s[100:101]
	global_load_lds_dwordx4 v[220:221], off
.Ldma_skip_51:
	v_lshl_add_u64 v[140:141], v[132:133], 0, s[18:19]
	s_mov_b32 m0, s0
	v_readfirstlane_b32 s0, v135
	v_or_b32_e32 v135, 0xc00, v128
	s_cmp_lg_u32 s33, 0
	s_cbranch_scc1 .Ldma_skip_52
	global_load_lds_dwordx4 v[140:141], off
	s_add_u32 m0, m0, 0x4000
	v_lshl_add_u64 v[220:221], v[140:141], 0, s[100:101]
	global_load_lds_dwordx4 v[220:221], off
.Ldma_skip_52:
	v_lshl_add_u64 v[140:141], v[130:131], 0, s[18:19]
	s_mov_b32 m0, s0
	v_readfirstlane_b32 s0, v135
	v_add_u32_e32 v128, 0x8c00, v128
	s_cmp_lg_u32 s33, 0
	s_cbranch_scc1 .Ldma_skip_53
	global_load_lds_dwordx4 v[140:141], off
	s_add_u32 m0, m0, 0x4000
	v_lshl_add_u64 v[220:221], v[140:141], 0, s[100:101]
	global_load_lds_dwordx4 v[220:221], off
.Ldma_skip_53:
	v_lshl_add_u64 v[138:139], v[138:139], 0, s[20:21]
	s_mov_b32 m0, s0
	v_readfirstlane_b32 s0, v128
	s_cmp_lg_u32 s33, 0
	s_cbranch_scc1 .Ldma_skip_54
	global_load_lds_dwordx4 v[138:139], off
	s_add_u32 m0, m0, 0x4000
	v_lshl_add_u64 v[220:221], v[138:139], 0, s[100:101]
	global_load_lds_dwordx4 v[220:221], off
.Ldma_skip_54:
	v_lshl_add_u64 v[136:137], v[136:137], 0, s[20:21]
	s_mov_b32 m0, s0
	v_mov_b32_e32 v140, v146
	s_cmp_lg_u32 s33, 0
	s_cbranch_scc1 .Ldma_skip_55
	global_load_lds_dwordx4 v[136:137], off
	s_add_u32 m0, m0, 0x4000
	v_lshl_add_u64 v[220:221], v[136:137], 0, s[100:101]
	global_load_lds_dwordx4 v[220:221], off
.Ldma_skip_55:
	v_mov_b32_e32 v136, v146
	s_nop 0
	v_ashrrev_i32_e32 v137, 31, v136
	v_lshl_add_u64 v[136:137], v[136:137], 4, s[4:5]
	global_load_dwordx4 v[136:139], v[136:137], off
	s_waitcnt vmcnt(0)
	v_lshlrev_b32_e32 v142, 16, v136
	v_and_b32_e32 v143, 0xffff0000, v136
	v_lshlrev_b32_e32 v136, 16, v137
	v_and_b32_e32 v137, 0xffff0000, v137
	v_lshlrev_b32_e32 v164, 16, v138
	v_and_b32_e32 v165, 0xffff0000, v138
	v_lshlrev_b32_e32 v138, 16, v139
	v_and_b32_e32 v139, 0xffff0000, v139
	v_ashrrev_i32_e32 v141, 31, v140
	v_pk_mul_f32 v[124:125], v[124:125], v[142:143]
	v_pk_mul_f32 v[126:127], v[126:127], v[136:137]
	v_pk_mul_f32 v[136:137], v[120:121], v[164:165]
	v_pk_mul_f32 v[138:139], v[122:123], v[138:139]
	v_lshl_add_u64 v[140:141], v[140:141], 4, s[10:11]
	v_cvt_pk_bf16_f32 v120, v124, v125
	v_cvt_pk_bf16_f32 v121, v126, v127
	v_cvt_pk_bf16_f32 v122, v136, v137
	v_cvt_pk_bf16_f32 v123, v138, v139
	global_store_dwordx4 v[140:141], v[120:123], off
	v_mov_b32_e32 v124, v147
	v_mov_b32_e32 v126, v148
	v_mov_b32_e32 v120, v147
	s_nop 0
	v_ashrrev_i32_e32 v121, 31, v120
	v_lshl_add_u64 v[120:121], v[120:121], 4, s[4:5]
	global_load_dwordx4 v[120:123], v[120:121], off
	s_waitcnt vmcnt(0)
; __device__ __forceinline__ float bf_lo(unsigned u) { return __uint_as_float(u << 16); }
; __device__ __forceinline__ float bf_hi(unsigned u) { return __uint_as_float(u & 0xffff0000u); }
; __device__ __forceinline__ int launder_i(int x) { asm volatile("" : "+v"(x)); return x; }
; __device__ void phaseM1(const Params& p, char* lds) {
;     ...
;             if (br == 0) {
; #pragma unroll
;                 for (int mi = 0; mi < 8; mi++)
; #pragma unroll
;                     for (int nh = 0; nh < 2; nh++) {
;                         const u32x4 sg = SG[(size_t)launder_i(pbase + (mi * 2 + nh) * 512)];
;                         const f32x4 a0 = acc[mi][2 * nh], a1 = acc[mi][2 * nh + 1];
;                         PA[(size_t)launder_i(pbase + (mi * 2 + nh) * 512)] = (u32x4){pack2(bf_lo(sg.x) * a0[0], bf_hi(sg.x) * a0[1]), pack2(bf_lo(sg.y) * a0[2], bf_hi(sg.y) * a0[3]),
;                                                                           pack2(bf_lo(sg.z) * a1[0], bf_hi(sg.z) * a1[1]), pack2(bf_lo(sg.w) * a1[2], bf_hi(sg.w) * a1[3])};
;                     }
	v_lshlrev_b32_e32 v136, 16, v120
	v_and_b32_e32 v137, 0xffff0000, v120
	v_lshlrev_b32_e32 v120, 16, v121
	v_and_b32_e32 v121, 0xffff0000, v121
	v_lshlrev_b32_e32 v138, 16, v122
	v_and_b32_e32 v139, 0xffff0000, v122
	v_lshlrev_b32_e32 v122, 16, v123
	v_and_b32_e32 v123, 0xffff0000, v123
	v_ashrrev_i32_e32 v125, 31, v124
	v_pk_mul_f32 v[116:117], v[116:117], v[136:137]
	v_pk_mul_f32 v[118:119], v[118:119], v[120:121]
	v_pk_mul_f32 v[120:121], v[112:113], v[138:139]
	v_pk_mul_f32 v[122:123], v[114:115], v[122:123]
	v_lshl_add_u64 v[124:125], v[124:125], 4, s[10:11]
	v_cvt_pk_bf16_f32 v112, v116, v117
	v_cvt_pk_bf16_f32 v113, v118, v119
	v_cvt_pk_bf16_f32 v114, v120, v121
	v_cvt_pk_bf16_f32 v115, v122, v123
	global_store_dwordx4 v[124:125], v[112:115], off
	v_mov_b32_e32 v116, v148
	v_ashrrev_i32_e32 v127, 31, v126
	v_lshl_add_u64 v[112:113], v[126:127], 4, s[4:5]
	global_load_dwordx4 v[112:115], v[112:113], off
	v_mov_b32_e32 v118, v149
	v_ashrrev_i32_e32 v117, 31, v116
	v_lshl_add_u64 v[116:117], v[116:117], 4, s[10:11]
	s_waitcnt vmcnt(0)
	v_lshlrev_b32_e32 v120, 16, v112
	v_and_b32_e32 v121, 0xffff0000, v112
	v_lshlrev_b32_e32 v112, 16, v113
	v_and_b32_e32 v113, 0xffff0000, v113
	v_lshlrev_b32_e32 v122, 16, v114
	v_and_b32_e32 v123, 0xffff0000, v114
	v_lshlrev_b32_e32 v114, 16, v115
	v_and_b32_e32 v115, 0xffff0000, v115
	v_pk_mul_f32 v[108:109], v[108:109], v[120:121]
	v_pk_mul_f32 v[110:111], v[110:111], v[112:113]
	v_pk_mul_f32 v[112:113], v[104:105], v[122:123]
	v_pk_mul_f32 v[114:115], v[106:107], v[114:115]
	v_cvt_pk_bf16_f32 v104, v108, v109
	v_cvt_pk_bf16_f32 v105, v110, v111
	v_cvt_pk_bf16_f32 v106, v112, v113
	v_cvt_pk_bf16_f32 v107, v114, v115
	global_store_dwordx4 v[116:117], v[104:107], off
	v_mov_b32_e32 v108, v149
	v_ashrrev_i32_e32 v119, 31, v118
	v_lshl_add_u64 v[104:105], v[118:119], 4, s[4:5]
	global_load_dwordx4 v[104:107], v[104:105], off
	v_mov_b32_e32 v110, v150
	v_ashrrev_i32_e32 v109, 31, v108
	v_lshl_add_u64 v[108:109], v[108:109], 4, s[10:11]
	s_waitcnt vmcnt(0)
	v_lshlrev_b32_e32 v112, 16, v104
	v_and_b32_e32 v113, 0xffff0000, v104
	v_lshlrev_b32_e32 v104, 16, v105
	v_and_b32_e32 v105, 0xffff0000, v105
	v_lshlrev_b32_e32 v114, 16, v106
	v_and_b32_e32 v115, 0xffff0000, v106
	v_lshlrev_b32_e32 v106, 16, v107
	v_and_b32_e32 v107, 0xffff0000, v107
	v_pk_mul_f32 v[100:101], v[100:101], v[112:113]
	v_pk_mul_f32 v[102:103], v[102:103], v[104:105]
	v_pk_mul_f32 v[104:105], v[96:97], v[114:115]
	v_pk_mul_f32 v[106:107], v[98:99], v[106:107]
	v_cvt_pk_bf16_f32 v96, v100, v101
	v_cvt_pk_bf16_f32 v97, v102, v103
	v_cvt_pk_bf16_f32 v98, v104, v105
	v_cvt_pk_bf16_f32 v99, v106, v107
	global_store_dwordx4 v[108:109], v[96:99], off
	v_mov_b32_e32 v100, v150
	v_ashrrev_i32_e32 v111, 31, v110
	v_lshl_add_u64 v[96:97], v[110:111], 4, s[4:5]
	global_load_dwordx4 v[96:99], v[96:97], off
	v_mov_b32_e32 v102, v151
	v_ashrrev_i32_e32 v101, 31, v100
	v_lshl_add_u64 v[100:101], v[100:101], 4, s[10:11]
	s_waitcnt vmcnt(0)
	v_lshlrev_b32_e32 v104, 16, v96
	v_and_b32_e32 v105, 0xffff0000, v96
	v_lshlrev_b32_e32 v96, 16, v97
	v_and_b32_e32 v97, 0xffff0000, v97
	v_lshlrev_b32_e32 v106, 16, v98
	v_and_b32_e32 v107, 0xffff0000, v98
	v_lshlrev_b32_e32 v98, 16, v99
	v_and_b32_e32 v99, 0xffff0000, v99
	v_pk_mul_f32 v[92:93], v[92:93], v[104:105]
	v_pk_mul_f32 v[94:95], v[94:95], v[96:97]
	v_pk_mul_f32 v[96:97], v[88:89], v[106:107]
	v_pk_mul_f32 v[98:99], v[90:91], v[98:99]
	v_cvt_pk_bf16_f32 v88, v92, v93
	v_cvt_pk_bf16_f32 v89, v94, v95
	v_cvt_pk_bf16_f32 v90, v96, v97
	v_cvt_pk_bf16_f32 v91, v98, v99
	global_store_dwordx4 v[100:101], v[88:91], off
	v_mov_b32_e32 v92, v151
	v_ashrrev_i32_e32 v103, 31, v102
	v_lshl_add_u64 v[88:89], v[102:103], 4, s[4:5]
	global_load_dwordx4 v[88:91], v[88:89], off
	v_mov_b32_e32 v94, v152
	v_ashrrev_i32_e32 v93, 31, v92
	v_lshl_add_u64 v[92:93], v[92:93], 4, s[10:11]
	s_waitcnt vmcnt(0)
	v_lshlrev_b32_e32 v96, 16, v88
	v_and_b32_e32 v97, 0xffff0000, v88
	v_lshlrev_b32_e32 v88, 16, v89
	v_and_b32_e32 v89, 0xffff0000, v89
	v_lshlrev_b32_e32 v98, 16, v90
	v_and_b32_e32 v99, 0xffff0000, v90
	v_lshlrev_b32_e32 v90, 16, v91
	v_and_b32_e32 v91, 0xffff0000, v91
	v_pk_mul_f32 v[84:85], v[84:85], v[96:97]
	v_pk_mul_f32 v[86:87], v[86:87], v[88:89]
	v_pk_mul_f32 v[88:89], v[80:81], v[98:99]
	v_pk_mul_f32 v[90:91], v[82:83], v[90:91]
	v_cvt_pk_bf16_f32 v80, v84, v85
	v_cvt_pk_bf16_f32 v81, v86, v87
	v_cvt_pk_bf16_f32 v82, v88, v89
	v_cvt_pk_bf16_f32 v83, v90, v91
	global_store_dwordx4 v[92:93], v[80:83], off
	v_mov_b32_e32 v84, v152
	v_ashrrev_i32_e32 v95, 31, v94
	v_lshl_add_u64 v[80:81], v[94:95], 4, s[4:5]
	global_load_dwordx4 v[80:83], v[80:81], off
	v_mov_b32_e32 v86, v153
	v_ashrrev_i32_e32 v85, 31, v84
	v_lshl_add_u64 v[84:85], v[84:85], 4, s[10:11]
	s_waitcnt vmcnt(0)
	v_lshlrev_b32_e32 v88, 16, v80
	v_and_b32_e32 v89, 0xffff0000, v80
	v_lshlrev_b32_e32 v80, 16, v81
	v_and_b32_e32 v81, 0xffff0000, v81
	v_lshlrev_b32_e32 v90, 16, v82
	v_and_b32_e32 v91, 0xffff0000, v82
	v_lshlrev_b32_e32 v82, 16, v83
	v_and_b32_e32 v83, 0xffff0000, v83
	v_pk_mul_f32 v[76:77], v[76:77], v[88:89]
	v_pk_mul_f32 v[78:79], v[78:79], v[80:81]
	v_pk_mul_f32 v[80:81], v[72:73], v[90:91]
	v_pk_mul_f32 v[82:83], v[74:75], v[82:83]
	v_cvt_pk_bf16_f32 v72, v76, v77
	v_cvt_pk_bf16_f32 v73, v78, v79
	v_cvt_pk_bf16_f32 v74, v80, v81
	v_cvt_pk_bf16_f32 v75, v82, v83
	global_store_dwordx4 v[84:85], v[72:75], off
	v_mov_b32_e32 v76, v153
	v_ashrrev_i32_e32 v87, 31, v86
	v_lshl_add_u64 v[72:73], v[86:87], 4, s[4:5]
	global_load_dwordx4 v[72:75], v[72:73], off
	v_mov_b32_e32 v78, v154
	v_ashrrev_i32_e32 v77, 31, v76
	v_lshl_add_u64 v[76:77], v[76:77], 4, s[10:11]
	s_waitcnt vmcnt(0)
; __device__ __forceinline__ float bf_lo(unsigned u) { return __uint_as_float(u << 16); }
; __device__ __forceinline__ float bf_hi(unsigned u) { return __uint_as_float(u & 0xffff0000u); }
; __device__ __forceinline__ int launder_i(int x) { asm volatile("" : "+v"(x)); return x; }
; __device__ void phaseM1(const Params& p, char* lds) {
;     ...
;             if (br == 0) {
; #pragma unroll
;                 for (int mi = 0; mi < 8; mi++)
; #pragma unroll
;                     for (int nh = 0; nh < 2; nh++) {
;                         const u32x4 sg = SG[(size_t)launder_i(pbase + (mi * 2 + nh) * 512)];
;                         const f32x4 a0 = acc[mi][2 * nh], a1 = acc[mi][2 * nh + 1];
;                         PA[(size_t)launder_i(pbase + (mi * 2 + nh) * 512)] = (u32x4){pack2(bf_lo(sg.x) * a0[0], bf_hi(sg.x) * a0[1]), pack2(bf_lo(sg.y) * a0[2], bf_hi(sg.y) * a0[3]),
;                                                                           pack2(bf_lo(sg.z) * a1[0], bf_hi(sg.z) * a1[1]), pack2(bf_lo(sg.w) * a1[2], bf_hi(sg.w) * a1[3])};
;                     }
	v_lshlrev_b32_e32 v80, 16, v72
	v_and_b32_e32 v81, 0xffff0000, v72
	v_lshlrev_b32_e32 v72, 16, v73
	v_and_b32_e32 v73, 0xffff0000, v73
	v_lshlrev_b32_e32 v82, 16, v74
	v_and_b32_e32 v83, 0xffff0000, v74
	v_lshlrev_b32_e32 v74, 16, v75
	v_and_b32_e32 v75, 0xffff0000, v75
	v_pk_mul_f32 v[64:65], v[64:65], v[80:81]
	v_pk_mul_f32 v[66:67], v[66:67], v[72:73]
	v_pk_mul_f32 v[68:69], v[68:69], v[82:83]
	v_pk_mul_f32 v[70:71], v[70:71], v[74:75]
	v_cvt_pk_bf16_f32 v64, v64, v65
	v_cvt_pk_bf16_f32 v65, v66, v67
	v_cvt_pk_bf16_f32 v66, v68, v69
	v_cvt_pk_bf16_f32 v67, v70, v71
	global_store_dwordx4 v[76:77], v[64:67], off
	v_mov_b32_e32 v68, v154
	v_ashrrev_i32_e32 v79, 31, v78
	v_lshl_add_u64 v[64:65], v[78:79], 4, s[4:5]
	global_load_dwordx4 v[64:67], v[64:65], off
	v_mov_b32_e32 v70, v155
	v_ashrrev_i32_e32 v69, 31, v68
	v_lshl_add_u64 v[68:69], v[68:69], 4, s[10:11]
	s_waitcnt vmcnt(0)
	v_lshlrev_b32_e32 v72, 16, v64
	v_and_b32_e32 v73, 0xffff0000, v64
	v_lshlrev_b32_e32 v64, 16, v65
	v_and_b32_e32 v65, 0xffff0000, v65
	v_lshlrev_b32_e32 v74, 16, v66
	v_and_b32_e32 v75, 0xffff0000, v66
	v_lshlrev_b32_e32 v66, 16, v67
	v_and_b32_e32 v67, 0xffff0000, v67
	v_pk_mul_f32 v[60:61], v[60:61], v[72:73]
	v_pk_mul_f32 v[62:63], v[62:63], v[64:65]
	v_pk_mul_f32 v[64:65], v[56:57], v[74:75]
	v_pk_mul_f32 v[66:67], v[58:59], v[66:67]
	v_cvt_pk_bf16_f32 v56, v60, v61
	v_cvt_pk_bf16_f32 v57, v62, v63
	v_cvt_pk_bf16_f32 v58, v64, v65
	v_cvt_pk_bf16_f32 v59, v66, v67
	global_store_dwordx4 v[68:69], v[56:59], off
	v_mov_b32_e32 v60, v155
	v_ashrrev_i32_e32 v71, 31, v70
	v_lshl_add_u64 v[56:57], v[70:71], 4, s[4:5]
	global_load_dwordx4 v[56:59], v[56:57], off
	v_mov_b32_e32 v62, v156
	v_ashrrev_i32_e32 v61, 31, v60
	v_lshl_add_u64 v[60:61], v[60:61], 4, s[10:11]
	s_waitcnt vmcnt(0)
	v_lshlrev_b32_e32 v64, 16, v56
	v_and_b32_e32 v65, 0xffff0000, v56
	v_lshlrev_b32_e32 v56, 16, v57
	v_and_b32_e32 v57, 0xffff0000, v57
	v_lshlrev_b32_e32 v66, 16, v58
	v_and_b32_e32 v67, 0xffff0000, v58
	v_lshlrev_b32_e32 v58, 16, v59
	v_and_b32_e32 v59, 0xffff0000, v59
	v_pk_mul_f32 v[52:53], v[52:53], v[64:65]
	v_pk_mul_f32 v[54:55], v[54:55], v[56:57]
	v_pk_mul_f32 v[56:57], v[48:49], v[66:67]
	v_pk_mul_f32 v[58:59], v[50:51], v[58:59]
	v_cvt_pk_bf16_f32 v48, v52, v53
	v_cvt_pk_bf16_f32 v49, v54, v55
	v_cvt_pk_bf16_f32 v50, v56, v57
	v_cvt_pk_bf16_f32 v51, v58, v59
	global_store_dwordx4 v[60:61], v[48:51], off
	v_mov_b32_e32 v52, v156
	v_ashrrev_i32_e32 v63, 31, v62
	v_lshl_add_u64 v[48:49], v[62:63], 4, s[4:5]
	global_load_dwordx4 v[48:51], v[48:49], off
	v_mov_b32_e32 v54, v157
	v_ashrrev_i32_e32 v53, 31, v52
	v_lshl_add_u64 v[52:53], v[52:53], 4, s[10:11]
	s_waitcnt vmcnt(0)
	v_lshlrev_b32_e32 v56, 16, v48
	v_and_b32_e32 v57, 0xffff0000, v48
	v_lshlrev_b32_e32 v48, 16, v49
	v_and_b32_e32 v49, 0xffff0000, v49
	v_lshlrev_b32_e32 v58, 16, v50
	v_and_b32_e32 v59, 0xffff0000, v50
	v_lshlrev_b32_e32 v50, 16, v51
	v_and_b32_e32 v51, 0xffff0000, v51
	v_pk_mul_f32 v[44:45], v[44:45], v[56:57]
	v_pk_mul_f32 v[46:47], v[46:47], v[48:49]
	v_pk_mul_f32 v[48:49], v[40:41], v[58:59]
	v_pk_mul_f32 v[50:51], v[42:43], v[50:51]
	v_cvt_pk_bf16_f32 v40, v44, v45
	v_cvt_pk_bf16_f32 v41, v46, v47
	v_cvt_pk_bf16_f32 v42, v48, v49
	v_cvt_pk_bf16_f32 v43, v50, v51
	global_store_dwordx4 v[52:53], v[40:43], off
	v_mov_b32_e32 v44, v157
	v_ashrrev_i32_e32 v55, 31, v54
	v_lshl_add_u64 v[40:41], v[54:55], 4, s[4:5]
	global_load_dwordx4 v[40:43], v[40:41], off
	v_mov_b32_e32 v46, v160
	v_ashrrev_i32_e32 v45, 31, v44
	v_lshl_add_u64 v[44:45], v[44:45], 4, s[10:11]
	s_waitcnt vmcnt(0)
; __device__ __forceinline__ float bf_lo(unsigned u) { return __uint_as_float(u << 16); }
; __device__ __forceinline__ float bf_hi(unsigned u) { return __uint_as_float(u & 0xffff0000u); }
; __device__ __forceinline__ int launder_i(int x) { asm volatile("" : "+v"(x)); return x; }
; __device__ void phaseM1(const Params& p, char* lds) {
;     ...
;             if (br == 0) {
; #pragma unroll
;                 for (int mi = 0; mi < 8; mi++)
; #pragma unroll
;                     for (int nh = 0; nh < 2; nh++) {
;                         const u32x4 sg = SG[(size_t)launder_i(pbase + (mi * 2 + nh) * 512)];
;                         const f32x4 a0 = acc[mi][2 * nh], a1 = acc[mi][2 * nh + 1];
;                         PA[(size_t)launder_i(pbase + (mi * 2 + nh) * 512)] = (u32x4){pack2(bf_lo(sg.x) * a0[0], bf_hi(sg.x) * a0[1]), pack2(bf_lo(sg.y) * a0[2], bf_hi(sg.y) * a0[3]),
;                                                                           pack2(bf_lo(sg.z) * a1[0], bf_hi(sg.z) * a1[1]), pack2(bf_lo(sg.w) * a1[2], bf_hi(sg.w) * a1[3])};
;                     }
	v_lshlrev_b32_e32 v48, 16, v40
	v_and_b32_e32 v49, 0xffff0000, v40
	v_lshlrev_b32_e32 v40, 16, v41
	v_and_b32_e32 v41, 0xffff0000, v41
	v_lshlrev_b32_e32 v50, 16, v42
	v_and_b32_e32 v51, 0xffff0000, v42
	v_lshlrev_b32_e32 v42, 16, v43
	v_and_b32_e32 v43, 0xffff0000, v43
	v_pk_mul_f32 v[36:37], v[36:37], v[48:49]
	v_pk_mul_f32 v[38:39], v[38:39], v[40:41]
	v_pk_mul_f32 v[40:41], v[32:33], v[50:51]
	v_pk_mul_f32 v[42:43], v[34:35], v[42:43]
	v_cvt_pk_bf16_f32 v32, v36, v37
	v_cvt_pk_bf16_f32 v33, v38, v39
	v_cvt_pk_bf16_f32 v34, v40, v41
	v_cvt_pk_bf16_f32 v35, v42, v43
	global_store_dwordx4 v[44:45], v[32:35], off
	v_mov_b32_e32 v36, v160
	v_ashrrev_i32_e32 v47, 31, v46
	v_lshl_add_u64 v[32:33], v[46:47], 4, s[4:5]
	global_load_dwordx4 v[32:35], v[32:33], off
	v_mov_b32_e32 v38, v161
	v_ashrrev_i32_e32 v37, 31, v36
	v_lshl_add_u64 v[36:37], v[36:37], 4, s[10:11]
	s_waitcnt vmcnt(0)
	v_lshlrev_b32_e32 v40, 16, v32
	v_and_b32_e32 v41, 0xffff0000, v32
	v_lshlrev_b32_e32 v32, 16, v33
	v_and_b32_e32 v33, 0xffff0000, v33
	v_lshlrev_b32_e32 v42, 16, v34
	v_and_b32_e32 v43, 0xffff0000, v34
	v_lshlrev_b32_e32 v34, 16, v35
	v_and_b32_e32 v35, 0xffff0000, v35
	v_pk_mul_f32 v[28:29], v[28:29], v[40:41]
	v_pk_mul_f32 v[30:31], v[30:31], v[32:33]
	v_pk_mul_f32 v[32:33], v[24:25], v[42:43]
	v_pk_mul_f32 v[34:35], v[26:27], v[34:35]
	v_cvt_pk_bf16_f32 v24, v28, v29
	v_cvt_pk_bf16_f32 v25, v30, v31
	v_cvt_pk_bf16_f32 v26, v32, v33
	v_cvt_pk_bf16_f32 v27, v34, v35
	global_store_dwordx4 v[36:37], v[24:27], off
	v_mov_b32_e32 v28, v161
	v_ashrrev_i32_e32 v39, 31, v38
	v_lshl_add_u64 v[24:25], v[38:39], 4, s[4:5]
	global_load_dwordx4 v[24:27], v[24:25], off
	v_mov_b32_e32 v30, v162
	v_ashrrev_i32_e32 v29, 31, v28
	v_lshl_add_u64 v[28:29], v[28:29], 4, s[10:11]
	s_waitcnt vmcnt(0)
	v_lshlrev_b32_e32 v32, 16, v24
	v_and_b32_e32 v33, 0xffff0000, v24
	v_lshlrev_b32_e32 v24, 16, v25
	v_and_b32_e32 v25, 0xffff0000, v25
	v_lshlrev_b32_e32 v34, 16, v26
	v_and_b32_e32 v35, 0xffff0000, v26
	v_lshlrev_b32_e32 v26, 16, v27
	v_and_b32_e32 v27, 0xffff0000, v27
	v_pk_mul_f32 v[20:21], v[20:21], v[32:33]
	v_pk_mul_f32 v[22:23], v[22:23], v[24:25]
	v_pk_mul_f32 v[24:25], v[16:17], v[34:35]
	v_pk_mul_f32 v[26:27], v[18:19], v[26:27]
	v_cvt_pk_bf16_f32 v16, v20, v21
	v_cvt_pk_bf16_f32 v17, v22, v23
	v_cvt_pk_bf16_f32 v18, v24, v25
	v_cvt_pk_bf16_f32 v19, v26, v27
	global_store_dwordx4 v[28:29], v[16:19], off
	v_mov_b32_e32 v20, v162
	v_ashrrev_i32_e32 v31, 31, v30
	v_lshl_add_u64 v[16:17], v[30:31], 4, s[4:5]
	global_load_dwordx4 v[16:19], v[16:17], off
	v_mov_b32_e32 v22, v163
	v_ashrrev_i32_e32 v21, 31, v20
	v_lshl_add_u64 v[20:21], v[20:21], 4, s[10:11]
	s_waitcnt vmcnt(0)
	v_lshlrev_b32_e32 v24, 16, v16
	v_and_b32_e32 v25, 0xffff0000, v16
	v_lshlrev_b32_e32 v16, 16, v17
	v_and_b32_e32 v17, 0xffff0000, v17
	v_lshlrev_b32_e32 v26, 16, v18
	v_and_b32_e32 v27, 0xffff0000, v18
	v_lshlrev_b32_e32 v18, 16, v19
	v_and_b32_e32 v19, 0xffff0000, v19
	v_pk_mul_f32 v[12:13], v[12:13], v[24:25]
	v_pk_mul_f32 v[14:15], v[14:15], v[16:17]
	v_pk_mul_f32 v[16:17], v[8:9], v[26:27]
	v_pk_mul_f32 v[18:19], v[10:11], v[18:19]
	v_cvt_pk_bf16_f32 v8, v12, v13
	v_cvt_pk_bf16_f32 v9, v14, v15
	v_cvt_pk_bf16_f32 v10, v16, v17
	v_cvt_pk_bf16_f32 v11, v18, v19
	global_store_dwordx4 v[20:21], v[8:11], off
	v_mov_b32_e32 v12, v163
	v_ashrrev_i32_e32 v23, 31, v22
	v_lshl_add_u64 v[8:9], v[22:23], 4, s[4:5]
	global_load_dwordx4 v[8:11], v[8:9], off
	s_waitcnt vmcnt(0)
	v_lshlrev_b32_e32 v14, 16, v8
	v_and_b32_e32 v15, 0xffff0000, v8
	v_lshlrev_b32_e32 v8, 16, v9
	v_and_b32_e32 v9, 0xffff0000, v9
	v_lshlrev_b32_e32 v16, 16, v10
	v_and_b32_e32 v17, 0xffff0000, v10
	v_lshlrev_b32_e32 v10, 16, v11
	v_and_b32_e32 v11, 0xffff0000, v11
	v_ashrrev_i32_e32 v13, 31, v12
	v_pk_mul_f32 v[4:5], v[4:5], v[14:15]
	v_pk_mul_f32 v[6:7], v[6:7], v[8:9]
	v_pk_mul_f32 v[8:9], v[0:1], v[16:17]
	v_pk_mul_f32 v[10:11], v[2:3], v[10:11]
	v_lshl_add_u64 v[12:13], v[12:13], 4, s[10:11]
	v_cvt_pk_bf16_f32 v0, v4, v5
	v_cvt_pk_bf16_f32 v1, v6, v7
	v_cvt_pk_bf16_f32 v2, v8, v9
	v_cvt_pk_bf16_f32 v3, v10, v11
	global_store_dwordx4 v[12:13], v[0:3], off
	s_branch .LBB0_712

; #define TIDX512 launder_i((int)threadIdx.x)
; __device__ __forceinline__ void glds16(const bf16_t* g, char* l) { __builtin_amdgcn_global_load_lds((const unsigned*)g, (unsigned*)l, 16, 0, 0); }
; __device__ __forceinline__ void gemm_issue(const GemmSrc& g, int kt, int s, char* lds) {
;     const int tid = TIDX512, lane = tid & 63, wave = tid >> 6;
;     char* xdst = lds + s * 65536 + wave * 4096 + lane * 16;
;     char* wdst = xdst + 32768;
; #pragma unroll
;     for (int i = 0; i < 4; i++) {
;         const int d = (i & 1) ? g.dsw : 0;
;         glds16(g.xsrc + (size_t)i * 8 * g.ldx + kt * 64 + d, xdst + i * 1024);
;         glds16(g.wsrc + (size_t)i * 8 * g.ldw + kt * 64 + d, wdst + i * 1024);
;     }
; }
; __device__ __forceinline__ void gemm_prologue(const GemmSrc& g, char* lds) { gemm_issue(g, 0, 0, lds); }
; __device__ __forceinline__ void zero_acc(f32x4 (&acc)[8][4]) {
; #pragma unroll
;     for (int a = 0; a < 8; a++)
; #pragma unroll
;         for (int b = 0; b < 4; b++) acc[a][b] = (f32x4){0.f, 0.f, 0.f, 0.f};
; }
.LBB0_786:
	v_mov_b32_e32 v0, v158
	s_lshl_b32 s47, s47, 8
	v_ashrrev_i32_e32 v1, 1, v0
	v_and_b32_e32 v12, 0xffffffe0, v1
	v_bfe_u32 v1, v0, 4, 2
	v_and_b32_e32 v3, 7, v0
	v_bitop3_b32 v4, v1, v0, 7 bitop3:0x78
	v_bitop3_b32 v5, v1, v3, 4 bitop3:0x36
	v_lshlrev_b32_e32 v152, 4, v4
	v_sub_u32_e32 v4, v5, v4
	v_mov_b32_e32 v5, v158
	v_bfe_u32 v13, v0, 3, 3
	v_or_b32_e32 v2, v12, v13
	v_lshlrev_b32_e32 v6, 6, v5
	v_lshlrev_b32_e32 v5, 4, v5
	s_lshl_b32 s38, s48, 8
	v_add_u32_e32 v0, s47, v2
	v_and_b32_e32 v5, 0x3f0, v5
	v_ashrrev_i32_e32 v1, 31, v0
	v_add_u32_e32 v2, s38, v2
	v_and_or_b32 v14, v6, s42, v5
	v_lshlrev_b64 v[0:1], 11, v[0:1]
	v_ashrrev_i32_e32 v3, 31, v2
	v_lshlrev_b32_e32 v4, 3, v4
	v_add_u32_e32 v5, 0x8000, v14
	v_readfirstlane_b32 s39, v14
	v_lshl_add_u64 v[0:1], s[4:5], 0, v[0:1]
	v_lshlrev_b64 v[2:3], 11, v[2:3]
	s_mov_b32 m0, s39
	v_readfirstlane_b32 s39, v5
	v_ashrrev_i32_e32 v5, 31, v4
	v_lshl_add_u64 v[0:1], v[0:1], 0, v[152:153]
	v_lshl_add_u64 v[2:3], s[10:11], 0, v[2:3]
	v_lshlrev_b64 v[4:5], 1, v[4:5]
	v_or_b32_e32 v10, 0x400, v14
	v_lshl_add_u64 v[2:3], v[2:3], 0, v[152:153]
	s_cmp_lg_u32 s33, 0
	s_cbranch_scc1 .Ldma_skip_56
	global_load_lds_dwordx4 v[0:1], off
	s_add_u32 m0, m0, 0x4000
	v_lshl_add_u64 v[220:221], v[0:1], 0, s[100:101]
	global_load_lds_dwordx4 v[220:221], off
.Ldma_skip_56:
	s_mov_b32 m0, s39
	v_lshl_add_u64 v[6:7], v[0:1], 0, v[4:5]
	v_readfirstlane_b32 s39, v10
	s_cmp_lg_u32 s33, 0
	s_cbranch_scc1 .Ldma_skip_57
	global_load_lds_dwordx4 v[2:3], off
	s_add_u32 m0, m0, 0x4000
	v_lshl_add_u64 v[220:221], v[2:3], 0, s[100:101]
	global_load_lds_dwordx4 v[220:221], off
.Ldma_skip_57:
	v_lshl_add_u64 v[8:9], v[6:7], 0, s[12:13]
	s_mov_b32 m0, s39
	v_add_u32_e32 v15, 0x8400, v14
	s_cmp_lg_u32 s33, 0
	s_cbranch_scc1 .Ldma_skip_58
	global_load_lds_dwordx4 v[8:9], off
	s_add_u32 m0, m0, 0x4000
	v_lshl_add_u64 v[220:221], v[8:9], 0, s[100:101]
	global_load_lds_dwordx4 v[220:221], off
.Ldma_skip_58:
	v_lshl_add_u64 v[8:9], v[2:3], 0, v[4:5]
	v_readfirstlane_b32 s39, v15
	v_lshl_add_u64 v[10:11], v[8:9], 0, s[12:13]
	s_mov_b32 m0, s39
	v_lshl_add_u64 v[0:1], v[0:1], 0, s[14:15]
	s_cmp_lg_u32 s33, 0
	s_cbranch_scc1 .Ldma_skip_59
	global_load_lds_dwordx4 v[10:11], off
	s_add_u32 m0, m0, 0x4000
	v_lshl_add_u64 v[220:221], v[10:11], 0, s[100:101]
	global_load_lds_dwordx4 v[220:221], off
.Ldma_skip_59:
	v_or_b32_e32 v10, 0x800, v14
	s_mov_b64 s[40:41], 0
	v_readfirstlane_b32 s39, v10
	s_mov_b32 m0, s39
	s_nop 0
	s_cmp_lg_u32 s33, 0
	s_cbranch_scc1 .Ldma_skip_60
	global_load_lds_dwordx4 v[0:1], off
	s_add_u32 m0, m0, 0x4000
	v_lshl_add_u64 v[220:221], v[0:1], 0, s[100:101]
	global_load_lds_dwordx4 v[220:221], off
.Ldma_skip_60:
	v_lshl_add_u64 v[0:1], v[2:3], 0, s[14:15]
	v_add_u32_e32 v2, 0x8800, v14
	s_nop 0
	v_readfirstlane_b32 s39, v2
	v_or_b32_e32 v2, 0xc00, v14
	s_mov_b32 m0, s39
	v_readfirstlane_b32 s39, v2
	v_add_u32_e32 v2, 0x8c00, v14
	s_cmp_lg_u32 s33, 0
	s_cbranch_scc1 .Ldma_skip_61
	global_load_lds_dwordx4 v[0:1], off
	s_add_u32 m0, m0, 0x4000
	v_lshl_add_u64 v[220:221], v[0:1], 0, s[100:101]
	global_load_lds_dwordx4 v[220:221], off
.Ldma_skip_61:
	v_lshl_add_u64 v[0:1], v[6:7], 0, s[16:17]
	s_mov_b32 m0, s39
	v_readfirstlane_b32 s39, v2
	s_cmp_lg_u32 s33, 0
	s_cbranch_scc1 .Ldma_skip_62
	global_load_lds_dwordx4 v[0:1], off
	s_add_u32 m0, m0, 0x4000
	v_lshl_add_u64 v[220:221], v[0:1], 0, s[100:101]
	global_load_lds_dwordx4 v[220:221], off
.Ldma_skip_62:
	v_lshl_add_u64 v[0:1], v[8:9], 0, s[16:17]
	s_mov_b32 m0, s39
	s_mov_b32 s39, 0x10000
	s_cmp_lg_u32 s33, 0
	s_cbranch_scc1 .Ldma_skip_63
	global_load_lds_dwordx4 v[0:1], off
	s_add_u32 m0, m0, 0x4000
	v_lshl_add_u64 v[220:221], v[0:1], 0, s[100:101]
	global_load_lds_dwordx4 v[220:221], off
.Ldma_skip_63:
	v_mov_b32_e32 v0, v158
	s_nop 0
	v_and_b32_e32 v1, 15, v0
	v_lshrrev_b32_e32 v2, 4, v0
	v_bfe_u32 v6, v0, 1, 3
	v_bfe_u32 v3, v0, 4, 2
	v_lshlrev_b32_e32 v1, 7, v1
	v_bitop3_b32 v2, v2, v6, 3 bitop3:0x6c
	v_lshl_or_b32 v137, v2, 4, v1
	v_bitop3_b32 v2, v3, v6, 4 bitop3:0x36
	v_lshl_or_b32 v136, v2, 4, v1
	v_lshlrev_b32_e32 v1, 7, v0
	v_lshlrev_b32_e32 v0, 6, v0
	v_and_b32_e32 v138, 0xffffc000, v0
	v_or_b32_e32 v0, s47, v13
	v_add_u32_e32 v0, v0, v12
	v_or_b32_e32 v2, s38, v13
	v_and_b32_e32 v139, 0x6000, v1
	v_ashrrev_i32_e32 v1, 31, v0
	v_add_u32_e32 v2, v2, v12
	v_lshlrev_b64 v[0:1], 11, v[0:1]
	v_ashrrev_i32_e32 v3, 31, v2
	v_or_b32_e32 v0, v0, v152
	v_lshlrev_b64 v[2:3], 11, v[2:3]
	v_lshl_add_u64 v[128:129], s[6:7], 0, v[0:1]
	v_or_b32_e32 v2, v2, v152
	v_lshl_add_u64 v[0:1], v[0:1], 0, v[4:5]
	v_lshl_add_u64 v[132:133], s[6:7], 0, v[0:1]
	v_lshl_add_u64 v[0:1], v[2:3], 0, v[4:5]
	v_lshl_add_u64 v[134:135], s[6:7], 0, v[0:1]
	v_mov_b32_e32 v0, 0
	v_lshl_add_u64 v[130:131], s[6:7], 0, v[2:3]
	v_mov_b32_e32 v1, v0
	v_mov_b32_e32 v2, v0
	v_mov_b32_e32 v3, v0
	v_mov_b32_e32 v4, v0
	v_mov_b32_e32 v5, v0
	v_mov_b32_e32 v6, v0
	v_mov_b32_e32 v7, v0
	v_mov_b32_e32 v8, v0
	v_mov_b32_e32 v9, v0
	v_mov_b32_e32 v10, v0
	v_mov_b32_e32 v11, v0
	v_mov_b32_e32 v12, v0
	v_mov_b32_e32 v13, v0
	v_mov_b32_e32 v14, v0
	v_mov_b32_e32 v15, v0
	v_mov_b32_e32 v16, v0
	v_mov_b32_e32 v17, v0
	v_mov_b32_e32 v18, v0
	v_mov_b32_e32 v19, v0
	v_mov_b32_e32 v20, v0
	v_mov_b32_e32 v21, v0
	v_mov_b32_e32 v22, v0
	v_mov_b32_e32 v23, v0
	v_mov_b32_e32 v24, v0
	v_mov_b32_e32 v25, v0
	v_mov_b32_e32 v26, v0
	v_mov_b32_e32 v27, v0
	v_mov_b32_e32 v28, v0
	v_mov_b32_e32 v29, v0
	v_mov_b32_e32 v30, v0
	v_mov_b32_e32 v31, v0
	v_mov_b32_e32 v32, v0
	v_mov_b32_e32 v33, v0
	v_mov_b32_e32 v34, v0
	v_mov_b32_e32 v35, v0
	v_mov_b32_e32 v36, v0
	v_mov_b32_e32 v37, v0
	v_mov_b32_e32 v38, v0
; __device__ __forceinline__ f32x4 mfma16(bf16x8 a, bf16x8 b, f32x4 c) { return __builtin_amdgcn_mfma_f32_16x16x32_bf16(a, b, c, 0, 0, 0); }
; __device__ __forceinline__ void gemm_mainloop(f32x4 (&acc)[8][4], const GemmSrc& g, int K, char* lds) {
;     ...
;     for (int kt = 0; kt < KT; kt++) {
;         WAIT_V(0);
;         __builtin_amdgcn_s_barrier();
;         const char* st = lds + (kt & 1) * 65536;
;         bf16x8 afA[4], afB[4], bX[4], bY[4];
; #pragma unroll
;         for (int ni = 0; ni < 4; ni++) afA[ni] = *(const bf16x8*)(st + woff + ni * 16 * 128 + rdo0);
; #pragma unroll
;         for (int mi = 0; mi < 4; mi++) bX[mi] = *(const bf16x8*)(st + xoff + mi * 16 * 128 + rdo0);
;         if (kt + 1 < KT) gemm_issue(g, kt + 1, (kt + 1) & 1, lds);
; #pragma unroll
;         for (int mi = 0; mi < 4; mi++) bY[mi] = *(const bf16x8*)(st + xoff + (4 + mi) * 16 * 128 + rdo0);
; #pragma unroll
;         for (int ni = 0; ni < 4; ni++) afB[ni] = *(const bf16x8*)(st + woff + ni * 16 * 128 + rdo1);
; #pragma unroll
;         for (int mi = 0; mi < 4; mi++)
; #pragma unroll
;             for (int ni = 0; ni < 4; ni++) acc[mi][ni] = mfma16(afA[ni], bX[mi], acc[mi][ni]);
;         __builtin_amdgcn_sched_barrier(0);
; #pragma unroll
;         for (int mi = 0; mi < 4; mi++) bX[mi] = *(const bf16x8*)(st + xoff + mi * 16 * 128 + rdo1);
; #pragma unroll
;         for (int mi = 0; mi < 4; mi++)
; #pragma unroll
;             for (int ni = 0; ni < 4; ni++) acc[4 + mi][ni] = mfma16(afA[ni], bY[mi], acc[4 + mi][ni]);
;         __builtin_amdgcn_sched_barrier(0);
; #pragma unroll
;         for (int mi = 0; mi < 4; mi++) bY[mi] = *(const bf16x8*)(st + xoff + (4 + mi) * 16 * 128 + rdo1);
; #pragma unroll
;         for (int mi = 0; mi < 4; mi++)
; #pragma unroll
;             for (int ni = 0; ni < 4; ni++) acc[mi][ni] = mfma16(afB[ni], bX[mi], acc[mi][ni]);
;         __builtin_amdgcn_sched_barrier(0);
; #pragma unroll
;         for (int mi = 0; mi < 4; mi++)
; #pragma unroll
;             for (int ni = 0; ni < 4; ni++) acc[4 + mi][ni] = mfma16(afB[ni], bY[mi], acc[4 + mi][ni]);
;         __builtin_amdgcn_sched_barrier(0);
;     }
; __device__ __forceinline__ void zero_acc(f32x4 (&acc)[8][4]) {
; #pragma unroll
;     for (int a = 0; a < 8; a++)
; #pragma unroll
;         for (int b = 0; b < 4; b++) acc[a][b] = (f32x4){0.f, 0.f, 0.f, 0.f};
; }
	v_mov_b32_e32 v39, v0
	v_mov_b32_e32 v40, v0
	v_mov_b32_e32 v41, v0
	v_mov_b32_e32 v42, v0
	v_mov_b32_e32 v43, v0
	v_mov_b32_e32 v44, v0
	v_mov_b32_e32 v45, v0
	v_mov_b32_e32 v46, v0
	v_mov_b32_e32 v47, v0
	v_mov_b32_e32 v48, v0
	v_mov_b32_e32 v49, v0
	v_mov_b32_e32 v50, v0
	v_mov_b32_e32 v51, v0
	v_mov_b32_e32 v52, v0
	v_mov_b32_e32 v53, v0
	v_mov_b32_e32 v54, v0
	v_mov_b32_e32 v55, v0
	v_mov_b32_e32 v56, v0
	v_mov_b32_e32 v57, v0
	v_mov_b32_e32 v58, v0
	v_mov_b32_e32 v59, v0
	v_mov_b32_e32 v60, v0
	v_mov_b32_e32 v61, v0
	v_mov_b32_e32 v62, v0
	v_mov_b32_e32 v63, v0
	v_mov_b32_e32 v64, v0
	v_mov_b32_e32 v65, v0
	v_mov_b32_e32 v66, v0
	v_mov_b32_e32 v67, v0
	v_mov_b32_e32 v68, v0
	v_mov_b32_e32 v69, v0
	v_mov_b32_e32 v70, v0
	v_mov_b32_e32 v71, v0
	v_mov_b32_e32 v72, v0
	v_mov_b32_e32 v73, v0
	v_mov_b32_e32 v74, v0
	v_mov_b32_e32 v75, v0
	v_mov_b32_e32 v76, v0
	v_mov_b32_e32 v77, v0
	v_mov_b32_e32 v78, v0
	v_mov_b32_e32 v79, v0
	v_mov_b32_e32 v80, v0
	v_mov_b32_e32 v81, v0
	v_mov_b32_e32 v82, v0
	v_mov_b32_e32 v83, v0
	v_mov_b32_e32 v84, v0
	v_mov_b32_e32 v85, v0
	v_mov_b32_e32 v86, v0
	v_mov_b32_e32 v87, v0
	v_mov_b32_e32 v88, v0
	v_mov_b32_e32 v89, v0
	v_mov_b32_e32 v90, v0
	v_mov_b32_e32 v91, v0
	v_mov_b32_e32 v92, v0
	v_mov_b32_e32 v93, v0
	v_mov_b32_e32 v94, v0
	v_mov_b32_e32 v95, v0
	v_mov_b32_e32 v96, v0
	v_mov_b32_e32 v97, v0
	v_mov_b32_e32 v98, v0
	v_mov_b32_e32 v99, v0
	v_mov_b32_e32 v100, v0
	v_mov_b32_e32 v101, v0
	v_mov_b32_e32 v102, v0
	v_mov_b32_e32 v103, v0
	v_mov_b32_e32 v104, v0
	v_mov_b32_e32 v105, v0
	v_mov_b32_e32 v106, v0
	v_mov_b32_e32 v107, v0
	v_mov_b32_e32 v108, v0
	v_mov_b32_e32 v109, v0
	v_mov_b32_e32 v110, v0
	v_mov_b32_e32 v111, v0
	v_mov_b32_e32 v112, v0
	v_mov_b32_e32 v113, v0
	v_mov_b32_e32 v114, v0
	v_mov_b32_e32 v115, v0
	v_mov_b32_e32 v116, v0
	v_mov_b32_e32 v117, v0
	v_mov_b32_e32 v118, v0
	v_mov_b32_e32 v119, v0
	v_mov_b32_e32 v120, v0
	v_mov_b32_e32 v121, v0
	v_mov_b32_e32 v122, v0
	v_mov_b32_e32 v123, v0
	v_mov_b32_e32 v124, v0
	v_mov_b32_e32 v125, v0
	v_mov_b32_e32 v126, v0
	v_mov_b32_e32 v127, v0
.LBB0_787:
	s_add_i32 s48, s39, 0xffff0000
	s_and_b32 s48, s48, 0x10000
	v_or_b32_e32 v152, s48, v139
	v_add_u32_e32 v200, s48, v138
	v_add_u32_e32 v154, v152, v137
	v_add_u32_e32 v188, v200, v137
	v_mov_b32_e32 v180, v158
	s_waitcnt vmcnt(0)
	s_barrier
	ds_read_b128 v[140:143], v154 offset:32768
	ds_read_b128 v[144:147], v154 offset:34816
	ds_read_b128 v[148:151], v154 offset:36864
	ds_read_b128 v[154:157], v154 offset:38912
	ds_read_b128 v[164:167], v188
	ds_read_b128 v[168:171], v188 offset:2048
	ds_read_b128 v[172:175], v188 offset:4096
	ds_read_b128 v[176:179], v188 offset:6144
	s_and_b32 s48, s39, 0x10000
	v_lshlrev_b32_e32 v181, 6, v180
	v_and_b32_e32 v181, 0xfffff000, v181
	v_add_u32_e32 v181, s48, v181
	v_lshlrev_b32_e32 v180, 4, v180
	v_and_or_b32 v189, v180, s3, v181
	v_lshl_add_u64 v[180:181], v[128:129], 0, s[40:41]
	v_readfirstlane_b32 s48, v189
	v_add_u32_e32 v186, 0x8000, v189
	v_lshl_add_u64 v[182:183], v[180:181], 0, s[18:19]
	s_mov_b32 m0, s48
	v_readfirstlane_b32 s48, v186
	s_cmp_lg_u32 s33, 0
	s_cbranch_scc1 .Ldma_skip_64
	global_load_lds_dwordx4 v[182:183], off
	s_add_u32 m0, m0, 0x4000
	v_lshl_add_u64 v[220:221], v[182:183], 0, s[100:101]
	global_load_lds_dwordx4 v[220:221], off
.Ldma_skip_64:
	v_lshl_add_u64 v[182:183], v[130:131], 0, s[40:41]
	v_lshl_add_u64 v[184:185], v[182:183], 0, s[20:21]
	s_mov_b32 m0, s48
	v_or_b32_e32 v190, 0x400, v189
	s_cmp_lg_u32 s33, 0
	s_cbranch_scc1 .Ldma_skip_65
	global_load_lds_dwordx4 v[184:185], off
	s_add_u32 m0, m0, 0x4000
	v_lshl_add_u64 v[220:221], v[184:185], 0, s[100:101]
	global_load_lds_dwordx4 v[220:221], off
.Ldma_skip_65:
	v_lshl_add_u64 v[184:185], v[132:133], 0, s[40:41]
	v_readfirstlane_b32 s48, v190
	s_waitcnt lgkmcnt(0)
	v_mfma_f32_16x16x32_bf16 v[124:127], v[140:143], v[164:167], v[124:127]
	v_lshl_add_u64 v[186:187], v[184:185], 0, s[22:23]
	s_mov_b32 m0, s48
	v_add_u32_e32 v152, v152, v136
	v_mfma_f32_16x16x32_bf16 v[120:123], v[144:147], v[164:167], v[120:123]
	s_cmp_lg_u32 s33, 0
	s_cbranch_scc1 .Ldma_skip_66
	global_load_lds_dwordx4 v[186:187], off
	s_add_u32 m0, m0, 0x4000
	v_lshl_add_u64 v[220:221], v[186:187], 0, s[100:101]
	global_load_lds_dwordx4 v[220:221], off
.Ldma_skip_66:
	v_lshl_add_u64 v[186:187], v[134:135], 0, s[40:41]
	v_mfma_f32_16x16x32_bf16 v[116:119], v[148:151], v[164:167], v[116:119]
	v_mfma_f32_16x16x32_bf16 v[112:115], v[154:157], v[164:167], v[112:115]
	v_add_u32_e32 v166, 0x8400, v189
	v_lshl_add_u64 v[164:165], v[186:187], 0, s[24:25]
	v_readfirstlane_b32 s48, v166
	v_or_b32_e32 v166, 0x800, v189
	s_mov_b32 m0, s48
	v_readfirstlane_b32 s48, v166
	v_add_u32_e32 v166, 0x8800, v189
	s_cmp_lg_u32 s33, 0
	s_cbranch_scc1 .Ldma_skip_67
	global_load_lds_dwordx4 v[164:165], off
	s_add_u32 m0, m0, 0x4000
	v_lshl_add_u64 v[220:221], v[164:165], 0, s[100:101]
	global_load_lds_dwordx4 v[220:221], off
.Ldma_skip_67:
	v_lshl_add_u64 v[164:165], v[180:181], 0, s[26:27]
	s_mov_b32 m0, s48
	v_readfirstlane_b32 s48, v166
	v_or_b32_e32 v166, 0xc00, v189
	s_cmp_lg_u32 s33, 0
	s_cbranch_scc1 .Ldma_skip_68
	global_load_lds_dwordx4 v[164:165], off
	s_add_u32 m0, m0, 0x4000
	v_lshl_add_u64 v[220:221], v[164:165], 0, s[100:101]
	global_load_lds_dwordx4 v[220:221], off
.Ldma_skip_68:
	v_lshl_add_u64 v[164:165], v[182:183], 0, s[28:29]
	s_mov_b32 m0, s48
	v_readfirstlane_b32 s48, v166
	v_add_u32_e32 v166, 0x8c00, v189
	s_cmp_lg_u32 s33, 0
	s_cbranch_scc1 .Ldma_skip_69
	global_load_lds_dwordx4 v[164:165], off
	s_add_u32 m0, m0, 0x4000
	v_lshl_add_u64 v[220:221], v[164:165], 0, s[100:101]
	global_load_lds_dwordx4 v[220:221], off
; __device__ __forceinline__ f32x4 mfma16(bf16x8 a, bf16x8 b, f32x4 c) { return __builtin_amdgcn_mfma_f32_16x16x32_bf16(a, b, c, 0, 0, 0); }
; #define WAIT_V(n) asm volatile("s_waitcnt vmcnt(" #n ")" ::: "memory")
; __device__ __forceinline__ void gemm_mainloop(f32x4 (&acc)[8][4], const GemmSrc& g, int K, char* lds) {
;     ...
;     for (int kt = 0; kt < KT; kt++) {
;         WAIT_V(0);
;         __builtin_amdgcn_s_barrier();
;         const char* st = lds + (kt & 1) * 65536;
;         bf16x8 afA[4], afB[4], bX[4], bY[4];
; #pragma unroll
;         for (int ni = 0; ni < 4; ni++) afA[ni] = *(const bf16x8*)(st + woff + ni * 16 * 128 + rdo0);
; #pragma unroll
;         for (int mi = 0; mi < 4; mi++) bX[mi] = *(const bf16x8*)(st + xoff + mi * 16 * 128 + rdo0);
;         if (kt + 1 < KT) gemm_issue(g, kt + 1, (kt + 1) & 1, lds);
; #pragma unroll
;         for (int mi = 0; mi < 4; mi++) bY[mi] = *(const bf16x8*)(st + xoff + (4 + mi) * 16 * 128 + rdo0);
; #pragma unroll
;         for (int ni = 0; ni < 4; ni++) afB[ni] = *(const bf16x8*)(st + woff + ni * 16 * 128 + rdo1);
; #pragma unroll
;         for (int mi = 0; mi < 4; mi++)
; #pragma unroll
;             for (int ni = 0; ni < 4; ni++) acc[mi][ni] = mfma16(afA[ni], bX[mi], acc[mi][ni]);
;         __builtin_amdgcn_sched_barrier(0);
; #pragma unroll
;         for (int mi = 0; mi < 4; mi++) bX[mi] = *(const bf16x8*)(st + xoff + mi * 16 * 128 + rdo1);
; #pragma unroll
;         for (int mi = 0; mi < 4; mi++)
; #pragma unroll
;             for (int ni = 0; ni < 4; ni++) acc[4 + mi][ni] = mfma16(afA[ni], bY[mi], acc[4 + mi][ni]);
;         __builtin_amdgcn_sched_barrier(0);
; #pragma unroll
;         for (int mi = 0; mi < 4; mi++) bY[mi] = *(const bf16x8*)(st + xoff + (4 + mi) * 16 * 128 + rdo1);
; #pragma unroll
;         for (int mi = 0; mi < 4; mi++)
; #pragma unroll
;             for (int ni = 0; ni < 4; ni++) acc[mi][ni] = mfma16(afB[ni], bX[mi], acc[mi][ni]);
;         __builtin_amdgcn_sched_barrier(0);
; #pragma unroll
;         for (int mi = 0; mi < 4; mi++)
; #pragma unroll
;             for (int ni = 0; ni < 4; ni++) acc[4 + mi][ni] = mfma16(afB[ni], bY[mi], acc[4 + mi][ni]);
;         __builtin_amdgcn_sched_barrier(0);
;     }
.Ldma_skip_69:
	v_lshl_add_u64 v[164:165], v[184:185], 0, s[30:31]
	s_mov_b32 m0, s48
	v_readfirstlane_b32 s48, v166
	s_cmp_lg_u32 s33, 0
	s_cbranch_scc1 .Ldma_skip_70
	global_load_lds_dwordx4 v[164:165], off
	s_add_u32 m0, m0, 0x4000
	v_lshl_add_u64 v[220:221], v[164:165], 0, s[100:101]
	global_load_lds_dwordx4 v[220:221], off
.Ldma_skip_70:
	v_lshl_add_u64 v[164:165], v[186:187], 0, s[34:35]
	s_mov_b32 m0, s48
	v_mfma_f32_16x16x32_bf16 v[108:111], v[140:143], v[168:171], v[108:111]
	s_cmp_lg_u32 s33, 0
	s_cbranch_scc1 .Ldma_skip_71
	global_load_lds_dwordx4 v[164:165], off
	s_add_u32 m0, m0, 0x4000
	v_lshl_add_u64 v[220:221], v[164:165], 0, s[100:101]
	global_load_lds_dwordx4 v[220:221], off
.Ldma_skip_71:
	v_mfma_f32_16x16x32_bf16 v[104:107], v[144:147], v[168:171], v[104:107]
	v_mfma_f32_16x16x32_bf16 v[100:103], v[148:151], v[168:171], v[100:103]
	v_mfma_f32_16x16x32_bf16 v[96:99], v[154:157], v[168:171], v[96:99]
	ds_read_b128 v[164:167], v188 offset:8192
	ds_read_b128 v[168:171], v188 offset:10240
	v_mfma_f32_16x16x32_bf16 v[92:95], v[140:143], v[172:175], v[92:95]
	v_mfma_f32_16x16x32_bf16 v[88:91], v[144:147], v[172:175], v[88:91]
	v_mfma_f32_16x16x32_bf16 v[84:87], v[148:151], v[172:175], v[84:87]
	v_mfma_f32_16x16x32_bf16 v[80:83], v[154:157], v[172:175], v[80:83]
	ds_read_b128 v[172:175], v188 offset:12288
	ds_read_b128 v[180:183], v188 offset:14336
	ds_read_b128 v[184:187], v152 offset:32768
	ds_read_b128 v[188:191], v152 offset:34816
	ds_read_b128 v[192:195], v152 offset:36864
	ds_read_b128 v[196:199], v152 offset:38912
	v_mfma_f32_16x16x32_bf16 v[76:79], v[140:143], v[176:179], v[76:79]
	v_mfma_f32_16x16x32_bf16 v[72:75], v[144:147], v[176:179], v[72:75]
	v_mfma_f32_16x16x32_bf16 v[68:71], v[148:151], v[176:179], v[68:71]
	v_mfma_f32_16x16x32_bf16 v[64:67], v[154:157], v[176:179], v[64:67]
	v_add_u32_e32 v152, v200, v136
	s_waitcnt lgkmcnt(0)
	v_mfma_f32_16x16x32_bf16 v[60:63], v[140:143], v[164:167], v[60:63]
	v_mfma_f32_16x16x32_bf16 v[56:59], v[144:147], v[164:167], v[56:59]
	v_mfma_f32_16x16x32_bf16 v[52:55], v[148:151], v[164:167], v[52:55]
	v_mfma_f32_16x16x32_bf16 v[48:51], v[154:157], v[164:167], v[48:51]
	v_mfma_f32_16x16x32_bf16 v[44:47], v[140:143], v[168:171], v[44:47]
	v_mfma_f32_16x16x32_bf16 v[40:43], v[144:147], v[168:171], v[40:43]
	v_mfma_f32_16x16x32_bf16 v[36:39], v[148:151], v[168:171], v[36:39]
	v_mfma_f32_16x16x32_bf16 v[28:31], v[140:143], v[172:175], v[28:31]
	v_mfma_f32_16x16x32_bf16 v[24:27], v[144:147], v[172:175], v[24:27]
	v_mfma_f32_16x16x32_bf16 v[20:23], v[148:151], v[172:175], v[20:23]
	v_mfma_f32_16x16x32_bf16 v[12:15], v[140:143], v[180:183], v[12:15]
	v_mfma_f32_16x16x32_bf16 v[8:11], v[144:147], v[180:183], v[8:11]
	v_mfma_f32_16x16x32_bf16 v[4:7], v[148:151], v[180:183], v[4:7]
	ds_read_b128 v[140:143], v152
	ds_read_b128 v[144:147], v152 offset:2048
	ds_read_b128 v[148:151], v152 offset:4096
	ds_read_b128 v[164:167], v152 offset:6144
	v_mfma_f32_16x16x32_bf16 v[32:35], v[154:157], v[168:171], v[32:35]
	v_mfma_f32_16x16x32_bf16 v[16:19], v[154:157], v[172:175], v[16:19]
	v_mfma_f32_16x16x32_bf16 v[0:3], v[154:157], v[180:183], v[0:3]
	s_waitcnt lgkmcnt(0)
	v_mfma_f32_16x16x32_bf16 v[124:127], v[184:187], v[140:143], v[124:127]
	v_mfma_f32_16x16x32_bf16 v[120:123], v[188:191], v[140:143], v[120:123]
	v_mfma_f32_16x16x32_bf16 v[116:119], v[192:195], v[140:143], v[116:119]
	v_mfma_f32_16x16x32_bf16 v[112:115], v[196:199], v[140:143], v[112:115]
	v_mfma_f32_16x16x32_bf16 v[108:111], v[184:187], v[144:147], v[108:111]
	v_mfma_f32_16x16x32_bf16 v[104:107], v[188:191], v[144:147], v[104:107]
	v_mfma_f32_16x16x32_bf16 v[100:103], v[192:195], v[144:147], v[100:103]
	v_mfma_f32_16x16x32_bf16 v[96:99], v[196:199], v[144:147], v[96:99]
	v_mfma_f32_16x16x32_bf16 v[92:95], v[184:187], v[148:151], v[92:95]
	v_mfma_f32_16x16x32_bf16 v[88:91], v[188:191], v[148:151], v[88:91]
	v_mfma_f32_16x16x32_bf16 v[84:87], v[192:195], v[148:151], v[84:87]
	v_mfma_f32_16x16x32_bf16 v[80:83], v[196:199], v[148:151], v[80:83]
	ds_read_b128 v[140:143], v152 offset:8192
	ds_read_b128 v[144:147], v152 offset:10240
	ds_read_b128 v[148:151], v152 offset:12288
	ds_read_b128 v[154:157], v152 offset:14336
	v_mfma_f32_16x16x32_bf16 v[76:79], v[184:187], v[164:167], v[76:79]
	v_mfma_f32_16x16x32_bf16 v[72:75], v[188:191], v[164:167], v[72:75]
	v_mfma_f32_16x16x32_bf16 v[68:71], v[192:195], v[164:167], v[68:71]
	v_mfma_f32_16x16x32_bf16 v[64:67], v[196:199], v[164:167], v[64:67]
	s_waitcnt lgkmcnt(0)
	v_mfma_f32_16x16x32_bf16 v[60:63], v[184:187], v[140:143], v[60:63]
	v_mfma_f32_16x16x32_bf16 v[56:59], v[188:191], v[140:143], v[56:59]
	v_mfma_f32_16x16x32_bf16 v[52:55], v[192:195], v[140:143], v[52:55]
	v_mfma_f32_16x16x32_bf16 v[48:51], v[196:199], v[140:143], v[48:51]
	v_mfma_f32_16x16x32_bf16 v[44:47], v[184:187], v[144:147], v[44:47]
	v_mfma_f32_16x16x32_bf16 v[40:43], v[188:191], v[144:147], v[40:43]
	v_mfma_f32_16x16x32_bf16 v[36:39], v[192:195], v[144:147], v[36:39]
	v_mfma_f32_16x16x32_bf16 v[32:35], v[196:199], v[144:147], v[32:35]
	v_mfma_f32_16x16x32_bf16 v[28:31], v[184:187], v[148:151], v[28:31]
	v_mfma_f32_16x16x32_bf16 v[24:27], v[188:191], v[148:151], v[24:27]
	v_mfma_f32_16x16x32_bf16 v[20:23], v[192:195], v[148:151], v[20:23]
	v_mfma_f32_16x16x32_bf16 v[16:19], v[196:199], v[148:151], v[16:19]
	v_mfma_f32_16x16x32_bf16 v[12:15], v[184:187], v[154:157], v[12:15]
	v_mfma_f32_16x16x32_bf16 v[8:11], v[188:191], v[154:157], v[8:11]
	v_mfma_f32_16x16x32_bf16 v[4:7], v[192:195], v[154:157], v[4:7]
	v_mfma_f32_16x16x32_bf16 v[0:3], v[196:199], v[154:157], v[0:3]
	s_add_u32 s40, s40, 0x80
	s_addc_u32 s41, s41, 0
	s_add_i32 s39, s39, 0x10000
	s_cmpk_lg_i32 s40, 0x780
	s_cbranch_scc1 .LBB0_787
; __device__ __forceinline__ void gemm_mainloop(f32x4 (&acc)[8][4], const GemmSrc& g, int K, char* lds) {
;     ...
;     for (int kt = 0; kt < KT; kt++) {
;         WAIT_V(0);
;         __builtin_amdgcn_s_barrier();
;         const char* st = lds + (kt & 1) * 65536;
;         bf16x8 afA[4], afB[4], bX[4], bY[4];
; #pragma unroll
;         for (int ni = 0; ni < 4; ni++) afA[ni] = *(const bf16x8*)(st + woff + ni * 16 * 128 + rdo0);
; #pragma unroll
;         for (int mi = 0; mi < 4; mi++) bX[mi] = *(const bf16x8*)(st + xoff + mi * 16 * 128 + rdo0);
;         if (kt + 1 < KT) gemm_issue(g, kt + 1, (kt + 1) & 1, lds);
; #pragma unroll
;         for (int mi = 0; mi < 4; mi++) bY[mi] = *(const bf16x8*)(st + xoff + (4 + mi) * 16 * 128 + rdo0);
; #pragma unroll
;         for (int ni = 0; ni < 4; ni++) afB[ni] = *(const bf16x8*)(st + woff + ni * 16 * 128 + rdo1);
; #pragma unroll
;         for (int mi = 0; mi < 4; mi++)
; #pragma unroll
;             for (int ni = 0; ni < 4; ni++) acc[mi][ni] = mfma16(afA[ni], bX[mi], acc[mi][ni]);
;         __builtin_amdgcn_sched_barrier(0);
; #pragma unroll
;         for (int mi = 0; mi < 4; mi++) bX[mi] = *(const bf16x8*)(st + xoff + mi * 16 * 128 + rdo1);
; #pragma unroll
;         for (int mi = 0; mi < 4; mi++)
; #pragma unroll
;             for (int ni = 0; ni < 4; ni++) acc[4 + mi][ni] = mfma16(afA[ni], bY[mi], acc[4 + mi][ni]);
;         __builtin_amdgcn_sched_barrier(0);
; #pragma unroll
;         for (int mi = 0; mi < 4; mi++) bY[mi] = *(const bf16x8*)(st + xoff + (4 + mi) * 16 * 128 + rdo1);
; #pragma unroll
;         for (int mi = 0; mi < 4; mi++)
; #pragma unroll
;             for (int ni = 0; ni < 4; ni++) acc[mi][ni] = mfma16(afB[ni], bX[mi], acc[mi][ni]);
;         __builtin_amdgcn_sched_barrier(0);
; #pragma unroll
;         for (int mi = 0; mi < 4; mi++)
; #pragma unroll
;             for (int ni = 0; ni < 4; ni++) acc[4 + mi][ni] = mfma16(afB[ni], bY[mi], acc[4 + mi][ni]);
;         __builtin_amdgcn_sched_barrier(0);
;     }
; }
; __device__ __forceinline__ void gemm_core(f32x4 (&acc)[8][4], const bf16_t* __restrict__ X, int ldx, const bf16_t* __restrict__ W, int ldw,
;                                           int K, int m0, int n0, char* lds) {
;     const GemmSrc g = gemm_src(X, ldx, W, ldw, m0, n0);
;     gemm_prologue(g, lds);
;     gemm_mainloop(acc, g, K, lds);
;     __syncthreads();
	v_or_b32_e32 v150, 0x8000, v139
	v_add_u32_e32 v152, 0x10000, v138
	v_add3_u32 v151, v150, v137, s44
	v_add_u32_e32 v137, v152, v137
	s_waitcnt vmcnt(0)
	s_barrier
	ds_read_b128 v[128:131], v151
	ds_read_b128 v[132:135], v151 offset:2048
	ds_read_b128 v[138:141], v137
	ds_read_b128 v[142:145], v137 offset:2048
	ds_read_b128 v[146:149], v151 offset:4096
	ds_read_b128 v[154:157], v151 offset:6144
	s_waitcnt lgkmcnt(0)
	v_mfma_f32_16x16x32_bf16 v[124:127], v[128:131], v[138:141], v[124:127]
	v_mfma_f32_16x16x32_bf16 v[120:123], v[132:135], v[138:141], v[120:123]
	v_mfma_f32_16x16x32_bf16 v[116:119], v[146:149], v[138:141], v[116:119]
	v_mfma_f32_16x16x32_bf16 v[112:115], v[154:157], v[138:141], v[112:115]
	v_mfma_f32_16x16x32_bf16 v[108:111], v[128:131], v[142:145], v[108:111]
	v_mfma_f32_16x16x32_bf16 v[104:107], v[132:135], v[142:145], v[104:107]
	v_mfma_f32_16x16x32_bf16 v[100:103], v[146:149], v[142:145], v[100:103]
	v_mfma_f32_16x16x32_bf16 v[96:99], v[154:157], v[142:145], v[96:99]
	ds_read_b128 v[138:141], v137 offset:4096
	ds_read_b128 v[142:145], v137 offset:6144
	s_waitcnt lgkmcnt(0)
	v_mfma_f32_16x16x32_bf16 v[92:95], v[128:131], v[138:141], v[92:95]
	v_mfma_f32_16x16x32_bf16 v[88:91], v[132:135], v[138:141], v[88:91]
	v_mfma_f32_16x16x32_bf16 v[84:87], v[146:149], v[138:141], v[84:87]
	v_mfma_f32_16x16x32_bf16 v[80:83], v[154:157], v[138:141], v[80:83]
	v_add3_u32 v138, v150, v136, s44
	ds_read_b128 v[164:167], v138 offset:6144
	ds_read_b128 v[168:171], v138 offset:4096
	ds_read_b128 v[172:175], v138 offset:2048
	ds_read_b128 v[176:179], v138
	ds_read_b128 v[138:141], v137 offset:14336
	ds_read_b128 v[180:183], v137 offset:12288
	ds_read_b128 v[184:187], v137 offset:10240
	ds_read_b128 v[188:191], v137 offset:8192
	v_mfma_f32_16x16x32_bf16 v[76:79], v[128:131], v[142:145], v[76:79]
	v_mfma_f32_16x16x32_bf16 v[72:75], v[132:135], v[142:145], v[72:75]
	v_mfma_f32_16x16x32_bf16 v[68:71], v[146:149], v[142:145], v[68:71]
	v_mfma_f32_16x16x32_bf16 v[192:195], v[154:157], v[142:145], v[64:67]
	v_add_u32_e32 v152, v152, v136
	s_waitcnt lgkmcnt(0)
	v_mfma_f32_16x16x32_bf16 v[52:55], v[146:149], v[188:191], v[52:55]
	v_mfma_f32_16x16x32_bf16 v[36:39], v[146:149], v[184:187], v[36:39]
	v_mfma_f32_16x16x32_bf16 v[28:31], v[128:131], v[180:183], v[28:31]
	v_mfma_f32_16x16x32_bf16 v[24:27], v[132:135], v[180:183], v[24:27]
	v_mfma_f32_16x16x32_bf16 v[20:23], v[146:149], v[180:183], v[20:23]
	v_mfma_f32_16x16x32_bf16 v[16:19], v[154:157], v[180:183], v[16:19]
	v_mfma_f32_16x16x32_bf16 v[4:7], v[146:149], v[138:141], v[4:7]
	ds_read_b128 v[64:67], v152
	ds_read_b128 v[144:147], v152 offset:2048
	ds_read_b128 v[148:151], v152 offset:4096
	ds_read_b128 v[180:183], v152 offset:6144
	v_mfma_f32_16x16x32_bf16 v[0:3], v[154:157], v[138:141], v[0:3]
	v_mfma_f32_16x16x32_bf16 v[60:63], v[128:131], v[188:191], v[60:63]
	v_mfma_f32_16x16x32_bf16 v[56:59], v[132:135], v[188:191], v[56:59]
	v_mfma_f32_16x16x32_bf16 v[48:51], v[154:157], v[188:191], v[48:51]
	v_mfma_f32_16x16x32_bf16 v[44:47], v[128:131], v[184:187], v[44:47]
	v_mfma_f32_16x16x32_bf16 v[40:43], v[132:135], v[184:187], v[40:43]
	v_mfma_f32_16x16x32_bf16 v[32:35], v[154:157], v[184:187], v[32:35]
	v_mfma_f32_16x16x32_bf16 v[12:15], v[128:131], v[138:141], v[12:15]
	v_mfma_f32_16x16x32_bf16 v[8:11], v[132:135], v[138:141], v[8:11]
	s_waitcnt lgkmcnt(0)
	v_mfma_f32_16x16x32_bf16 v[140:143], v[176:179], v[64:67], v[124:127]
	v_mfma_f32_16x16x32_bf16 v[136:139], v[172:175], v[64:67], v[120:123]
	v_mfma_f32_16x16x32_bf16 v[132:135], v[168:171], v[64:67], v[116:119]
	v_mfma_f32_16x16x32_bf16 v[128:131], v[164:167], v[64:67], v[112:115]
	v_mfma_f32_16x16x32_bf16 v[124:127], v[176:179], v[144:147], v[108:111]
	v_mfma_f32_16x16x32_bf16 v[120:123], v[172:175], v[144:147], v[104:107]
	v_mfma_f32_16x16x32_bf16 v[116:119], v[168:171], v[144:147], v[100:103]
	v_mfma_f32_16x16x32_bf16 v[112:115], v[164:167], v[144:147], v[96:99]
	v_mfma_f32_16x16x32_bf16 v[108:111], v[176:179], v[148:151], v[92:95]
	v_mfma_f32_16x16x32_bf16 v[104:107], v[172:175], v[148:151], v[88:91]
	v_mfma_f32_16x16x32_bf16 v[100:103], v[168:171], v[148:151], v[84:87]
	v_mfma_f32_16x16x32_bf16 v[96:99], v[164:167], v[148:151], v[80:83]
	v_mfma_f32_16x16x32_bf16 v[92:95], v[176:179], v[180:183], v[76:79]
	v_mfma_f32_16x16x32_bf16 v[80:83], v[172:175], v[180:183], v[72:75]
	s_nop 2
	ds_read_b128 v[72:75], v152 offset:8192
	ds_read_b128 v[76:79], v152 offset:10240
	ds_read_b128 v[84:87], v152 offset:12288
	ds_read_b128 v[88:91], v152 offset:14336
	v_mfma_f32_16x16x32_bf16 v[64:67], v[168:171], v[180:183], v[68:71]
	v_mfma_f32_16x16x32_bf16 v[68:71], v[164:167], v[180:183], v[192:195]
	s_waitcnt lgkmcnt(0)
	v_mfma_f32_16x16x32_bf16 v[0:3], v[164:167], v[88:91], v[0:3]
	v_mfma_f32_16x16x32_bf16 v[60:63], v[176:179], v[72:75], v[60:63]
	v_mfma_f32_16x16x32_bf16 v[56:59], v[172:175], v[72:75], v[56:59]
	v_mfma_f32_16x16x32_bf16 v[52:55], v[168:171], v[72:75], v[52:55]
	v_mfma_f32_16x16x32_bf16 v[48:51], v[164:167], v[72:75], v[48:51]
	v_mfma_f32_16x16x32_bf16 v[44:47], v[176:179], v[76:79], v[44:47]
	v_mfma_f32_16x16x32_bf16 v[40:43], v[172:175], v[76:79], v[40:43]
	v_mfma_f32_16x16x32_bf16 v[36:39], v[168:171], v[76:79], v[36:39]
	v_mfma_f32_16x16x32_bf16 v[32:35], v[164:167], v[76:79], v[32:35]
	v_mfma_f32_16x16x32_bf16 v[28:31], v[176:179], v[84:87], v[28:31]
	v_mfma_f32_16x16x32_bf16 v[24:27], v[172:175], v[84:87], v[24:27]
	v_mfma_f32_16x16x32_bf16 v[20:23], v[168:171], v[84:87], v[20:23]
	v_mfma_f32_16x16x32_bf16 v[16:19], v[164:167], v[84:87], v[16:19]
	v_mfma_f32_16x16x32_bf16 v[12:15], v[176:179], v[88:91], v[12:15]
	v_mfma_f32_16x16x32_bf16 v[8:11], v[172:175], v[88:91], v[8:11]
	v_mfma_f32_16x16x32_bf16 v[4:7], v[168:171], v[88:91], v[4:7]
	v_add_u32_e32 v72, s47, v161
	s_waitcnt vmcnt(0)
	s_barrier
; __device__ __forceinline__ void epi_fill(char* lds, int wr, int wc, int r, int q, int mi, int ni, f32x4 v) {
;     *(u32x2*)(lds + (wr * 128 + mi * 16 + r) * EPI_ROWB + (wc * 64 + ni * 16 + 4 * q) * 2) = (u32x2){pack2(v[0], v[1]), pack2(v[2], v[3])};
; }
; __device__ void phaseM2(const Params& p, char* lds) {
;     ...
; #pragma unroll
;         for (int mi = 0; mi < 8; mi++)
; #pragma unroll
;             for (int ni = 0; ni < 4; ni++) {
;                 const int tok = m0 + wr * 128 + mi * 16 + r, col = n0 + wc * 64 + ni * 16 + 4 * q;
;                 const f32x4 xv = *(const f32x4*)(p.x + (size_t)tok * DM + col);
;                 const f32x4 gt = *(const f32x4*)(mod + (tok >> 11) * 6144 + 2 * 1024 + col);
;                 epi_fill(lds, wr, wc, r, q, mi, ni, xv + gt * acc[mi][ni]);
;             }
	v_or_b32_e32 v154, v72, v160
	v_ashrrev_i32_e32 v72, 11, v72
	s_load_dwordx2 s[40:41], s[8:9], 0x0
	v_mul_i32_i24_e32 v72, 0x1800, v72
	v_ashrrev_i32_e32 v73, 31, v72
	v_or_b32_e32 v84, s38, v162
	v_lshl_add_u64 v[72:73], v[72:73], 2, s[6:7]
	v_ashrrev_i32_e32 v155, 31, v154
	v_lshl_add_u64 v[86:87], v[72:73], 0, s[36:37]
	v_lshlrev_b64 v[72:73], 12, v[154:155]
	v_ashrrev_i32_e32 v85, 31, v84
	v_or_b32_e32 v74, 16, v84
	v_or_b32_e32 v144, 16, v154
	s_waitcnt lgkmcnt(0)
	v_lshl_add_u64 v[72:73], s[40:41], 0, v[72:73]
	v_lshlrev_b64 v[156:157], 2, v[84:85]
	v_ashrrev_i32_e32 v75, 31, v74
	v_or_b32_e32 v90, 32, v84
	v_or_b32_e32 v84, 48, v84
	v_ashrrev_i32_e32 v145, 31, v144
	v_lshl_add_u64 v[88:89], v[72:73], 0, v[156:157]
	v_lshl_add_u64 v[72:73], v[86:87], 0, v[156:157]
	v_lshl_add_u64 v[74:75], v[74:75], 2, v[86:87]
	v_ashrrev_i32_e32 v91, 31, v90
	v_ashrrev_i32_e32 v85, 31, v84
	v_lshlrev_b64 v[144:145], 12, v[144:145]
	global_load_dwordx4 v[164:167], v[88:89], off
	global_load_dwordx4 v[168:171], v[88:89], off offset:64
	global_load_dwordx4 v[76:79], v[72:73], off
	s_nop 0
	global_load_dwordx4 v[72:75], v[74:75], off
	v_lshl_add_u64 v[90:91], v[90:91], 2, v[86:87]
	v_lshl_add_u64 v[84:85], v[84:85], 2, v[86:87]
	v_lshl_add_u64 v[144:145], s[40:41], 0, v[144:145]
	global_load_dwordx4 v[172:175], v[88:89], off offset:128
	global_load_dwordx4 v[176:179], v[88:89], off offset:192
	s_nop 0
	global_load_dwordx4 v[88:91], v[90:91], off
	s_nop 0
	global_load_dwordx4 v[84:87], v[84:85], off
	v_lshl_add_u64 v[144:145], v[144:145], 0, v[156:157]
	global_load_dwordx4 v[180:183], v[144:145], off
	global_load_dwordx4 v[184:187], v[144:145], off offset:64
	global_load_dwordx4 v[188:191], v[144:145], off offset:128
	global_load_dwordx4 v[192:195], v[144:145], off offset:192
	v_or_b32_e32 v144, 32, v154
	v_ashrrev_i32_e32 v145, 31, v144
	v_lshlrev_b64 v[144:145], 12, v[144:145]
	v_lshl_add_u64 v[144:145], s[40:41], 0, v[144:145]
	v_lshl_add_u64 v[144:145], v[144:145], 0, v[156:157]
	global_load_dwordx4 v[196:199], v[144:145], off
	global_load_dwordx4 v[200:203], v[144:145], off offset:64
	v_or_b32_e32 v146, 48, v154
	global_load_dwordx4 v[204:207], v[144:145], off offset:128
	v_ashrrev_i32_e32 v147, 31, v146
	v_lshlrev_b64 v[146:147], 12, v[146:147]
	v_lshl_add_u64 v[146:147], s[40:41], 0, v[146:147]
	v_lshl_add_u64 v[146:147], v[146:147], 0, v[156:157]
	global_load_dwordx4 v[208:211], v[144:145], off offset:192
	global_load_dwordx4 v[212:215], v[146:147], off
	global_load_dwordx4 v[216:219], v[146:147], off offset:64
	global_load_dwordx4 v[148:151], v[146:147], off offset:128
	s_nop 0
	global_load_dwordx4 v[144:147], v[146:147], off offset:192
	v_or_b32_e32 v220, 64, v154
	v_ashrrev_i32_e32 v221, 31, v220
	v_add_u32_e32 v152, 0x4000, v163
	s_waitcnt vmcnt(17)
	v_pk_fma_f32 v[142:143], v[142:143], v[78:79], v[166:167]
	v_pk_fma_f32 v[140:141], v[140:141], v[76:77], v[164:165]
	s_waitcnt vmcnt(16)
	v_pk_fma_f32 v[138:139], v[138:139], v[74:75], v[170:171]
	v_pk_fma_f32 v[136:137], v[136:137], v[72:73], v[168:169]
	v_cvt_pk_bf16_f32 v140, v140, v141
	s_waitcnt vmcnt(11)
	v_pk_fma_f32 v[126:127], v[126:127], v[78:79], v[182:183]
	v_pk_fma_f32 v[124:125], v[124:125], v[76:77], v[180:181]
	s_waitcnt vmcnt(10)
	v_pk_fma_f32 v[120:121], v[120:121], v[72:73], v[184:185]
	v_pk_fma_f32 v[134:135], v[134:135], v[90:91], v[174:175]
	v_pk_fma_f32 v[132:133], v[132:133], v[88:89], v[172:173]
	v_pk_fma_f32 v[130:131], v[130:131], v[86:87], v[178:179]
	v_pk_fma_f32 v[128:129], v[128:129], v[84:85], v[176:177]
	v_cvt_pk_bf16_f32 v124, v124, v125
	v_cvt_pk_bf16_f32 v125, v126, v127
	v_cvt_pk_bf16_f32 v126, v120, v121
	v_lshlrev_b64 v[120:121], 12, v[220:221]
	v_pk_fma_f32 v[122:123], v[122:123], v[74:75], v[186:187]
	v_cvt_pk_bf16_f32 v141, v142, v143
	v_cvt_pk_bf16_f32 v136, v136, v137
	v_cvt_pk_bf16_f32 v137, v138, v139
	v_cvt_pk_bf16_f32 v132, v132, v133
	v_cvt_pk_bf16_f32 v133, v134, v135
	v_cvt_pk_bf16_f32 v128, v128, v129
	v_cvt_pk_bf16_f32 v129, v130, v131
	v_lshl_add_u64 v[120:121], s[40:41], 0, v[120:121]
	s_waitcnt vmcnt(9)
	v_pk_fma_f32 v[118:119], v[118:119], v[90:91], v[190:191]
	v_pk_fma_f32 v[116:117], v[116:117], v[88:89], v[188:189]
	v_cvt_pk_bf16_f32 v127, v122, v123
	ds_write2_b64 v163, v[140:141], v[136:137] offset1:4
	ds_write2_b64 v163, v[132:133], v[128:129] offset0:8 offset1:12
	v_lshl_add_u64 v[128:129], v[120:121], 0, v[156:157]
	v_add_u32_e32 v138, 0x2000, v163
	v_cvt_pk_bf16_f32 v132, v116, v117
	v_cvt_pk_bf16_f32 v133, v118, v119
	s_waitcnt vmcnt(8)
	v_pk_fma_f32 v[116:117], v[114:115], v[86:87], v[194:195]
	v_pk_fma_f32 v[118:119], v[112:113], v[84:85], v[192:193]
	global_load_dwordx4 v[120:123], v[128:129], off
	ds_write2_b64 v138, v[124:125], v[126:127] offset0:32 offset1:36
	global_load_dwordx4 v[124:127], v[128:129], off offset:64
	global_load_dwordx4 v[112:115], v[128:129], off offset:128
	v_cvt_pk_bf16_f32 v134, v118, v119
	v_cvt_pk_bf16_f32 v135, v116, v117
	global_load_dwordx4 v[116:119], v[128:129], off offset:192
	v_or_b32_e32 v128, 0x50, v154
	v_ashrrev_i32_e32 v129, 31, v128
	v_lshlrev_b64 v[128:129], 12, v[128:129]
	v_lshl_add_u64 v[128:129], s[40:41], 0, v[128:129]
	ds_write2_b64 v138, v[132:133], v[134:135] offset0:40 offset1:44
	s_waitcnt vmcnt(11)
	v_pk_fma_f32 v[132:133], v[110:111], v[78:79], v[198:199]
	v_lshl_add_u64 v[136:137], v[128:129], 0, v[156:157]
	v_pk_fma_f32 v[134:135], v[108:109], v[76:77], v[196:197]
	v_cvt_pk_bf16_f32 v141, v132, v133
	s_waitcnt vmcnt(10)
; __device__ __forceinline__ void epi_fill(char* lds, int wr, int wc, int r, int q, int mi, int ni, f32x4 v) {
;     *(u32x2*)(lds + (wr * 128 + mi * 16 + r) * EPI_ROWB + (wc * 64 + ni * 16 + 4 * q) * 2) = (u32x2){pack2(v[0], v[1]), pack2(v[2], v[3])};
; }
; __device__ void phaseM2(const Params& p, char* lds) {
;     ...
; #pragma unroll
;         for (int mi = 0; mi < 8; mi++)
; #pragma unroll
;             for (int ni = 0; ni < 4; ni++) {
;                 const int tok = m0 + wr * 128 + mi * 16 + r, col = n0 + wc * 64 + ni * 16 + 4 * q;
;                 const f32x4 xv = *(const f32x4*)(p.x + (size_t)tok * DM + col);
;                 const f32x4 gt = *(const f32x4*)(mod + (tok >> 11) * 6144 + 2 * 1024 + col);
;                 epi_fill(lds, wr, wc, r, q, mi, ni, xv + gt * acc[mi][ni]);
;             }
	v_pk_fma_f32 v[132:133], v[106:107], v[74:75], v[202:203]
	v_pk_fma_f32 v[104:105], v[104:105], v[72:73], v[200:201]
	global_load_dwordx4 v[128:131], v[136:137], off
	global_load_dwordx4 v[108:111], v[136:137], off offset:64
	v_cvt_pk_bf16_f32 v140, v134, v135
	v_cvt_pk_bf16_f32 v142, v104, v105
	global_load_dwordx4 v[104:107], v[136:137], off offset:128
	v_cvt_pk_bf16_f32 v143, v132, v133
	global_load_dwordx4 v[132:135], v[136:137], off offset:192
	v_or_b32_e32 v136, 0x60, v154
	v_ashrrev_i32_e32 v137, 31, v136
	ds_write2_b64 v152, v[140:141], v[142:143] offset0:64 offset1:68
	s_waitcnt vmcnt(13)
	v_pk_fma_f32 v[140:141], v[102:103], v[90:91], v[206:207]
	v_pk_fma_f32 v[142:143], v[100:101], v[88:89], v[204:205]
	v_or_b32_e32 v154, 0x70, v154
	v_lshlrev_b64 v[136:137], 12, v[136:137]
	v_cvt_pk_bf16_f32 v142, v142, v143
	v_cvt_pk_bf16_f32 v143, v140, v141
	s_waitcnt vmcnt(12)
	v_pk_fma_f32 v[140:141], v[98:99], v[86:87], v[210:211]
	v_pk_fma_f32 v[96:97], v[96:97], v[84:85], v[208:209]
	v_ashrrev_i32_e32 v155, 31, v154
	v_lshl_add_u64 v[136:137], s[40:41], 0, v[136:137]
	v_cvt_pk_bf16_f32 v166, v96, v97
	v_cvt_pk_bf16_f32 v167, v140, v141
	v_lshlrev_b64 v[154:155], 12, v[154:155]
	v_lshl_add_u64 v[164:165], v[136:137], 0, v[156:157]
	ds_write2_b64 v152, v[142:143], v[166:167] offset0:72 offset1:76
	v_lshl_add_u64 v[154:155], s[40:41], 0, v[154:155]
	s_waitcnt vmcnt(11)
	v_pk_fma_f32 v[166:167], v[94:95], v[78:79], v[214:215]
	v_pk_fma_f32 v[92:93], v[92:93], v[76:77], v[212:213]
	s_waitcnt vmcnt(10)
	v_pk_fma_f32 v[82:83], v[82:83], v[74:75], v[218:219]
	v_pk_fma_f32 v[80:81], v[80:81], v[72:73], v[216:217]
	global_load_dwordx4 v[136:139], v[164:165], off
	global_load_dwordx4 v[100:103], v[164:165], off offset:64
	global_load_dwordx4 v[96:99], v[164:165], off offset:128
	global_load_dwordx4 v[140:143], v[164:165], off offset:192
	v_lshl_add_u64 v[164:165], v[154:155], 0, v[156:157]
	v_cvt_pk_bf16_f32 v168, v92, v93
	v_cvt_pk_bf16_f32 v169, v166, v167
	v_cvt_pk_bf16_f32 v166, v80, v81
	v_cvt_pk_bf16_f32 v167, v82, v83
	v_add_u32_e32 v152, 0x6000, v163
	global_load_dwordx4 v[154:157], v[164:165], off
	global_load_dwordx4 v[92:95], v[164:165], off offset:64
	global_load_dwordx4 v[80:83], v[164:165], off offset:128
	ds_write2_b64 v152, v[168:169], v[166:167] offset0:96 offset1:100
	global_load_dwordx4 v[164:167], v[164:165], off offset:192
	s_waitcnt vmcnt(17)
	v_pk_fma_f32 v[66:67], v[66:67], v[90:91], v[150:151]
	v_pk_fma_f32 v[64:65], v[64:65], v[88:89], v[148:149]
	s_waitcnt vmcnt(16)
	v_pk_fma_f32 v[68:69], v[68:69], v[84:85], v[144:145]
	v_cvt_pk_bf16_f32 v64, v64, v65
	v_cvt_pk_bf16_f32 v65, v66, v67
	v_pk_fma_f32 v[66:67], v[70:71], v[86:87], v[146:147]
	v_cvt_pk_bf16_f32 v68, v68, v69
	v_cvt_pk_bf16_f32 v69, v66, v67
	ds_write2_b64 v152, v[64:65], v[68:69] offset0:104 offset1:108
	s_waitcnt vmcnt(15)
	v_pk_fma_f32 v[62:63], v[62:63], v[78:79], v[122:123]
	v_pk_fma_f32 v[60:61], v[60:61], v[76:77], v[120:121]
	s_waitcnt vmcnt(14)
	v_pk_fma_f32 v[58:59], v[58:59], v[74:75], v[126:127]
	v_pk_fma_f32 v[56:57], v[56:57], v[72:73], v[124:125]
	s_waitcnt vmcnt(13)
	v_pk_fma_f32 v[54:55], v[54:55], v[90:91], v[114:115]
	v_pk_fma_f32 v[52:53], v[52:53], v[88:89], v[112:113]
	s_waitcnt vmcnt(12)
	v_pk_fma_f32 v[50:51], v[50:51], v[86:87], v[118:119]
	v_pk_fma_f32 v[48:49], v[48:49], v[84:85], v[116:117]
	v_cvt_pk_bf16_f32 v60, v60, v61
	v_cvt_pk_bf16_f32 v61, v62, v63
	v_cvt_pk_bf16_f32 v56, v56, v57
	v_cvt_pk_bf16_f32 v57, v58, v59
	v_add_u32_e32 v58, 0x8000, v163
	v_cvt_pk_bf16_f32 v52, v52, v53
	v_cvt_pk_bf16_f32 v53, v54, v55
	v_cvt_pk_bf16_f32 v48, v48, v49
	v_cvt_pk_bf16_f32 v49, v50, v51
	ds_write2_b64 v58, v[60:61], v[56:57] offset0:128 offset1:132
	s_waitcnt vmcnt(11)
	v_pk_fma_f32 v[46:47], v[46:47], v[78:79], v[130:131]
	v_pk_fma_f32 v[44:45], v[44:45], v[76:77], v[128:129]
	s_waitcnt vmcnt(10)
	v_pk_fma_f32 v[42:43], v[42:43], v[74:75], v[110:111]
	v_pk_fma_f32 v[40:41], v[40:41], v[72:73], v[108:109]
	s_waitcnt vmcnt(9)
	v_pk_fma_f32 v[38:39], v[38:39], v[90:91], v[106:107]
	v_pk_fma_f32 v[36:37], v[36:37], v[88:89], v[104:105]
	s_waitcnt vmcnt(8)
	v_pk_fma_f32 v[34:35], v[34:35], v[86:87], v[134:135]
	v_pk_fma_f32 v[32:33], v[32:33], v[84:85], v[132:133]
	v_cvt_pk_bf16_f32 v44, v44, v45
	v_cvt_pk_bf16_f32 v45, v46, v47
	v_cvt_pk_bf16_f32 v40, v40, v41
	v_cvt_pk_bf16_f32 v41, v42, v43
	v_add_u32_e32 v42, 0xa000, v163
	v_cvt_pk_bf16_f32 v36, v36, v37
	v_cvt_pk_bf16_f32 v37, v38, v39
	v_cvt_pk_bf16_f32 v32, v32, v33
	v_cvt_pk_bf16_f32 v33, v34, v35
	ds_write2_b64 v58, v[52:53], v[48:49] offset0:136 offset1:140
	ds_write2_b64 v42, v[44:45], v[40:41] offset0:160 offset1:164
	ds_write2_b64 v42, v[36:37], v[32:33] offset0:168 offset1:172
	s_waitcnt vmcnt(7)
	v_pk_fma_f32 v[30:31], v[30:31], v[78:79], v[138:139]
	v_pk_fma_f32 v[28:29], v[28:29], v[76:77], v[136:137]
	s_waitcnt vmcnt(6)
	v_pk_fma_f32 v[26:27], v[26:27], v[74:75], v[102:103]
	v_pk_fma_f32 v[24:25], v[24:25], v[72:73], v[100:101]
	s_waitcnt vmcnt(5)
	v_pk_fma_f32 v[22:23], v[22:23], v[90:91], v[98:99]
	v_pk_fma_f32 v[20:21], v[20:21], v[88:89], v[96:97]
	s_waitcnt vmcnt(4)
	v_pk_fma_f32 v[18:19], v[18:19], v[86:87], v[142:143]
	v_pk_fma_f32 v[16:17], v[16:17], v[84:85], v[140:141]
	v_cvt_pk_bf16_f32 v28, v28, v29
	v_cvt_pk_bf16_f32 v29, v30, v31
	s_waitcnt vmcnt(3)
	v_pk_fma_f32 v[14:15], v[14:15], v[78:79], v[156:157]
	v_pk_fma_f32 v[12:13], v[12:13], v[76:77], v[154:155]
	s_waitcnt vmcnt(2)
	v_pk_fma_f32 v[10:11], v[10:11], v[74:75], v[94:95]
	v_pk_fma_f32 v[8:9], v[8:9], v[72:73], v[92:93]
	s_waitcnt vmcnt(1)
	v_pk_fma_f32 v[6:7], v[6:7], v[90:91], v[82:83]
	v_pk_fma_f32 v[4:5], v[4:5], v[88:89], v[80:81]
	s_waitcnt vmcnt(0)
	v_pk_fma_f32 v[2:3], v[2:3], v[86:87], v[166:167]
	v_pk_fma_f32 v[0:1], v[0:1], v[84:85], v[164:165]
	v_cvt_pk_bf16_f32 v24, v24, v25
	v_cvt_pk_bf16_f32 v25, v26, v27
	v_add_u32_e32 v26, 0xc000, v163
	v_cvt_pk_bf16_f32 v20, v20, v21
	v_cvt_pk_bf16_f32 v21, v22, v23
	v_cvt_pk_bf16_f32 v16, v16, v17
	v_cvt_pk_bf16_f32 v17, v18, v19
	v_cvt_pk_bf16_f32 v12, v12, v13
	v_cvt_pk_bf16_f32 v13, v14, v15
	v_cvt_pk_bf16_f32 v8, v8, v9
	v_cvt_pk_bf16_f32 v9, v10, v11
	v_add_u32_e32 v10, 0xe000, v163
	v_cvt_pk_bf16_f32 v4, v4, v5
	v_cvt_pk_bf16_f32 v5, v6, v7
	v_cvt_pk_bf16_f32 v0, v0, v1
	v_cvt_pk_bf16_f32 v1, v2, v3
	v_mov_b32_e32 v2, v158
	ds_write2_b64 v26, v[28:29], v[24:25] offset0:192 offset1:196
	ds_write2_b64 v26, v[20:21], v[16:17] offset0:200 offset1:204
	ds_write2_b64 v10, v[12:13], v[8:9] offset0:224 offset1:228
	ds_write2_b64 v10, v[4:5], v[0:1] offset0:232 offset1:236
	s_waitcnt lgkmcnt(0)
	s_barrier
; #define TIDX512 launder_i((int)threadIdx.x)
; __device__ __forceinline__ void epi_store(const char* lds, bf16_t* __restrict__ O, int ldo, int m0, int n0, int ncols_valid) {
;     const int t = TIDX512;
;     const int chunk = t & 31, rsub = t >> 5;
;     if (n0 + chunk * 8 < ncols_valid) {
; #pragma unroll
;         for (int ps = 0; ps < 16; ps++) {
;             const int row = ps * 16 + rsub;
;             const u32x4 v = *(const u32x4*)(lds + row * EPI_ROWB + chunk * 16);
;             *(u32x4*)(O + (size_t)(m0 + row) * ldo + n0 + chunk * 8) = v;
;         }
;     }
; }
	s_nop 0
	v_and_b32_e32 v0, 31, v2
	v_lshlrev_b32_e32 v1, 3, v0
	v_or_b32_e32 v3, s38, v1
	v_cmp_gt_i32_e32 vcc, s43, v3
	s_and_saveexec_b64 s[40:41], vcc
	s_cbranch_execz .LBB0_775
	v_ashrrev_i32_e32 v4, 5, v2
	v_lshlrev_b32_e32 v152, 1, v1
	v_mul_lo_u32 v1, v4, s0
	s_ashr_i32 s39, s38, 31
	v_lshl_add_u32 v14, v0, 4, v1
	s_lshl_b64 s[38:39], s[38:39], 1
	ds_read_b128 v[0:3], v14
	s_add_u32 s38, s1, s38
	v_add_u32_e32 v10, s47, v4
	s_addc_u32 s39, s2, s39
	v_ashrrev_i32_e32 v11, 31, v10
	v_lshl_add_u64 v[8:9], s[38:39], 0, v[152:153]
	v_lshlrev_b64 v[4:5], 11, v[10:11]
	v_lshl_add_u64 v[12:13], v[8:9], 0, v[4:5]
	ds_read_b128 v[4:7], v14 offset:8448
	s_waitcnt lgkmcnt(1)
	global_store_dwordx4 v[12:13], v[0:3], off
	v_add_u32_e32 v11, 0x2100, v14
	v_add_u32_e32 v15, 0x4200, v14
	v_add_u32_e32 v0, 16, v10
	v_ashrrev_i32_e32 v1, 31, v0
	v_lshlrev_b64 v[0:1], 11, v[0:1]
	v_lshl_add_u64 v[0:1], v[8:9], 0, v[0:1]
	s_waitcnt lgkmcnt(0)
	global_store_dwordx4 v[0:1], v[4:7], off
	ds_read_b128 v[0:3], v14 offset:16896
	v_add_u32_e32 v16, 0x6300, v14
	v_add_u32_e32 v4, 32, v10
	v_ashrrev_i32_e32 v5, 31, v4
	v_lshlrev_b64 v[4:5], 11, v[4:5]
	v_lshl_add_u64 v[12:13], v[8:9], 0, v[4:5]
	ds_read_b128 v[4:7], v14 offset:25344
	s_waitcnt lgkmcnt(1)
	global_store_dwordx4 v[12:13], v[0:3], off
	v_add_u32_e32 v17, 0x8400, v14
	v_add_u32_e32 v18, 0xa500, v14
	v_add_u32_e32 v0, 48, v10
	v_ashrrev_i32_e32 v1, 31, v0
	v_lshlrev_b64 v[0:1], 11, v[0:1]
	v_lshl_add_u64 v[0:1], v[8:9], 0, v[0:1]
	s_waitcnt lgkmcnt(0)
	global_store_dwordx4 v[0:1], v[4:7], off
	ds_read_b128 v[0:3], v14 offset:33792
	v_add_u32_e32 v19, 0xc600, v14
	v_add_u32_e32 v4, 64, v10
	v_ashrrev_i32_e32 v5, 31, v4
	v_lshlrev_b64 v[4:5], 11, v[4:5]
	v_lshl_add_u64 v[12:13], v[8:9], 0, v[4:5]
	ds_read_b128 v[4:7], v14 offset:42240
	s_waitcnt lgkmcnt(1)
	global_store_dwordx4 v[12:13], v[0:3], off
	v_add_u32_e32 v20, 0xe700, v11
	s_nop 0
	v_add_u32_e32 v0, 0x50, v10
	v_ashrrev_i32_e32 v1, 31, v0
	v_lshlrev_b64 v[0:1], 11, v[0:1]
	v_lshl_add_u64 v[0:1], v[8:9], 0, v[0:1]
	s_waitcnt lgkmcnt(0)
	global_store_dwordx4 v[0:1], v[4:7], off
	ds_read_b128 v[0:3], v14 offset:50688
	s_nop 0
	v_add_u32_e32 v4, 0x60, v10
	v_ashrrev_i32_e32 v5, 31, v4
	v_lshlrev_b64 v[4:5], 11, v[4:5]
	v_lshl_add_u64 v[12:13], v[8:9], 0, v[4:5]
	ds_read_b128 v[4:7], v14 offset:59136
	s_waitcnt lgkmcnt(1)
	global_store_dwordx4 v[12:13], v[0:3], off
	v_add_u32_e32 v14, 0xe700, v14
	s_nop 0
	v_add_u32_e32 v0, 0x70, v10
	v_ashrrev_i32_e32 v1, 31, v0
	v_lshlrev_b64 v[0:1], 11, v[0:1]
	v_lshl_add_u64 v[0:1], v[8:9], 0, v[0:1]
	s_waitcnt lgkmcnt(0)
	global_store_dwordx4 v[0:1], v[4:7], off
	ds_read_b128 v[0:3], v11 offset:59136
	s_nop 0
	v_add_u32_e32 v4, 0x80, v10
	v_ashrrev_i32_e32 v5, 31, v4
	v_lshlrev_b64 v[4:5], 11, v[4:5]
	v_lshl_add_u64 v[12:13], v[8:9], 0, v[4:5]
	ds_read_b128 v[4:7], v15 offset:59136
	s_waitcnt lgkmcnt(1)
	global_store_dwordx4 v[12:13], v[0:3], off
	s_nop 1
	v_add_u32_e32 v0, 0x90, v10
	v_ashrrev_i32_e32 v1, 31, v0
	v_lshlrev_b64 v[0:1], 11, v[0:1]
	v_lshl_add_u64 v[0:1], v[8:9], 0, v[0:1]
	s_waitcnt lgkmcnt(0)
	global_store_dwordx4 v[0:1], v[4:7], off
	ds_read_b128 v[0:3], v16 offset:59136
	s_nop 0
	v_add_u32_e32 v4, 0xa0, v10
	v_ashrrev_i32_e32 v5, 31, v4
	v_lshlrev_b64 v[4:5], 11, v[4:5]
	v_lshl_add_u64 v[12:13], v[8:9], 0, v[4:5]
	ds_read_b128 v[4:7], v17 offset:59136
	s_waitcnt lgkmcnt(1)
	global_store_dwordx4 v[12:13], v[0:3], off
	s_nop 1
	v_add_u32_e32 v0, 0xb0, v10
	v_ashrrev_i32_e32 v1, 31, v0
	v_lshlrev_b64 v[0:1], 11, v[0:1]
	v_lshl_add_u64 v[0:1], v[8:9], 0, v[0:1]
	s_waitcnt lgkmcnt(0)
	global_store_dwordx4 v[0:1], v[4:7], off
	ds_read_b128 v[0:3], v18 offset:59136
	s_nop 0
	v_add_u32_e32 v4, 0xc0, v10
	v_ashrrev_i32_e32 v5, 31, v4
	v_lshlrev_b64 v[4:5], 11, v[4:5]
	v_lshl_add_u64 v[12:13], v[8:9], 0, v[4:5]
	ds_read_b128 v[4:7], v19 offset:59136
	s_waitcnt lgkmcnt(1)
	global_store_dwordx4 v[12:13], v[0:3], off
	s_nop 1
	v_add_u32_e32 v0, 0xd0, v10
	v_ashrrev_i32_e32 v1, 31, v0
	v_lshlrev_b64 v[0:1], 11, v[0:1]
	v_lshl_add_u64 v[0:1], v[8:9], 0, v[0:1]
	s_waitcnt lgkmcnt(0)
	global_store_dwordx4 v[0:1], v[4:7], off
	ds_read_b128 v[0:3], v14 offset:59136
	s_nop 0
	v_add_u32_e32 v4, 0xe0, v10
	v_ashrrev_i32_e32 v5, 31, v4
	v_lshlrev_b64 v[4:5], 11, v[4:5]
	v_lshl_add_u64 v[12:13], v[8:9], 0, v[4:5]
	ds_read_b128 v[4:7], v20 offset:59136
	s_waitcnt lgkmcnt(1)
	global_store_dwordx4 v[12:13], v[0:3], off
	s_nop 1
	v_add_u32_e32 v0, 0xf0, v10
	v_ashrrev_i32_e32 v1, 31, v0
	v_lshlrev_b64 v[0:1], 11, v[0:1]
	v_lshl_add_u64 v[0:1], v[8:9], 0, v[0:1]
	s_waitcnt lgkmcnt(0)
	global_store_dwordx4 v[0:1], v[4:7], off
	s_branch .LBB0_775

; #define TIDX512 launder_i((int)threadIdx.x)
; __device__ __forceinline__ void glds16(const bf16_t* g, char* l) { __builtin_amdgcn_global_load_lds((const unsigned*)g, (unsigned*)l, 16, 0, 0); }
; __device__ __forceinline__ void gemm_issue(const GemmSrc& g, int kt, int s, char* lds) {
;     const int tid = TIDX512, lane = tid & 63, wave = tid >> 6;
;     char* xdst = lds + s * 65536 + wave * 4096 + lane * 16;
;     char* wdst = xdst + 32768;
; #pragma unroll
;     for (int i = 0; i < 4; i++) {
;         const int d = (i & 1) ? g.dsw : 0;
;         glds16(g.xsrc + (size_t)i * 8 * g.ldx + kt * 64 + d, xdst + i * 1024);
;         glds16(g.wsrc + (size_t)i * 8 * g.ldw + kt * 64 + d, wdst + i * 1024);
;     }
; }
; __device__ __forceinline__ void gemm_prologue(const GemmSrc& g, char* lds) { gemm_issue(g, 0, 0, lds); }
; __device__ __forceinline__ void zero_acc(f32x4 (&acc)[8][4]) {
; #pragma unroll
;     for (int a = 0; a < 8; a++)
; #pragma unroll
;         for (int b = 0; b < 4; b++) acc[a][b] = (f32x4){0.f, 0.f, 0.f, 0.f};
; }
.LBB0_918:
	v_mov_b32_e32 v0, v158
	s_lshl_b32 s42, s42, 8
	v_ashrrev_i32_e32 v1, 1, v0
	v_and_b32_e32 v12, 0xffffffe0, v1
	v_bfe_u32 v1, v0, 4, 2
	v_and_b32_e32 v3, 7, v0
	v_bitop3_b32 v4, v1, v0, 7 bitop3:0x78
	v_bitop3_b32 v5, v1, v3, 4 bitop3:0x36
	v_lshlrev_b32_e32 v128, 4, v4
	v_sub_u32_e32 v4, v5, v4
	v_mov_b32_e32 v5, v158
	v_bfe_u32 v13, v0, 3, 3
	v_or_b32_e32 v2, v12, v13
	v_lshlrev_b32_e32 v6, 6, v5
	v_lshlrev_b32_e32 v5, 4, v5
	s_lshl_b32 s34, s43, 8
	v_add_u32_e32 v0, s42, v2
	v_and_b32_e32 v5, 0x3f0, v5
	v_ashrrev_i32_e32 v1, 31, v0
	v_add_u32_e32 v2, s34, v2
	v_and_or_b32 v14, v6, s38, v5
	v_lshlrev_b64 v[0:1], 11, v[0:1]
	v_ashrrev_i32_e32 v3, 31, v2
	v_lshlrev_b32_e32 v4, 3, v4
	v_add_u32_e32 v5, 0x8000, v14
	v_readfirstlane_b32 s35, v14
	v_lshl_add_u64 v[0:1], s[6:7], 0, v[0:1]
	v_lshlrev_b64 v[2:3], 11, v[2:3]
	s_mov_b32 m0, s35
	v_readfirstlane_b32 s35, v5
	v_ashrrev_i32_e32 v5, 31, v4
	v_lshl_add_u64 v[0:1], v[0:1], 0, v[128:129]
	v_lshl_add_u64 v[2:3], s[8:9], 0, v[2:3]
	v_lshlrev_b64 v[4:5], 1, v[4:5]
	v_or_b32_e32 v10, 0x400, v14
	v_lshl_add_u64 v[2:3], v[2:3], 0, v[128:129]
	s_cmp_lg_u32 s33, 0
	s_cbranch_scc1 .Ldma_skip_72
	global_load_lds_dwordx4 v[0:1], off
	s_add_u32 m0, m0, 0x4000
	v_lshl_add_u64 v[220:221], v[0:1], 0, s[100:101]
	global_load_lds_dwordx4 v[220:221], off
.Ldma_skip_72:
	s_mov_b32 m0, s35
	v_lshl_add_u64 v[6:7], v[0:1], 0, v[4:5]
	v_readfirstlane_b32 s35, v10
	s_cmp_lg_u32 s33, 0
	s_cbranch_scc1 .Ldma_skip_73
	global_load_lds_dwordx4 v[2:3], off
	s_add_u32 m0, m0, 0x4000
	v_lshl_add_u64 v[220:221], v[2:3], 0, s[100:101]
	global_load_lds_dwordx4 v[220:221], off
.Ldma_skip_73:
	v_lshl_add_u64 v[8:9], v[6:7], 0, s[10:11]
	s_mov_b32 m0, s35
	v_add_u32_e32 v15, 0x8400, v14
	s_cmp_lg_u32 s33, 0
	s_cbranch_scc1 .Ldma_skip_74
	global_load_lds_dwordx4 v[8:9], off
	s_add_u32 m0, m0, 0x4000
	v_lshl_add_u64 v[220:221], v[8:9], 0, s[100:101]
	global_load_lds_dwordx4 v[220:221], off
.Ldma_skip_74:
	v_lshl_add_u64 v[8:9], v[2:3], 0, v[4:5]
	v_readfirstlane_b32 s35, v15
	v_lshl_add_u64 v[10:11], v[8:9], 0, s[10:11]
	s_mov_b32 m0, s35
	v_lshl_add_u64 v[0:1], v[0:1], 0, s[12:13]
	s_cmp_lg_u32 s33, 0
	s_cbranch_scc1 .Ldma_skip_75
	global_load_lds_dwordx4 v[10:11], off
	s_add_u32 m0, m0, 0x4000
	v_lshl_add_u64 v[220:221], v[10:11], 0, s[100:101]
	global_load_lds_dwordx4 v[220:221], off
.Ldma_skip_75:
	v_or_b32_e32 v10, 0x800, v14
	s_mov_b64 s[36:37], 0
	v_readfirstlane_b32 s35, v10
	s_mov_b32 m0, s35
	s_nop 0
	s_cmp_lg_u32 s33, 0
	s_cbranch_scc1 .Ldma_skip_76
	global_load_lds_dwordx4 v[0:1], off
	s_add_u32 m0, m0, 0x4000
	v_lshl_add_u64 v[220:221], v[0:1], 0, s[100:101]
	global_load_lds_dwordx4 v[220:221], off
.Ldma_skip_76:
	v_lshl_add_u64 v[0:1], v[2:3], 0, s[12:13]
	v_add_u32_e32 v2, 0x8800, v14
	s_nop 0
	v_readfirstlane_b32 s35, v2
	v_or_b32_e32 v2, 0xc00, v14
	s_mov_b32 m0, s35
	v_readfirstlane_b32 s35, v2
	v_add_u32_e32 v2, 0x8c00, v14
	s_cmp_lg_u32 s33, 0
	s_cbranch_scc1 .Ldma_skip_77
	global_load_lds_dwordx4 v[0:1], off
	s_add_u32 m0, m0, 0x4000
	v_lshl_add_u64 v[220:221], v[0:1], 0, s[100:101]
	global_load_lds_dwordx4 v[220:221], off
.Ldma_skip_77:
	v_lshl_add_u64 v[0:1], v[6:7], 0, s[14:15]
	s_mov_b32 m0, s35
	v_readfirstlane_b32 s35, v2
	s_cmp_lg_u32 s33, 0
	s_cbranch_scc1 .Ldma_skip_78
	global_load_lds_dwordx4 v[0:1], off
	s_add_u32 m0, m0, 0x4000
	v_lshl_add_u64 v[220:221], v[0:1], 0, s[100:101]
	global_load_lds_dwordx4 v[220:221], off
.Ldma_skip_78:
	v_lshl_add_u64 v[0:1], v[8:9], 0, s[14:15]
	s_mov_b32 m0, s35
	s_mov_b32 s35, 0x10000
	s_cmp_lg_u32 s33, 0
	s_cbranch_scc1 .Ldma_skip_79
	global_load_lds_dwordx4 v[0:1], off
	s_add_u32 m0, m0, 0x4000
	v_lshl_add_u64 v[220:221], v[0:1], 0, s[100:101]
	global_load_lds_dwordx4 v[220:221], off
.Ldma_skip_79:
	v_mov_b32_e32 v0, v158
	s_nop 0
	v_and_b32_e32 v1, 15, v0
	v_lshrrev_b32_e32 v2, 4, v0
	v_bfe_u32 v6, v0, 1, 3
	v_bfe_u32 v3, v0, 4, 2
	v_lshlrev_b32_e32 v1, 7, v1
	v_bitop3_b32 v2, v2, v6, 3 bitop3:0x6c
	v_lshl_or_b32 v140, v2, 4, v1
	v_bitop3_b32 v2, v3, v6, 4 bitop3:0x36
	v_lshl_or_b32 v139, v2, 4, v1
	v_lshlrev_b32_e32 v1, 7, v0
	v_lshlrev_b32_e32 v0, 6, v0
	v_and_b32_e32 v141, 0xffffc000, v0
	v_or_b32_e32 v0, s42, v13
	v_add_u32_e32 v0, v0, v12
	v_or_b32_e32 v2, s34, v13
	v_and_b32_e32 v142, 0x6000, v1
	v_ashrrev_i32_e32 v1, 31, v0
	v_add_u32_e32 v2, v2, v12
	v_lshlrev_b64 v[0:1], 11, v[0:1]
	v_ashrrev_i32_e32 v3, 31, v2
	v_or_b32_e32 v0, v0, v128
	v_lshlrev_b64 v[2:3], 11, v[2:3]
	v_lshl_add_u64 v[130:131], s[4:5], 0, v[0:1]
	v_or_b32_e32 v2, v2, v128
	v_lshl_add_u64 v[0:1], v[0:1], 0, v[4:5]
	v_lshl_add_u64 v[134:135], s[4:5], 0, v[0:1]
	v_lshl_add_u64 v[0:1], v[2:3], 0, v[4:5]
	v_lshl_add_u64 v[136:137], s[4:5], 0, v[0:1]
	v_mov_b32_e32 v0, 0
	v_lshl_add_u64 v[132:133], s[4:5], 0, v[2:3]
	v_mov_b32_e32 v1, v0
	v_mov_b32_e32 v2, v0
	v_mov_b32_e32 v3, v0
	v_mov_b32_e32 v4, v0
	v_mov_b32_e32 v5, v0
	v_mov_b32_e32 v6, v0
	v_mov_b32_e32 v7, v0
	v_mov_b32_e32 v8, v0
	v_mov_b32_e32 v9, v0
	v_mov_b32_e32 v10, v0
	v_mov_b32_e32 v11, v0
	v_mov_b32_e32 v12, v0
	v_mov_b32_e32 v13, v0
	v_mov_b32_e32 v14, v0
	v_mov_b32_e32 v15, v0
	v_mov_b32_e32 v16, v0
	v_mov_b32_e32 v17, v0
	v_mov_b32_e32 v18, v0
	v_mov_b32_e32 v19, v0
	v_mov_b32_e32 v20, v0
	v_mov_b32_e32 v21, v0
	v_mov_b32_e32 v22, v0
	v_mov_b32_e32 v23, v0
	v_mov_b32_e32 v24, v0
	v_mov_b32_e32 v25, v0
	v_mov_b32_e32 v26, v0
	v_mov_b32_e32 v27, v0
	v_mov_b32_e32 v28, v0
	v_mov_b32_e32 v29, v0
	v_mov_b32_e32 v30, v0
	v_mov_b32_e32 v31, v0
	v_mov_b32_e32 v32, v0
	v_mov_b32_e32 v33, v0
	v_mov_b32_e32 v34, v0
	v_mov_b32_e32 v35, v0
	v_mov_b32_e32 v36, v0
	v_mov_b32_e32 v37, v0
	v_mov_b32_e32 v38, v0
; __device__ __forceinline__ f32x4 mfma16(bf16x8 a, bf16x8 b, f32x4 c) { return __builtin_amdgcn_mfma_f32_16x16x32_bf16(a, b, c, 0, 0, 0); }
; __device__ __forceinline__ void gemm_mainloop(f32x4 (&acc)[8][4], const GemmSrc& g, int K, char* lds) {
;     ...
;     for (int kt = 0; kt < KT; kt++) {
;         WAIT_V(0);
;         __builtin_amdgcn_s_barrier();
;         const char* st = lds + (kt & 1) * 65536;
;         bf16x8 afA[4], afB[4], bX[4], bY[4];
; #pragma unroll
;         for (int ni = 0; ni < 4; ni++) afA[ni] = *(const bf16x8*)(st + woff + ni * 16 * 128 + rdo0);
; #pragma unroll
;         for (int mi = 0; mi < 4; mi++) bX[mi] = *(const bf16x8*)(st + xoff + mi * 16 * 128 + rdo0);
;         if (kt + 1 < KT) gemm_issue(g, kt + 1, (kt + 1) & 1, lds);
; #pragma unroll
;         for (int mi = 0; mi < 4; mi++) bY[mi] = *(const bf16x8*)(st + xoff + (4 + mi) * 16 * 128 + rdo0);
; #pragma unroll
;         for (int ni = 0; ni < 4; ni++) afB[ni] = *(const bf16x8*)(st + woff + ni * 16 * 128 + rdo1);
; #pragma unroll
;         for (int mi = 0; mi < 4; mi++)
; #pragma unroll
;             for (int ni = 0; ni < 4; ni++) acc[mi][ni] = mfma16(afA[ni], bX[mi], acc[mi][ni]);
;         __builtin_amdgcn_sched_barrier(0);
; #pragma unroll
;         for (int mi = 0; mi < 4; mi++) bX[mi] = *(const bf16x8*)(st + xoff + mi * 16 * 128 + rdo1);
; #pragma unroll
;         for (int mi = 0; mi < 4; mi++)
; #pragma unroll
;             for (int ni = 0; ni < 4; ni++) acc[4 + mi][ni] = mfma16(afA[ni], bY[mi], acc[4 + mi][ni]);
;         __builtin_amdgcn_sched_barrier(0);
; #pragma unroll
;         for (int mi = 0; mi < 4; mi++) bY[mi] = *(const bf16x8*)(st + xoff + (4 + mi) * 16 * 128 + rdo1);
; #pragma unroll
;         for (int mi = 0; mi < 4; mi++)
; #pragma unroll
;             for (int ni = 0; ni < 4; ni++) acc[mi][ni] = mfma16(afB[ni], bX[mi], acc[mi][ni]);
;         __builtin_amdgcn_sched_barrier(0);
; #pragma unroll
;         for (int mi = 0; mi < 4; mi++)
; #pragma unroll
;             for (int ni = 0; ni < 4; ni++) acc[4 + mi][ni] = mfma16(afB[ni], bY[mi], acc[4 + mi][ni]);
;         __builtin_amdgcn_sched_barrier(0);
;     }
; __device__ __forceinline__ void zero_acc(f32x4 (&acc)[8][4]) {
; #pragma unroll
;     for (int a = 0; a < 8; a++)
; #pragma unroll
;         for (int b = 0; b < 4; b++) acc[a][b] = (f32x4){0.f, 0.f, 0.f, 0.f};
; }
	v_mov_b32_e32 v39, v0
	v_mov_b32_e32 v40, v0
	v_mov_b32_e32 v41, v0
	v_mov_b32_e32 v42, v0
	v_mov_b32_e32 v43, v0
	v_mov_b32_e32 v44, v0
	v_mov_b32_e32 v45, v0
	v_mov_b32_e32 v46, v0
	v_mov_b32_e32 v47, v0
	v_mov_b32_e32 v48, v0
	v_mov_b32_e32 v49, v0
	v_mov_b32_e32 v50, v0
	v_mov_b32_e32 v51, v0
	v_mov_b32_e32 v52, v0
	v_mov_b32_e32 v53, v0
	v_mov_b32_e32 v54, v0
	v_mov_b32_e32 v55, v0
	v_mov_b32_e32 v56, v0
	v_mov_b32_e32 v57, v0
	v_mov_b32_e32 v58, v0
	v_mov_b32_e32 v59, v0
	v_mov_b32_e32 v60, v0
	v_mov_b32_e32 v61, v0
	v_mov_b32_e32 v62, v0
	v_mov_b32_e32 v63, v0
	v_mov_b32_e32 v64, v0
	v_mov_b32_e32 v65, v0
	v_mov_b32_e32 v66, v0
	v_mov_b32_e32 v67, v0
	v_mov_b32_e32 v68, v0
	v_mov_b32_e32 v69, v0
	v_mov_b32_e32 v70, v0
	v_mov_b32_e32 v71, v0
	v_mov_b32_e32 v72, v0
	v_mov_b32_e32 v73, v0
	v_mov_b32_e32 v74, v0
	v_mov_b32_e32 v75, v0
	v_mov_b32_e32 v76, v0
	v_mov_b32_e32 v77, v0
	v_mov_b32_e32 v78, v0
	v_mov_b32_e32 v79, v0
	v_mov_b32_e32 v80, v0
	v_mov_b32_e32 v81, v0
	v_mov_b32_e32 v82, v0
	v_mov_b32_e32 v83, v0
	v_mov_b32_e32 v84, v0
	v_mov_b32_e32 v85, v0
	v_mov_b32_e32 v86, v0
	v_mov_b32_e32 v87, v0
	v_mov_b32_e32 v88, v0
	v_mov_b32_e32 v89, v0
	v_mov_b32_e32 v90, v0
	v_mov_b32_e32 v91, v0
	v_mov_b32_e32 v92, v0
	v_mov_b32_e32 v93, v0
	v_mov_b32_e32 v94, v0
	v_mov_b32_e32 v95, v0
	v_mov_b32_e32 v96, v0
	v_mov_b32_e32 v97, v0
	v_mov_b32_e32 v98, v0
	v_mov_b32_e32 v99, v0
	v_mov_b32_e32 v100, v0
	v_mov_b32_e32 v101, v0
	v_mov_b32_e32 v102, v0
	v_mov_b32_e32 v103, v0
	v_mov_b32_e32 v104, v0
	v_mov_b32_e32 v105, v0
	v_mov_b32_e32 v106, v0
	v_mov_b32_e32 v107, v0
	v_mov_b32_e32 v108, v0
	v_mov_b32_e32 v109, v0
	v_mov_b32_e32 v110, v0
	v_mov_b32_e32 v111, v0
	v_mov_b32_e32 v112, v0
	v_mov_b32_e32 v113, v0
	v_mov_b32_e32 v114, v0
	v_mov_b32_e32 v115, v0
	v_mov_b32_e32 v116, v0
	v_mov_b32_e32 v117, v0
	v_mov_b32_e32 v118, v0
	v_mov_b32_e32 v119, v0
	v_mov_b32_e32 v120, v0
	v_mov_b32_e32 v121, v0
	v_mov_b32_e32 v122, v0
	v_mov_b32_e32 v123, v0
	v_mov_b32_e32 v124, v0
	v_mov_b32_e32 v125, v0
	v_mov_b32_e32 v126, v0
	v_mov_b32_e32 v127, v0
.LBB0_919:
	s_add_i32 s43, s35, 0xffff0000
	s_and_b32 s43, s43, 0x10000
	v_or_b32_e32 v128, s43, v142
	v_add_u32_e32 v143, v128, v140
	s_waitcnt vmcnt(0)
	s_barrier
	ds_read_b128 v[144:147], v143 offset:32768
	ds_read_b128 v[148:151], v143 offset:34816
	ds_read_b128 v[152:155], v143 offset:36864
	ds_read_b128 v[160:163], v143 offset:38912
	v_add_u32_e32 v143, s43, v141
	v_add_u32_e32 v186, v143, v140
	v_mov_b32_e32 v156, v158
	ds_read_b128 v[164:167], v186
	ds_read_b128 v[168:171], v186 offset:2048
	ds_read_b128 v[172:175], v186 offset:4096
	ds_read_b128 v[176:179], v186 offset:6144
	s_and_b32 s43, s35, 0x10000
	v_lshlrev_b32_e32 v157, 6, v156
	v_and_b32_e32 v157, 0xfffff000, v157
	v_add_u32_e32 v157, s43, v157
	v_lshlrev_b32_e32 v156, 4, v156
	v_and_or_b32 v187, v156, s3, v157
	v_lshl_add_u64 v[156:157], v[130:131], 0, s[36:37]
	v_readfirstlane_b32 s43, v187
	v_add_u32_e32 v184, 0x8000, v187
	v_lshl_add_u64 v[180:181], v[156:157], 0, s[16:17]
	s_mov_b32 m0, s43
	v_readfirstlane_b32 s43, v184
	s_cmp_lg_u32 s33, 0
	s_cbranch_scc1 .Ldma_skip_80
	global_load_lds_dwordx4 v[180:181], off
	s_add_u32 m0, m0, 0x4000
	v_lshl_add_u64 v[220:221], v[180:181], 0, s[100:101]
	global_load_lds_dwordx4 v[220:221], off
.Ldma_skip_80:
	v_lshl_add_u64 v[180:181], v[132:133], 0, s[36:37]
	v_lshl_add_u64 v[182:183], v[180:181], 0, s[18:19]
	s_mov_b32 m0, s43
	v_or_b32_e32 v188, 0x400, v187
	s_cmp_lg_u32 s33, 0
	s_cbranch_scc1 .Ldma_skip_81
	global_load_lds_dwordx4 v[182:183], off
	s_add_u32 m0, m0, 0x4000
	v_lshl_add_u64 v[220:221], v[182:183], 0, s[100:101]
	global_load_lds_dwordx4 v[220:221], off
.Ldma_skip_81:
	v_lshl_add_u64 v[182:183], v[134:135], 0, s[36:37]
	v_readfirstlane_b32 s43, v188
	s_waitcnt lgkmcnt(0)
	v_mfma_f32_16x16x32_bf16 v[124:127], v[144:147], v[164:167], v[124:127]
	v_lshl_add_u64 v[184:185], v[182:183], 0, s[20:21]
	s_mov_b32 m0, s43
	v_lshl_add_u64 v[156:157], v[156:157], 0, s[24:25]
	v_mfma_f32_16x16x32_bf16 v[120:123], v[148:151], v[164:167], v[120:123]
	s_cmp_lg_u32 s33, 0
	s_cbranch_scc1 .Ldma_skip_82
	global_load_lds_dwordx4 v[184:185], off
	s_add_u32 m0, m0, 0x4000
	v_lshl_add_u64 v[220:221], v[184:185], 0, s[100:101]
	global_load_lds_dwordx4 v[220:221], off
.Ldma_skip_82:
	v_lshl_add_u64 v[184:185], v[136:137], 0, s[36:37]
	v_mfma_f32_16x16x32_bf16 v[116:119], v[152:155], v[164:167], v[116:119]
	v_add_u32_e32 v128, v128, v139
	v_mfma_f32_16x16x32_bf16 v[112:115], v[160:163], v[164:167], v[112:115]
	v_add_u32_e32 v166, 0x8400, v187
	v_lshl_add_u64 v[164:165], v[184:185], 0, s[22:23]
	v_readfirstlane_b32 s43, v166
	s_mov_b32 m0, s43
	v_mfma_f32_16x16x32_bf16 v[108:111], v[144:147], v[168:171], v[108:111]
	s_cmp_lg_u32 s33, 0
	s_cbranch_scc1 .Ldma_skip_83
	global_load_lds_dwordx4 v[164:165], off
	s_add_u32 m0, m0, 0x4000
	v_lshl_add_u64 v[220:221], v[164:165], 0, s[100:101]
	global_load_lds_dwordx4 v[220:221], off
.Ldma_skip_83:
	v_or_b32_e32 v164, 0x800, v187
	v_mfma_f32_16x16x32_bf16 v[104:107], v[148:151], v[168:171], v[104:107]
	v_readfirstlane_b32 s43, v164
	v_add_u32_e32 v164, 0x8800, v187
	s_mov_b32 m0, s43
	v_readfirstlane_b32 s43, v164
	v_or_b32_e32 v164, 0xc00, v187
	s_cmp_lg_u32 s33, 0
	s_cbranch_scc1 .Ldma_skip_84
	global_load_lds_dwordx4 v[156:157], off
	s_add_u32 m0, m0, 0x4000
	v_lshl_add_u64 v[220:221], v[156:157], 0, s[100:101]
	global_load_lds_dwordx4 v[220:221], off
.Ldma_skip_84:
	v_lshl_add_u64 v[156:157], v[180:181], 0, s[26:27]
	s_mov_b32 m0, s43
	v_readfirstlane_b32 s43, v164
	v_add_u32_e32 v164, 0x8c00, v187
	s_cmp_lg_u32 s33, 0
	s_cbranch_scc1 .Ldma_skip_85
	global_load_lds_dwordx4 v[156:157], off
	s_add_u32 m0, m0, 0x4000
	v_lshl_add_u64 v[220:221], v[156:157], 0, s[100:101]
	global_load_lds_dwordx4 v[220:221], off
; __device__ __forceinline__ f32x4 mfma16(bf16x8 a, bf16x8 b, f32x4 c) { return __builtin_amdgcn_mfma_f32_16x16x32_bf16(a, b, c, 0, 0, 0); }
; #define WAIT_V(n) asm volatile("s_waitcnt vmcnt(" #n ")" ::: "memory")
; __device__ __forceinline__ void gemm_mainloop(f32x4 (&acc)[8][4], const GemmSrc& g, int K, char* lds) {
;     ...
;     for (int kt = 0; kt < KT; kt++) {
;         WAIT_V(0);
;         __builtin_amdgcn_s_barrier();
;         const char* st = lds + (kt & 1) * 65536;
;         bf16x8 afA[4], afB[4], bX[4], bY[4];
; #pragma unroll
;         for (int ni = 0; ni < 4; ni++) afA[ni] = *(const bf16x8*)(st + woff + ni * 16 * 128 + rdo0);
; #pragma unroll
;         for (int mi = 0; mi < 4; mi++) bX[mi] = *(const bf16x8*)(st + xoff + mi * 16 * 128 + rdo0);
;         if (kt + 1 < KT) gemm_issue(g, kt + 1, (kt + 1) & 1, lds);
; #pragma unroll
;         for (int mi = 0; mi < 4; mi++) bY[mi] = *(const bf16x8*)(st + xoff + (4 + mi) * 16 * 128 + rdo0);
; #pragma unroll
;         for (int ni = 0; ni < 4; ni++) afB[ni] = *(const bf16x8*)(st + woff + ni * 16 * 128 + rdo1);
; #pragma unroll
;         for (int mi = 0; mi < 4; mi++)
; #pragma unroll
;             for (int ni = 0; ni < 4; ni++) acc[mi][ni] = mfma16(afA[ni], bX[mi], acc[mi][ni]);
;         __builtin_amdgcn_sched_barrier(0);
; #pragma unroll
;         for (int mi = 0; mi < 4; mi++) bX[mi] = *(const bf16x8*)(st + xoff + mi * 16 * 128 + rdo1);
; #pragma unroll
;         for (int mi = 0; mi < 4; mi++)
; #pragma unroll
;             for (int ni = 0; ni < 4; ni++) acc[4 + mi][ni] = mfma16(afA[ni], bY[mi], acc[4 + mi][ni]);
;         __builtin_amdgcn_sched_barrier(0);
; #pragma unroll
;         for (int mi = 0; mi < 4; mi++) bY[mi] = *(const bf16x8*)(st + xoff + (4 + mi) * 16 * 128 + rdo1);
; #pragma unroll
;         for (int mi = 0; mi < 4; mi++)
; #pragma unroll
;             for (int ni = 0; ni < 4; ni++) acc[mi][ni] = mfma16(afB[ni], bX[mi], acc[mi][ni]);
;         __builtin_amdgcn_sched_barrier(0);
; #pragma unroll
;         for (int mi = 0; mi < 4; mi++)
; #pragma unroll
;             for (int ni = 0; ni < 4; ni++) acc[4 + mi][ni] = mfma16(afB[ni], bY[mi], acc[4 + mi][ni]);
;         __builtin_amdgcn_sched_barrier(0);
;     }
.Ldma_skip_85:
	v_lshl_add_u64 v[156:157], v[182:183], 0, s[28:29]
	s_mov_b32 m0, s43
	v_readfirstlane_b32 s43, v164
	s_cmp_lg_u32 s33, 0
	s_cbranch_scc1 .Ldma_skip_86
	global_load_lds_dwordx4 v[156:157], off
	s_add_u32 m0, m0, 0x4000
	v_lshl_add_u64 v[220:221], v[156:157], 0, s[100:101]
	global_load_lds_dwordx4 v[220:221], off
.Ldma_skip_86:
	v_lshl_add_u64 v[156:157], v[184:185], 0, s[30:31]
	s_mov_b32 m0, s43
	v_mfma_f32_16x16x32_bf16 v[100:103], v[152:155], v[168:171], v[100:103]
	s_cmp_lg_u32 s33, 0
	s_cbranch_scc1 .Ldma_skip_87
	global_load_lds_dwordx4 v[156:157], off
	s_add_u32 m0, m0, 0x4000
	v_lshl_add_u64 v[220:221], v[156:157], 0, s[100:101]
	global_load_lds_dwordx4 v[220:221], off
.Ldma_skip_87:
	v_mfma_f32_16x16x32_bf16 v[96:99], v[160:163], v[168:171], v[96:99]
	ds_read_b128 v[164:167], v186 offset:8192
	ds_read_b128 v[168:171], v186 offset:10240
	v_mfma_f32_16x16x32_bf16 v[92:95], v[144:147], v[172:175], v[92:95]
	v_mfma_f32_16x16x32_bf16 v[88:91], v[148:151], v[172:175], v[88:91]
	v_mfma_f32_16x16x32_bf16 v[84:87], v[152:155], v[172:175], v[84:87]
	v_mfma_f32_16x16x32_bf16 v[80:83], v[160:163], v[172:175], v[80:83]
	ds_read_b128 v[172:175], v186 offset:12288
	ds_read_b128 v[180:183], v186 offset:14336
	ds_read_b128 v[184:187], v128 offset:32768
	ds_read_b128 v[188:191], v128 offset:34816
	ds_read_b128 v[192:195], v128 offset:36864
	ds_read_b128 v[196:199], v128 offset:38912
	v_mfma_f32_16x16x32_bf16 v[76:79], v[144:147], v[176:179], v[76:79]
	v_mfma_f32_16x16x32_bf16 v[72:75], v[148:151], v[176:179], v[72:75]
	v_mfma_f32_16x16x32_bf16 v[68:71], v[152:155], v[176:179], v[68:71]
	v_mfma_f32_16x16x32_bf16 v[64:67], v[160:163], v[176:179], v[64:67]
	v_add_u32_e32 v128, v143, v139
	s_waitcnt lgkmcnt(0)
	v_mfma_f32_16x16x32_bf16 v[60:63], v[144:147], v[164:167], v[60:63]
	v_mfma_f32_16x16x32_bf16 v[56:59], v[148:151], v[164:167], v[56:59]
	v_mfma_f32_16x16x32_bf16 v[52:55], v[152:155], v[164:167], v[52:55]
	v_mfma_f32_16x16x32_bf16 v[48:51], v[160:163], v[164:167], v[48:51]
	v_mfma_f32_16x16x32_bf16 v[44:47], v[144:147], v[168:171], v[44:47]
	v_mfma_f32_16x16x32_bf16 v[40:43], v[148:151], v[168:171], v[40:43]
	v_mfma_f32_16x16x32_bf16 v[36:39], v[152:155], v[168:171], v[36:39]
	v_mfma_f32_16x16x32_bf16 v[28:31], v[144:147], v[172:175], v[28:31]
	v_mfma_f32_16x16x32_bf16 v[24:27], v[148:151], v[172:175], v[24:27]
	v_mfma_f32_16x16x32_bf16 v[20:23], v[152:155], v[172:175], v[20:23]
	v_mfma_f32_16x16x32_bf16 v[12:15], v[144:147], v[180:183], v[12:15]
	v_mfma_f32_16x16x32_bf16 v[8:11], v[148:151], v[180:183], v[8:11]
	v_mfma_f32_16x16x32_bf16 v[4:7], v[152:155], v[180:183], v[4:7]
	ds_read_b128 v[144:147], v128
	ds_read_b128 v[148:151], v128 offset:2048
	ds_read_b128 v[152:155], v128 offset:4096
	ds_read_b128 v[164:167], v128 offset:6144
	v_mfma_f32_16x16x32_bf16 v[32:35], v[160:163], v[168:171], v[32:35]
	v_mfma_f32_16x16x32_bf16 v[16:19], v[160:163], v[172:175], v[16:19]
	v_mfma_f32_16x16x32_bf16 v[0:3], v[160:163], v[180:183], v[0:3]
	s_waitcnt lgkmcnt(0)
	v_mfma_f32_16x16x32_bf16 v[124:127], v[184:187], v[144:147], v[124:127]
	v_mfma_f32_16x16x32_bf16 v[120:123], v[188:191], v[144:147], v[120:123]
	v_mfma_f32_16x16x32_bf16 v[116:119], v[192:195], v[144:147], v[116:119]
	v_mfma_f32_16x16x32_bf16 v[112:115], v[196:199], v[144:147], v[112:115]
	v_mfma_f32_16x16x32_bf16 v[108:111], v[184:187], v[148:151], v[108:111]
	v_mfma_f32_16x16x32_bf16 v[104:107], v[188:191], v[148:151], v[104:107]
	v_mfma_f32_16x16x32_bf16 v[100:103], v[192:195], v[148:151], v[100:103]
	v_mfma_f32_16x16x32_bf16 v[96:99], v[196:199], v[148:151], v[96:99]
	v_mfma_f32_16x16x32_bf16 v[92:95], v[184:187], v[152:155], v[92:95]
	v_mfma_f32_16x16x32_bf16 v[88:91], v[188:191], v[152:155], v[88:91]
	v_mfma_f32_16x16x32_bf16 v[84:87], v[192:195], v[152:155], v[84:87]
	v_mfma_f32_16x16x32_bf16 v[80:83], v[196:199], v[152:155], v[80:83]
	ds_read_b128 v[144:147], v128 offset:8192
	ds_read_b128 v[148:151], v128 offset:10240
	ds_read_b128 v[152:155], v128 offset:12288
	ds_read_b128 v[160:163], v128 offset:14336
	v_mfma_f32_16x16x32_bf16 v[76:79], v[184:187], v[164:167], v[76:79]
	v_mfma_f32_16x16x32_bf16 v[72:75], v[188:191], v[164:167], v[72:75]
	v_mfma_f32_16x16x32_bf16 v[68:71], v[192:195], v[164:167], v[68:71]
	v_mfma_f32_16x16x32_bf16 v[64:67], v[196:199], v[164:167], v[64:67]
	s_waitcnt lgkmcnt(0)
	v_mfma_f32_16x16x32_bf16 v[60:63], v[184:187], v[144:147], v[60:63]
	v_mfma_f32_16x16x32_bf16 v[56:59], v[188:191], v[144:147], v[56:59]
	v_mfma_f32_16x16x32_bf16 v[52:55], v[192:195], v[144:147], v[52:55]
	v_mfma_f32_16x16x32_bf16 v[48:51], v[196:199], v[144:147], v[48:51]
	v_mfma_f32_16x16x32_bf16 v[44:47], v[184:187], v[148:151], v[44:47]
	v_mfma_f32_16x16x32_bf16 v[40:43], v[188:191], v[148:151], v[40:43]
	v_mfma_f32_16x16x32_bf16 v[36:39], v[192:195], v[148:151], v[36:39]
	v_mfma_f32_16x16x32_bf16 v[32:35], v[196:199], v[148:151], v[32:35]
	v_mfma_f32_16x16x32_bf16 v[28:31], v[184:187], v[152:155], v[28:31]
	v_mfma_f32_16x16x32_bf16 v[24:27], v[188:191], v[152:155], v[24:27]
	v_mfma_f32_16x16x32_bf16 v[20:23], v[192:195], v[152:155], v[20:23]
	v_mfma_f32_16x16x32_bf16 v[16:19], v[196:199], v[152:155], v[16:19]
	v_mfma_f32_16x16x32_bf16 v[12:15], v[184:187], v[160:163], v[12:15]
	v_mfma_f32_16x16x32_bf16 v[8:11], v[188:191], v[160:163], v[8:11]
	v_mfma_f32_16x16x32_bf16 v[4:7], v[192:195], v[160:163], v[4:7]
	v_mfma_f32_16x16x32_bf16 v[0:3], v[196:199], v[160:163], v[0:3]
	s_add_u32 s36, s36, 0x80
	s_addc_u32 s37, s37, 0
	s_add_i32 s35, s35, 0x10000
	s_cmpk_lg_i32 s36, 0x780
	s_cbranch_scc1 .LBB0_919
; __device__ __forceinline__ f32x4 mfma16(bf16x8 a, bf16x8 b, f32x4 c) { return __builtin_amdgcn_mfma_f32_16x16x32_bf16(a, b, c, 0, 0, 0); }
; #define WAIT_V(n) asm volatile("s_waitcnt vmcnt(" #n ")" ::: "memory")
; __device__ __forceinline__ void gemm_mainloop(f32x4 (&acc)[8][4], const GemmSrc& g, int K, char* lds) {
;     ...
;     for (int kt = 0; kt < KT; kt++) {
;         WAIT_V(0);
;         __builtin_amdgcn_s_barrier();
;         const char* st = lds + (kt & 1) * 65536;
;         bf16x8 afA[4], afB[4], bX[4], bY[4];
; #pragma unroll
;         for (int ni = 0; ni < 4; ni++) afA[ni] = *(const bf16x8*)(st + woff + ni * 16 * 128 + rdo0);
; #pragma unroll
;         for (int mi = 0; mi < 4; mi++) bX[mi] = *(const bf16x8*)(st + xoff + mi * 16 * 128 + rdo0);
;         if (kt + 1 < KT) gemm_issue(g, kt + 1, (kt + 1) & 1, lds);
; #pragma unroll
;         for (int mi = 0; mi < 4; mi++) bY[mi] = *(const bf16x8*)(st + xoff + (4 + mi) * 16 * 128 + rdo0);
; #pragma unroll
;         for (int ni = 0; ni < 4; ni++) afB[ni] = *(const bf16x8*)(st + woff + ni * 16 * 128 + rdo1);
; #pragma unroll
;         for (int mi = 0; mi < 4; mi++)
; #pragma unroll
;             for (int ni = 0; ni < 4; ni++) acc[mi][ni] = mfma16(afA[ni], bX[mi], acc[mi][ni]);
;         __builtin_amdgcn_sched_barrier(0);
; #pragma unroll
;         for (int mi = 0; mi < 4; mi++) bX[mi] = *(const bf16x8*)(st + xoff + mi * 16 * 128 + rdo1);
; #pragma unroll
;         for (int mi = 0; mi < 4; mi++)
; #pragma unroll
;             for (int ni = 0; ni < 4; ni++) acc[4 + mi][ni] = mfma16(afA[ni], bY[mi], acc[4 + mi][ni]);
;         __builtin_amdgcn_sched_barrier(0);
; #pragma unroll
;         for (int mi = 0; mi < 4; mi++) bY[mi] = *(const bf16x8*)(st + xoff + (4 + mi) * 16 * 128 + rdo1);
; #pragma unroll
;         for (int mi = 0; mi < 4; mi++)
; #pragma unroll
;             for (int ni = 0; ni < 4; ni++) acc[mi][ni] = mfma16(afB[ni], bX[mi], acc[mi][ni]);
;         __builtin_amdgcn_sched_barrier(0);
; #pragma unroll
;         for (int mi = 0; mi < 4; mi++)
; #pragma unroll
;             for (int ni = 0; ni < 4; ni++) acc[4 + mi][ni] = mfma16(afB[ni], bY[mi], acc[4 + mi][ni]);
;         __builtin_amdgcn_sched_barrier(0);
;     }
	v_or_b32_e32 v128, 0x8000, v142
	v_add_u32_e32 v156, 0x10000, v141
	v_add3_u32 v152, v128, v140, s40
	v_add_u32_e32 v157, v156, v140
	s_waitcnt vmcnt(0)
	s_barrier
	ds_read_b128 v[130:133], v152
	ds_read_b128 v[134:137], v152 offset:2048
	ds_read_b128 v[140:143], v157
	ds_read_b128 v[144:147], v157 offset:2048
	ds_read_b128 v[148:151], v152 offset:4096
	ds_read_b128 v[152:155], v152 offset:6144
	s_waitcnt lgkmcnt(0)
	v_mfma_f32_16x16x32_bf16 v[124:127], v[130:133], v[140:143], v[124:127]
	v_add3_u32 v128, v128, v139, s40
	v_mfma_f32_16x16x32_bf16 v[120:123], v[134:137], v[140:143], v[120:123]
	v_mfma_f32_16x16x32_bf16 v[116:119], v[148:151], v[140:143], v[116:119]
	v_mfma_f32_16x16x32_bf16 v[112:115], v[152:155], v[140:143], v[112:115]
	v_mfma_f32_16x16x32_bf16 v[108:111], v[130:133], v[144:147], v[108:111]
	v_mfma_f32_16x16x32_bf16 v[104:107], v[134:137], v[144:147], v[104:107]
	v_mfma_f32_16x16x32_bf16 v[100:103], v[148:151], v[144:147], v[100:103]
	v_mfma_f32_16x16x32_bf16 v[96:99], v[152:155], v[144:147], v[96:99]
	ds_read_b128 v[140:143], v157 offset:4096
	ds_read_b128 v[144:147], v157 offset:6144
	s_waitcnt lgkmcnt(0)
	v_mfma_f32_16x16x32_bf16 v[92:95], v[130:133], v[140:143], v[92:95]
	v_mfma_f32_16x16x32_bf16 v[88:91], v[134:137], v[140:143], v[88:91]
	v_mfma_f32_16x16x32_bf16 v[84:87], v[148:151], v[140:143], v[84:87]
	v_mfma_f32_16x16x32_bf16 v[80:83], v[152:155], v[140:143], v[80:83]
	ds_read_b128 v[140:143], v128 offset:6144
	ds_read_b128 v[160:163], v128 offset:4096
	ds_read_b128 v[164:167], v128 offset:2048
	ds_read_b128 v[168:171], v128
	ds_read_b128 v[172:175], v157 offset:14336
	ds_read_b128 v[176:179], v157 offset:12288
	ds_read_b128 v[180:183], v157 offset:10240
	ds_read_b128 v[184:187], v157 offset:8192
	v_mfma_f32_16x16x32_bf16 v[76:79], v[130:133], v[144:147], v[76:79]
	v_mfma_f32_16x16x32_bf16 v[72:75], v[134:137], v[144:147], v[72:75]
	v_mfma_f32_16x16x32_bf16 v[68:71], v[148:151], v[144:147], v[68:71]
	v_mfma_f32_16x16x32_bf16 v[64:67], v[152:155], v[144:147], v[64:67]
	v_add_u32_e32 v128, v156, v139
	s_waitcnt lgkmcnt(0)
	v_mfma_f32_16x16x32_bf16 v[60:63], v[130:133], v[184:187], v[60:63]
	v_mfma_f32_16x16x32_bf16 v[56:59], v[134:137], v[184:187], v[56:59]
	v_mfma_f32_16x16x32_bf16 v[52:55], v[148:151], v[184:187], v[52:55]
	v_mfma_f32_16x16x32_bf16 v[44:47], v[130:133], v[180:183], v[44:47]
	v_mfma_f32_16x16x32_bf16 v[40:43], v[134:137], v[180:183], v[40:43]
	v_mfma_f32_16x16x32_bf16 v[36:39], v[148:151], v[180:183], v[36:39]
	v_mfma_f32_16x16x32_bf16 v[28:31], v[130:133], v[176:179], v[28:31]
	v_mfma_f32_16x16x32_bf16 v[24:27], v[134:137], v[176:179], v[24:27]
	v_mfma_f32_16x16x32_bf16 v[20:23], v[148:151], v[176:179], v[20:23]
	v_mfma_f32_16x16x32_bf16 v[12:15], v[130:133], v[172:175], v[12:15]
	v_mfma_f32_16x16x32_bf16 v[8:11], v[134:137], v[172:175], v[8:11]
	v_mfma_f32_16x16x32_bf16 v[4:7], v[148:151], v[172:175], v[4:7]
	ds_read_b128 v[130:133], v128
	ds_read_b128 v[134:137], v128 offset:2048
	ds_read_b128 v[144:147], v128 offset:4096
	ds_read_b128 v[148:151], v128 offset:6144
	v_mfma_f32_16x16x32_bf16 v[0:3], v[152:155], v[172:175], v[0:3]
	v_mfma_f32_16x16x32_bf16 v[48:51], v[152:155], v[184:187], v[48:51]
	v_mfma_f32_16x16x32_bf16 v[32:35], v[152:155], v[180:183], v[32:35]
	v_mfma_f32_16x16x32_bf16 v[16:19], v[152:155], v[176:179], v[16:19]
	s_waitcnt lgkmcnt(0)
	v_mfma_f32_16x16x32_bf16 v[124:127], v[168:171], v[130:133], v[124:127]
	v_mfma_f32_16x16x32_bf16 v[120:123], v[164:167], v[130:133], v[120:123]
	v_mfma_f32_16x16x32_bf16 v[116:119], v[160:163], v[130:133], v[116:119]
	v_mfma_f32_16x16x32_bf16 v[112:115], v[140:143], v[130:133], v[112:115]
	v_mfma_f32_16x16x32_bf16 v[108:111], v[168:171], v[134:137], v[108:111]
	v_mfma_f32_16x16x32_bf16 v[104:107], v[164:167], v[134:137], v[104:107]
	v_mfma_f32_16x16x32_bf16 v[100:103], v[160:163], v[134:137], v[100:103]
	v_mfma_f32_16x16x32_bf16 v[96:99], v[140:143], v[134:137], v[96:99]
	v_mfma_f32_16x16x32_bf16 v[92:95], v[168:171], v[144:147], v[92:95]
	v_mfma_f32_16x16x32_bf16 v[88:91], v[164:167], v[144:147], v[88:91]
	v_mfma_f32_16x16x32_bf16 v[84:87], v[160:163], v[144:147], v[84:87]
	v_mfma_f32_16x16x32_bf16 v[80:83], v[140:143], v[144:147], v[80:83]
	ds_read_b128 v[130:133], v128 offset:8192
	ds_read_b128 v[134:137], v128 offset:10240
	ds_read_b128 v[144:147], v128 offset:12288
	ds_read_b128 v[152:155], v128 offset:14336
	v_mfma_f32_16x16x32_bf16 v[76:79], v[168:171], v[148:151], v[76:79]
	v_mfma_f32_16x16x32_bf16 v[72:75], v[164:167], v[148:151], v[72:75]
	v_mfma_f32_16x16x32_bf16 v[68:71], v[160:163], v[148:151], v[68:71]
	v_mfma_f32_16x16x32_bf16 v[64:67], v[140:143], v[148:151], v[64:67]
	s_waitcnt lgkmcnt(0)
; __device__ __forceinline__ void epi_fill(char* lds, int wr, int wc, int r, int q, int mi, int ni, f32x4 v) {
;     *(u32x2*)(lds + (wr * 128 + mi * 16 + r) * EPI_ROWB + (wc * 64 + ni * 16 + 4 * q) * 2) = (u32x2){pack2(v[0], v[1]), pack2(v[2], v[3])};
; }
; __device__ void phaseP1(const Params& p, char* lds) {
;     ...
; #pragma unroll
;         for (int mi = 0; mi < 8; mi++)
; #pragma unroll
;             for (int ni = 0; ni < 4; ni++) epi_fill(lds, wr, wc, r, q, mi, ni, acc[mi][ni]);
;         __syncthreads();
	v_mfma_f32_16x16x32_bf16 v[0:3], v[140:143], v[152:155], v[0:3]
	v_mfma_f32_16x16x32_bf16 v[60:63], v[168:171], v[130:133], v[60:63]
	v_mfma_f32_16x16x32_bf16 v[56:59], v[164:167], v[130:133], v[56:59]
	v_mfma_f32_16x16x32_bf16 v[52:55], v[160:163], v[130:133], v[52:55]
	v_mfma_f32_16x16x32_bf16 v[48:51], v[140:143], v[130:133], v[48:51]
	v_mfma_f32_16x16x32_bf16 v[44:47], v[168:171], v[134:137], v[44:47]
	v_mfma_f32_16x16x32_bf16 v[40:43], v[164:167], v[134:137], v[40:43]
	v_mfma_f32_16x16x32_bf16 v[36:39], v[160:163], v[134:137], v[36:39]
	v_mfma_f32_16x16x32_bf16 v[32:35], v[140:143], v[134:137], v[32:35]
	v_mfma_f32_16x16x32_bf16 v[28:31], v[168:171], v[144:147], v[28:31]
	v_mfma_f32_16x16x32_bf16 v[24:27], v[164:167], v[144:147], v[24:27]
	v_mfma_f32_16x16x32_bf16 v[20:23], v[160:163], v[144:147], v[20:23]
	v_mfma_f32_16x16x32_bf16 v[16:19], v[140:143], v[144:147], v[16:19]
	v_mfma_f32_16x16x32_bf16 v[12:15], v[168:171], v[152:155], v[12:15]
	v_mfma_f32_16x16x32_bf16 v[8:11], v[164:167], v[152:155], v[8:11]
	v_mfma_f32_16x16x32_bf16 v[4:7], v[160:163], v[152:155], v[4:7]
	v_cvt_pk_bf16_f32 v124, v124, v125
	v_cvt_pk_bf16_f32 v125, v126, v127
	v_cvt_pk_bf16_f32 v120, v120, v121
	v_cvt_pk_bf16_f32 v121, v122, v123
	v_cvt_pk_bf16_f32 v116, v116, v117
	v_cvt_pk_bf16_f32 v117, v118, v119
	v_cvt_pk_bf16_f32 v112, v112, v113
	v_cvt_pk_bf16_f32 v113, v114, v115
	v_cvt_pk_bf16_f32 v108, v108, v109
	v_cvt_pk_bf16_f32 v109, v110, v111
	v_cvt_pk_bf16_f32 v104, v104, v105
	v_cvt_pk_bf16_f32 v105, v106, v107
	v_add_u32_e32 v106, 0x2000, v138
	v_cvt_pk_bf16_f32 v100, v100, v101
	v_cvt_pk_bf16_f32 v101, v102, v103
	v_cvt_pk_bf16_f32 v96, v96, v97
	v_cvt_pk_bf16_f32 v97, v98, v99
	v_cvt_pk_bf16_f32 v92, v92, v93
	v_cvt_pk_bf16_f32 v93, v94, v95
	v_cvt_pk_bf16_f32 v88, v88, v89
	v_cvt_pk_bf16_f32 v89, v90, v91
	v_add_u32_e32 v90, 0x4000, v138
	v_cvt_pk_bf16_f32 v84, v84, v85
	v_cvt_pk_bf16_f32 v85, v86, v87
	v_cvt_pk_bf16_f32 v80, v80, v81
	v_cvt_pk_bf16_f32 v81, v82, v83
	v_cvt_pk_bf16_f32 v76, v76, v77
	v_cvt_pk_bf16_f32 v77, v78, v79
	v_cvt_pk_bf16_f32 v72, v72, v73
	v_cvt_pk_bf16_f32 v73, v74, v75
	v_add_u32_e32 v74, 0x6000, v138
	v_cvt_pk_bf16_f32 v68, v68, v69
	v_cvt_pk_bf16_f32 v69, v70, v71
	v_cvt_pk_bf16_f32 v64, v64, v65
	v_cvt_pk_bf16_f32 v65, v66, v67
	v_cvt_pk_bf16_f32 v60, v60, v61
	v_cvt_pk_bf16_f32 v61, v62, v63
	v_cvt_pk_bf16_f32 v56, v56, v57
	v_cvt_pk_bf16_f32 v57, v58, v59
	v_add_u32_e32 v58, 0x8000, v138
	v_cvt_pk_bf16_f32 v52, v52, v53
	v_cvt_pk_bf16_f32 v53, v54, v55
	v_cvt_pk_bf16_f32 v48, v48, v49
	v_cvt_pk_bf16_f32 v49, v50, v51
	v_cvt_pk_bf16_f32 v44, v44, v45
	v_cvt_pk_bf16_f32 v45, v46, v47
	v_cvt_pk_bf16_f32 v40, v40, v41
	v_cvt_pk_bf16_f32 v41, v42, v43
	v_add_u32_e32 v42, 0xa000, v138
	v_cvt_pk_bf16_f32 v36, v36, v37
	v_cvt_pk_bf16_f32 v37, v38, v39
	v_cvt_pk_bf16_f32 v32, v32, v33
	v_cvt_pk_bf16_f32 v33, v34, v35
	v_cvt_pk_bf16_f32 v28, v28, v29
	v_cvt_pk_bf16_f32 v29, v30, v31
	v_cvt_pk_bf16_f32 v24, v24, v25
	v_cvt_pk_bf16_f32 v25, v26, v27
	v_add_u32_e32 v26, 0xc000, v138
	v_cvt_pk_bf16_f32 v20, v20, v21
	v_cvt_pk_bf16_f32 v21, v22, v23
	v_cvt_pk_bf16_f32 v16, v16, v17
	v_cvt_pk_bf16_f32 v17, v18, v19
	v_cvt_pk_bf16_f32 v12, v12, v13
	v_cvt_pk_bf16_f32 v13, v14, v15
	v_cvt_pk_bf16_f32 v8, v8, v9
	v_cvt_pk_bf16_f32 v9, v10, v11
	v_add_u32_e32 v10, 0xe000, v138
	v_cvt_pk_bf16_f32 v4, v4, v5
	v_cvt_pk_bf16_f32 v5, v6, v7
	v_cvt_pk_bf16_f32 v0, v0, v1
	v_cvt_pk_bf16_f32 v1, v2, v3
	v_mov_b32_e32 v2, v158
	s_waitcnt vmcnt(0)
	s_barrier
	ds_write2_b64 v138, v[124:125], v[120:121] offset1:4
	ds_write2_b64 v138, v[116:117], v[112:113] offset0:8 offset1:12
	ds_write2_b64 v106, v[108:109], v[104:105] offset0:32 offset1:36
	ds_write2_b64 v106, v[100:101], v[96:97] offset0:40 offset1:44
	ds_write2_b64 v90, v[92:93], v[88:89] offset0:64 offset1:68
	ds_write2_b64 v90, v[84:85], v[80:81] offset0:72 offset1:76
	ds_write2_b64 v74, v[76:77], v[72:73] offset0:96 offset1:100
	ds_write2_b64 v74, v[68:69], v[64:65] offset0:104 offset1:108
	ds_write2_b64 v58, v[60:61], v[56:57] offset0:128 offset1:132
	ds_write2_b64 v58, v[52:53], v[48:49] offset0:136 offset1:140
	ds_write2_b64 v42, v[44:45], v[40:41] offset0:160 offset1:164
	ds_write2_b64 v42, v[36:37], v[32:33] offset0:168 offset1:172
	ds_write2_b64 v26, v[28:29], v[24:25] offset0:192 offset1:196
	ds_write2_b64 v26, v[20:21], v[16:17] offset0:200 offset1:204
	ds_write2_b64 v10, v[12:13], v[8:9] offset0:224 offset1:228
	ds_write2_b64 v10, v[4:5], v[0:1] offset0:232 offset1:236
	s_waitcnt lgkmcnt(0)
	s_barrier
; #define TIDX512 launder_i((int)threadIdx.x)
; __device__ __forceinline__ void epi_store(const char* lds, bf16_t* __restrict__ O, int ldo, int m0, int n0, int ncols_valid) {
;     const int t = TIDX512;
;     const int chunk = t & 31, rsub = t >> 5;
;     if (n0 + chunk * 8 < ncols_valid) {
; #pragma unroll
;         for (int ps = 0; ps < 16; ps++) {
;             const int row = ps * 16 + rsub;
;             const u32x4 v = *(const u32x4*)(lds + row * EPI_ROWB + chunk * 16);
;             *(u32x4*)(O + (size_t)(m0 + row) * ldo + n0 + chunk * 8) = v;
;         }
;     }
; }
	s_nop 0
	v_and_b32_e32 v0, 31, v2
	v_lshlrev_b32_e32 v1, 3, v0
	v_or_b32_e32 v3, s34, v1
	v_cmp_gt_i32_e32 vcc, s39, v3
	s_and_saveexec_b64 s[36:37], vcc
	s_cbranch_execz .LBB0_907
	v_ashrrev_i32_e32 v4, 5, v2
	v_lshlrev_b32_e32 v128, 1, v1
	v_mul_lo_u32 v1, v4, s2
	s_ashr_i32 s35, s34, 31
	v_lshl_add_u32 v14, v0, 4, v1
	s_lshl_b64 s[34:35], s[34:35], 1
	ds_read_b128 v[0:3], v14
	s_add_u32 s34, s0, s34
	v_add_u32_e32 v10, s42, v4
	s_addc_u32 s35, s1, s35
	v_ashrrev_i32_e32 v11, 31, v10
	v_lshl_add_u64 v[8:9], s[34:35], 0, v[128:129]
	v_lshlrev_b64 v[4:5], 12, v[10:11]
	v_lshl_add_u64 v[12:13], v[8:9], 0, v[4:5]
	ds_read_b128 v[4:7], v14 offset:8448
	s_waitcnt lgkmcnt(1)
	global_store_dwordx4 v[12:13], v[0:3], off
	v_add_u32_e32 v11, 0x2100, v14
	v_add_u32_e32 v15, 0x4200, v14
	v_add_u32_e32 v0, 16, v10
	v_ashrrev_i32_e32 v1, 31, v0
	v_lshlrev_b64 v[0:1], 12, v[0:1]
	v_lshl_add_u64 v[0:1], v[8:9], 0, v[0:1]
	s_waitcnt lgkmcnt(0)
	global_store_dwordx4 v[0:1], v[4:7], off
	ds_read_b128 v[0:3], v14 offset:16896
	v_add_u32_e32 v16, 0x6300, v14
	v_add_u32_e32 v4, 32, v10
	v_ashrrev_i32_e32 v5, 31, v4
	v_lshlrev_b64 v[4:5], 12, v[4:5]
	v_lshl_add_u64 v[12:13], v[8:9], 0, v[4:5]
	ds_read_b128 v[4:7], v14 offset:25344
	s_waitcnt lgkmcnt(1)
	global_store_dwordx4 v[12:13], v[0:3], off
	v_add_u32_e32 v17, 0x8400, v14
	v_add_u32_e32 v18, 0xa500, v14
	v_add_u32_e32 v0, 48, v10
	v_ashrrev_i32_e32 v1, 31, v0
	v_lshlrev_b64 v[0:1], 12, v[0:1]
	v_lshl_add_u64 v[0:1], v[8:9], 0, v[0:1]
	s_waitcnt lgkmcnt(0)
	global_store_dwordx4 v[0:1], v[4:7], off
	ds_read_b128 v[0:3], v14 offset:33792
	v_add_u32_e32 v19, 0xc600, v14
	v_add_u32_e32 v4, 64, v10
	v_ashrrev_i32_e32 v5, 31, v4
	v_lshlrev_b64 v[4:5], 12, v[4:5]
	v_lshl_add_u64 v[12:13], v[8:9], 0, v[4:5]
	ds_read_b128 v[4:7], v14 offset:42240
	s_waitcnt lgkmcnt(1)
	global_store_dwordx4 v[12:13], v[0:3], off
	v_add_u32_e32 v20, 0xe700, v11
	s_nop 0
	v_add_u32_e32 v0, 0x50, v10
	v_ashrrev_i32_e32 v1, 31, v0
	v_lshlrev_b64 v[0:1], 12, v[0:1]
	v_lshl_add_u64 v[0:1], v[8:9], 0, v[0:1]
	s_waitcnt lgkmcnt(0)
	global_store_dwordx4 v[0:1], v[4:7], off
	ds_read_b128 v[0:3], v14 offset:50688
	s_nop 0
	v_add_u32_e32 v4, 0x60, v10
	v_ashrrev_i32_e32 v5, 31, v4
	v_lshlrev_b64 v[4:5], 12, v[4:5]
	v_lshl_add_u64 v[12:13], v[8:9], 0, v[4:5]
	ds_read_b128 v[4:7], v14 offset:59136
	s_waitcnt lgkmcnt(1)
	global_store_dwordx4 v[12:13], v[0:3], off
	v_add_u32_e32 v14, 0xe700, v14
	s_nop 0
	v_add_u32_e32 v0, 0x70, v10
	v_ashrrev_i32_e32 v1, 31, v0
	v_lshlrev_b64 v[0:1], 12, v[0:1]
	v_lshl_add_u64 v[0:1], v[8:9], 0, v[0:1]
	s_waitcnt lgkmcnt(0)
	global_store_dwordx4 v[0:1], v[4:7], off
	ds_read_b128 v[0:3], v11 offset:59136
	s_nop 0
	v_add_u32_e32 v4, 0x80, v10
	v_ashrrev_i32_e32 v5, 31, v4
	v_lshlrev_b64 v[4:5], 12, v[4:5]
	v_lshl_add_u64 v[12:13], v[8:9], 0, v[4:5]
	ds_read_b128 v[4:7], v15 offset:59136
	s_waitcnt lgkmcnt(1)
	global_store_dwordx4 v[12:13], v[0:3], off
	s_nop 1
	v_add_u32_e32 v0, 0x90, v10
	v_ashrrev_i32_e32 v1, 31, v0
	v_lshlrev_b64 v[0:1], 12, v[0:1]
	v_lshl_add_u64 v[0:1], v[8:9], 0, v[0:1]
	s_waitcnt lgkmcnt(0)
	global_store_dwordx4 v[0:1], v[4:7], off
	ds_read_b128 v[0:3], v16 offset:59136
	s_nop 0
	v_add_u32_e32 v4, 0xa0, v10
	v_ashrrev_i32_e32 v5, 31, v4
	v_lshlrev_b64 v[4:5], 12, v[4:5]
	v_lshl_add_u64 v[12:13], v[8:9], 0, v[4:5]
	ds_read_b128 v[4:7], v17 offset:59136
	s_waitcnt lgkmcnt(1)
	global_store_dwordx4 v[12:13], v[0:3], off
	s_nop 1
	v_add_u32_e32 v0, 0xb0, v10
	v_ashrrev_i32_e32 v1, 31, v0
	v_lshlrev_b64 v[0:1], 12, v[0:1]
	v_lshl_add_u64 v[0:1], v[8:9], 0, v[0:1]
	s_waitcnt lgkmcnt(0)
	global_store_dwordx4 v[0:1], v[4:7], off
	ds_read_b128 v[0:3], v18 offset:59136
	s_nop 0
	v_add_u32_e32 v4, 0xc0, v10
	v_ashrrev_i32_e32 v5, 31, v4
	v_lshlrev_b64 v[4:5], 12, v[4:5]
	v_lshl_add_u64 v[12:13], v[8:9], 0, v[4:5]
	ds_read_b128 v[4:7], v19 offset:59136
	s_waitcnt lgkmcnt(1)
	global_store_dwordx4 v[12:13], v[0:3], off
	s_nop 1
	v_add_u32_e32 v0, 0xd0, v10
	v_ashrrev_i32_e32 v1, 31, v0
	v_lshlrev_b64 v[0:1], 12, v[0:1]
	v_lshl_add_u64 v[0:1], v[8:9], 0, v[0:1]
	s_waitcnt lgkmcnt(0)
	global_store_dwordx4 v[0:1], v[4:7], off
	ds_read_b128 v[0:3], v14 offset:59136
	s_nop 0
	v_add_u32_e32 v4, 0xe0, v10
	v_ashrrev_i32_e32 v5, 31, v4
	v_lshlrev_b64 v[4:5], 12, v[4:5]
	v_lshl_add_u64 v[12:13], v[8:9], 0, v[4:5]
	ds_read_b128 v[4:7], v20 offset:59136
	s_waitcnt lgkmcnt(1)
	global_store_dwordx4 v[12:13], v[0:3], off
	s_nop 1
	v_add_u32_e32 v0, 0xf0, v10
	v_ashrrev_i32_e32 v1, 31, v0
	v_lshlrev_b64 v[0:1], 12, v[0:1]
	v_lshl_add_u64 v[0:1], v[8:9], 0, v[0:1]
	s_waitcnt lgkmcnt(0)
	global_store_dwordx4 v[0:1], v[4:7], off
	s_branch .LBB0_907

; __global__ void __launch_bounds__(BLOCK_THREADS, 2) mega(Params p_unused) {
;     __shared__ __attribute__((aligned(16))) char lds[LDS_BYTES];
	.amdhsa_kernel _Z4mega6Params
		.amdhsa_group_segment_fixed_size 147520
		.amdhsa_private_segment_fixed_size 0
		.amdhsa_kernarg_size 480
		.amdhsa_user_sgpr_count 2
		.amdhsa_user_sgpr_dispatch_ptr 0
		.amdhsa_user_sgpr_queue_ptr 0
		.amdhsa_user_sgpr_kernarg_segment_ptr 1
		.amdhsa_user_sgpr_dispatch_id 0
		.amdhsa_user_sgpr_kernarg_preload_length 0
		.amdhsa_user_sgpr_kernarg_preload_offset 0
		.amdhsa_user_sgpr_private_segment_size 0
		.amdhsa_uses_dynamic_stack 0
		.amdhsa_enable_private_segment 0
		.amdhsa_system_sgpr_workgroup_id_x 1
		.amdhsa_system_sgpr_workgroup_id_y 0
		.amdhsa_system_sgpr_workgroup_id_z 0
		.amdhsa_system_sgpr_workgroup_info 0
		.amdhsa_system_vgpr_workitem_id 2
		.amdhsa_next_free_vgpr 223
		.amdhsa_next_free_sgpr 102
		.amdhsa_accum_offset 224
		.amdhsa_reserve_vcc 1
		.amdhsa_float_round_mode_32 0
		.amdhsa_float_round_mode_16_64 0
		.amdhsa_float_denorm_mode_32 3
		.amdhsa_float_denorm_mode_16_64 3
		.amdhsa_dx10_clamp 1
		.amdhsa_ieee_mode 1
		.amdhsa_fp16_overflow 0
		.amdhsa_tg_split 0
		.amdhsa_exception_fp_ieee_invalid_op 0
		.amdhsa_exception_fp_denorm_src 0
		.amdhsa_exception_fp_ieee_div_zero 0
		.amdhsa_exception_fp_ieee_overflow 0
		.amdhsa_exception_fp_ieee_underflow 0
		.amdhsa_exception_fp_ieee_inexact 0
		.amdhsa_exception_int_div_zero 0
	.end_amdhsa_kernel

; __global__ void __launch_bounds__(BLOCK_THREADS, 2) mega(Params p_unused) {
;     __shared__ __attribute__((aligned(16))) char lds[LDS_BYTES];
amdhsa.kernels:
  - .agpr_count:     0
    .args:
      - .offset:         0
        .size:           224
        .value_kind:     by_value
      - .offset:         224
        .size:           4
        .value_kind:     hidden_block_count_x
      - .offset:         228
        .size:           4
        .value_kind:     hidden_block_count_y
      - .offset:         232
        .size:           4
        .value_kind:     hidden_block_count_z
      - .offset:         236
        .size:           2
        .value_kind:     hidden_group_size_x
      - .offset:         238
        .size:           2
        .value_kind:     hidden_group_size_y
      - .offset:         240
        .size:           2
        .value_kind:     hidden_group_size_z
      - .offset:         242
        .size:           2
        .value_kind:     hidden_remainder_x
      - .offset:         244
        .size:           2
        .value_kind:     hidden_remainder_y
      - .offset:         246
        .size:           2
        .value_kind:     hidden_remainder_z
      - .offset:         264
        .size:           8
        .value_kind:     hidden_global_offset_x
      - .offset:         272
        .size:           8
        .value_kind:     hidden_global_offset_y
      - .offset:         280
        .size:           8
        .value_kind:     hidden_global_offset_z
      - .offset:         288
        .size:           2
        .value_kind:     hidden_grid_dims
      - .offset:         312
        .size:           8
        .value_kind:     hidden_multigrid_sync_arg
    .group_segment_fixed_size: 147520
    .kernarg_segment_align: 8
    .kernarg_segment_size: 480
    .language:       OpenCL C
    .language_version:
      - 2
      - 0
    .max_flat_workgroup_size: 512
    .name:           _Z4mega6Params
    .private_segment_fixed_size: 0
    .sgpr_count:     108
    .sgpr_spill_count: 19
    .symbol:         _Z4mega6Params.kd
    .uniform_work_group_size: 1
    .uses_dynamic_stack: false
    .vgpr_count:     223
    .vgpr_spill_count: 0
    .wavefront_size: 64
